# v15: v14 + hg readout gain-table load issued ahead of the row loads with a counted wait (was a one-trip loop with vmcnt(0))
# baseline (speedup 1.0000x reference)
; #define GAS __attribute__((address_space(1)))
; #define LAS __attribute__((address_space(3)))
; template <bool HG>
; __device__ __forceinline__ void readout_phase2(const Args& a, Frame& F, const float* gain, int nrows) {
;     ...
;     RO_LOAD(f0, b0, g0, nw); RO_LOAD(f1, b1, g1, nw + 2048); RO_LOAD(f2, b2, g2, nw + 2 * 2048);
;     if (HG) { for (int q = F.tid; q < D / 4; q += NWAVES * 64) ((LAS f32x4*)GL)[q] = ((const GAS f32x4*)gain)[q];
;               asm volatile("s_waitcnt lgkmcnt(0)" ::: "memory"); __builtin_amdgcn_s_barrier(); asm volatile("" ::: "memory"); }
.LBB0_576:
	s_andn2_b64 vcc, exec, s[8:9]
	s_cbranch_vccnz .LBB0_583
	s_getreg_b32 s6, hwreg(HW_REG_HW_ID, 0, 6)
	s_lshl_b32 s6, s6, 2
	s_add_i32 s6, s6, 0
	s_add_i32 s6, s6, 0x20540
	v_mov_b32_e32 v0, s6
	ds_read_b32 v0, v0
	v_mov_b64_e32 v[2:3], s[0:1]
	s_waitcnt lgkmcnt(0)
	v_readfirstlane_b32 s6, v0
	v_mbcnt_lo_u32_b32 v0, -1, 0
	v_mbcnt_hi_u32_b32 v0, -1, v0
	s_nop 1
	v_lshl_add_u32 v100, s6, 6, v0
	v_mov_b32_e32 v2, s72
	v_mov_b32_e32 v3, s73
	v_readfirstlane_b32 s6, v100
	s_ashr_i32 s6, s6, 6
	s_add_i32 s10, s6, s91
	s_mov_b64 s[6:7], 0x2ac00000
	s_ashr_i32 s11, s10, 31
	v_and_b32_e32 v166, 63, v100
	v_lshlrev_b32_e32 v0, 3, v166
	s_add_i32 s8, s10, 0x800
	s_ashr_i32 s9, s8, 31
	s_add_i32 s12, s10, 0x1000
	s_ashr_i32 s13, s12, 31
	s_waitcnt vmcnt(0) lgkmcnt(0)
	v_lshl_add_u64 v[36:37], v[2:3], 0, s[6:7]
	s_mov_b64 s[6:7], 0x33400000
	v_lshl_add_u64 v[38:39], v[2:3], 0, s[6:7]
	s_mov_b64 s[6:7], 0x26800000
	v_lshl_add_u64 v[40:41], v[2:3], 0, s[6:7]
	s_lshl_b64 s[6:7], s[10:11], 12
	v_lshl_add_u64 v[8:9], v[38:39], 0, s[6:7]
	v_lshl_add_u64 v[4:5], v[36:37], 0, s[6:7]
	v_lshl_add_u64 v[42:43], v[8:9], 0, v[0:1]
	v_lshl_add_u64 v[8:9], v[40:41], 0, s[6:7]
	v_lshl_add_u64 v[4:5], v[4:5], 0, v[0:1]
	v_lshl_add_u64 v[44:45], v[8:9], 0, v[0:1]
	s_lshl_b64 s[6:7], s[8:9], 12
	v_lshl_add_u64 v[184:185], s[84:85], 2, v[6:7]
	v_mov_b32_e32 v186, v100
	v_mov_b32_e32 v187, 0
	v_lshl_add_u64 v[184:185], v[186:187], 4, v[184:185]
	global_load_dwordx4 v[188:191], v[184:185], off
	global_load_dwordx2 v[156:157], v[4:5], off nt
	global_load_dwordx2 v[154:155], v[42:43], off nt
	global_load_dwordx2 v[8:9], v[44:45], off nt
	global_load_dwordx2 v[152:153], v[4:5], off offset:512 nt
	global_load_dwordx2 v[150:151], v[42:43], off offset:512 nt
	global_load_dwordx2 v[10:11], v[44:45], off offset:512 nt
	global_load_dwordx2 v[148:149], v[4:5], off offset:1024 nt
	global_load_dwordx2 v[140:141], v[42:43], off offset:1024 nt
	global_load_dwordx2 v[14:15], v[44:45], off offset:1024 nt
	global_load_dwordx2 v[90:91], v[4:5], off offset:1536 nt
	global_load_dwordx2 v[80:81], v[42:43], off offset:1536 nt
	global_load_dwordx2 v[18:19], v[44:45], off offset:1536 nt
	global_load_dwordx2 v[34:35], v[4:5], off offset:2048 nt
	global_load_dwordx2 v[32:33], v[42:43], off offset:2048 nt
	global_load_dwordx2 v[22:23], v[44:45], off offset:2048 nt
	global_load_dwordx2 v[28:29], v[4:5], off offset:2560 nt
	global_load_dwordx2 v[24:25], v[42:43], off offset:2560 nt
	global_load_dwordx2 v[26:27], v[44:45], off offset:2560 nt
	global_load_dwordx2 v[20:21], v[4:5], off offset:3072 nt
	global_load_dwordx2 v[16:17], v[42:43], off offset:3072 nt
	global_load_dwordx2 v[30:31], v[44:45], off offset:3072 nt
	global_load_dwordx2 v[12:13], v[4:5], off offset:3584 nt
	s_nop 0
	global_load_dwordx2 v[4:5], v[42:43], off offset:3584 nt
	global_load_dwordx2 v[76:77], v[44:45], off offset:3584 nt
	v_lshl_add_u64 v[42:43], v[36:37], 0, s[6:7]
	v_lshl_add_u64 v[44:45], v[38:39], 0, s[6:7]
	v_lshl_add_u64 v[42:43], v[42:43], 0, v[0:1]
	v_lshl_add_u64 v[48:49], v[44:45], 0, v[0:1]
	v_lshl_add_u64 v[44:45], v[40:41], 0, s[6:7]
	s_lshl_b64 s[6:7], s[12:13], 12
	v_lshl_add_u64 v[50:51], v[44:45], 0, v[0:1]
	global_load_dwordx2 v[146:147], v[42:43], off nt
	global_load_dwordx2 v[144:145], v[48:49], off nt
	global_load_dwordx2 v[72:73], v[50:51], off nt
	global_load_dwordx2 v[142:143], v[42:43], off offset:512 nt
	global_load_dwordx2 v[138:139], v[48:49], off offset:512 nt
	global_load_dwordx2 v[70:71], v[50:51], off offset:512 nt
	global_load_dwordx2 v[128:129], v[42:43], off offset:1024 nt
	global_load_dwordx2 v[126:127], v[48:49], off offset:1024 nt
	global_load_dwordx2 v[66:67], v[50:51], off offset:1024 nt
	global_load_dwordx2 v[120:121], v[42:43], off offset:1536 nt
	global_load_dwordx2 v[118:119], v[48:49], off offset:1536 nt
	global_load_dwordx2 v[60:61], v[50:51], off offset:1536 nt
	global_load_dwordx2 v[108:109], v[42:43], off offset:2048 nt
	global_load_dwordx2 v[106:107], v[48:49], off offset:2048 nt
	global_load_dwordx2 v[54:55], v[50:51], off offset:2048 nt
	global_load_dwordx2 v[98:99], v[42:43], off offset:2560 nt
	global_load_dwordx2 v[96:97], v[48:49], off offset:2560 nt
	global_load_dwordx2 v[46:47], v[50:51], off offset:2560 nt
	global_load_dwordx2 v[84:85], v[42:43], off offset:3072 nt
	global_load_dwordx2 v[82:83], v[48:49], off offset:3072 nt
	global_load_dwordx2 v[44:45], v[50:51], off offset:3072 nt
	global_load_dwordx2 v[78:79], v[42:43], off offset:3584 nt
	global_load_dwordx2 v[74:75], v[48:49], off offset:3584 nt
	s_nop 0
	global_load_dwordx2 v[42:43], v[50:51], off offset:3584 nt
	v_lshl_add_u64 v[48:49], v[36:37], 0, s[6:7]
	v_lshl_add_u64 v[86:87], v[48:49], 0, v[0:1]
	v_lshl_add_u64 v[48:49], v[38:39], 0, s[6:7]
	v_lshl_add_u64 v[50:51], v[48:49], 0, v[0:1]
	v_lshl_add_u64 v[48:49], v[40:41], 0, s[6:7]
	v_lshl_add_u64 v[158:159], v[48:49], 0, v[0:1]
	global_load_dwordx2 v[136:137], v[86:87], off nt
	global_load_dwordx2 v[134:135], v[50:51], off nt
	global_load_dwordx2 v[68:69], v[158:159], off nt
	global_load_dwordx2 v[132:133], v[86:87], off offset:512 nt
	global_load_dwordx2 v[130:131], v[50:51], off offset:512 nt
	global_load_dwordx2 v[64:65], v[158:159], off offset:512 nt
	global_load_dwordx2 v[124:125], v[86:87], off offset:1024 nt
	global_load_dwordx2 v[122:123], v[50:51], off offset:1024 nt
	global_load_dwordx2 v[58:59], v[158:159], off offset:1024 nt
	global_load_dwordx2 v[114:115], v[86:87], off offset:1536 nt
	global_load_dwordx2 v[116:117], v[50:51], off offset:1536 nt
	global_load_dwordx2 v[62:63], v[158:159], off offset:1536 nt
	global_load_dwordx2 v[112:113], v[86:87], off offset:2048 nt
	global_load_dwordx2 v[110:111], v[50:51], off offset:2048 nt
	global_load_dwordx2 v[56:57], v[158:159], off offset:2048 nt
	global_load_dwordx2 v[104:105], v[86:87], off offset:2560 nt
	global_load_dwordx2 v[102:103], v[50:51], off offset:2560 nt
	global_load_dwordx2 v[52:53], v[158:159], off offset:2560 nt
	global_load_dwordx2 v[94:95], v[86:87], off offset:3072 nt
	global_load_dwordx2 v[92:93], v[50:51], off offset:3072 nt
	global_load_dwordx2 v[48:49], v[158:159], off offset:3072 nt
	s_nop 0
	global_load_dwordx2 v[86:87], v[86:87], off offset:3584 nt
	s_nop 0
	global_load_dwordx2 v[88:89], v[50:51], off offset:3584 nt
	s_nop 0
	global_load_dwordx2 v[50:51], v[158:159], off offset:3584 nt
	s_waitcnt vmcnt(62)
; #define GAS __attribute__((address_space(1)))
; #define LAS __attribute__((address_space(3)))
; template <bool HG>
; __device__ __forceinline__ void readout_phase2(const Args& a, Frame& F, const float* gain, int nrows) {
;     ...
;     if (HG) { for (int q = F.tid; q < D / 4; q += NWAVES * 64) ((LAS f32x4*)GL)[q] = ((const GAS f32x4*)gain)[q];
	v_lshl_add_u32 v184, v100, 4, 0
	ds_write_b128 v184, v[188:191]
	s_waitcnt vmcnt(62)
	v_lshlrev_b32_e32 v6, 16, v156
	v_and_b32_e32 v7, 0xffff0000, v156
	v_lshlrev_b32_e32 v100, 16, v154
	v_and_b32_e32 v101, 0xffff0000, v154
	v_pk_add_f32 v[6:7], v[6:7], v[100:101]
	v_lshlrev_b32_e32 v100, 16, v157
	v_and_b32_e32 v101, 0xffff0000, v157
	v_lshlrev_b32_e32 v154, 16, v155
	v_and_b32_e32 v155, 0xffff0000, v155
	v_pk_add_f32 v[154:155], v[100:101], v[154:155]
	v_lshlrev_b32_e32 v100, 16, v152
	v_and_b32_e32 v101, 0xffff0000, v152
	v_lshlrev_b32_e32 v156, 16, v150
	v_and_b32_e32 v157, 0xffff0000, v150
	v_pk_add_f32 v[100:101], v[100:101], v[156:157]
	v_lshlrev_b32_e32 v152, 16, v153
	v_and_b32_e32 v153, 0xffff0000, v153
	v_lshlrev_b32_e32 v150, 16, v151
	v_and_b32_e32 v151, 0xffff0000, v151
	v_pk_add_f32 v[150:151], v[152:153], v[150:151]
	v_mov_b32_e32 v156, v7
	v_mov_b32_e32 v157, v101
	v_mov_b32_e32 v152, v6
	v_mov_b32_e32 v153, v100
	v_pk_mul_f32 v[156:157], v[156:157], v[156:157]
	v_mov_b32_e32 v158, v155
	v_mov_b32_e32 v159, v151
	v_pk_fma_f32 v[152:153], v[152:153], v[152:153], v[156:157]
	v_mov_b32_e32 v156, v154
	v_mov_b32_e32 v157, v150
	v_pk_mul_f32 v[158:159], v[158:159], v[158:159]
	s_lshl_b64 s[18:19], s[8:9], 11
	v_pk_fma_f32 v[156:157], v[156:157], v[156:157], v[158:159]
	s_waitcnt vmcnt(58)
	v_lshlrev_b32_e32 v158, 16, v32
	v_pk_add_f32 v[152:153], v[152:153], v[156:157]
	v_lshlrev_b32_e32 v156, 16, v140
	v_pk_add_f32 v[160:161], v[152:153], v[152:153] op_sel:[0,1] op_sel_hi:[1,0]
	v_lshlrev_b32_e32 v152, 16, v148
	v_and_b32_e32 v153, 0xffff0000, v148
	v_and_b32_e32 v157, 0xffff0000, v140
	v_lshlrev_b32_e32 v148, 16, v149
	v_and_b32_e32 v149, 0xffff0000, v149
	v_lshlrev_b32_e32 v140, 16, v141
	v_and_b32_e32 v141, 0xffff0000, v141
	v_pk_add_f32 v[152:153], v[152:153], v[156:157]
	v_pk_add_f32 v[156:157], v[148:149], v[140:141]
	v_mov_b32_e32 v148, v153
	v_mov_b32_e32 v149, v157
	v_mov_b32_e32 v140, v152
	v_mov_b32_e32 v141, v156
	v_pk_mul_f32 v[148:149], v[148:149], v[148:149]
	v_and_b32_e32 v159, 0xffff0000, v32
	v_pk_fma_f32 v[140:141], v[140:141], v[140:141], v[148:149]
	v_lshlrev_b32_e32 v148, 16, v80
	v_pk_add_f32 v[162:163], v[140:141], v[140:141] op_sel:[0,1] op_sel_hi:[1,0]
	v_lshlrev_b32_e32 v140, 16, v90
	v_and_b32_e32 v141, 0xffff0000, v90
	v_and_b32_e32 v149, 0xffff0000, v80
	v_pk_add_f32 v[140:141], v[140:141], v[148:149]
	v_lshlrev_b32_e32 v90, 16, v91
	v_and_b32_e32 v91, 0xffff0000, v91
	v_lshlrev_b32_e32 v80, 16, v81
	v_and_b32_e32 v81, 0xffff0000, v81
	v_pk_add_f32 v[148:149], v[90:91], v[80:81]
	v_mul_f32_e32 v80, v141, v141
	v_pk_fma_f32 v[90:91], v[140:141], v[140:141], v[80:81] op_sel_hi:[1,1,0]
	v_mul_f32_e32 v80, v149, v149
	v_pk_fma_f32 v[164:165], v[148:149], v[148:149], v[80:81] op_sel_hi:[1,1,0]
	v_lshlrev_b32_e32 v80, 16, v34
	v_and_b32_e32 v81, 0xffff0000, v34
	v_lshlrev_b32_e32 v34, 16, v35
	v_and_b32_e32 v35, 0xffff0000, v35
	v_lshlrev_b32_e32 v32, 16, v33
	v_and_b32_e32 v33, 0xffff0000, v33
	v_pk_add_f32 v[80:81], v[80:81], v[158:159]
	v_pk_add_f32 v[158:159], v[34:35], v[32:33]
	v_pk_mul_f32 v[32:33], v[80:81], v[80:81]
	v_pk_mul_f32 v[34:35], v[158:159], v[158:159]
	v_mov_b32_e32 v161, v32
	v_mov_b32_e32 v163, v33
	v_mov_b32_e32 v91, v34
	v_mov_b32_e32 v165, v35
	v_pk_add_f32 v[32:33], v[160:161], v[162:163]
	v_pk_add_f32 v[34:35], v[90:91], v[164:165]
	s_waitcnt vmcnt(55)
	v_lshlrev_b32_e32 v90, 16, v24
	v_pk_add_f32 v[32:33], v[32:33], v[34:35]
	v_and_b32_e32 v91, 0xffff0000, v24
	v_pk_add_f32 v[34:35], v[32:33], v[32:33] op_sel:[0,1] op_sel_hi:[1,0]
	v_lshlrev_b32_e32 v32, 16, v28
	v_and_b32_e32 v33, 0xffff0000, v28
	v_lshlrev_b32_e32 v28, 16, v29
	v_and_b32_e32 v29, 0xffff0000, v29
	v_lshlrev_b32_e32 v24, 16, v25
	v_and_b32_e32 v25, 0xffff0000, v25
	v_pk_add_f32 v[32:33], v[32:33], v[90:91]
	v_pk_add_f32 v[28:29], v[28:29], v[24:25]
	v_mov_b32_e32 v90, v33
	v_mov_b32_e32 v91, v29
	v_mov_b32_e32 v24, v32
	v_mov_b32_e32 v25, v28
	v_pk_mul_f32 v[90:91], v[90:91], v[90:91]
	s_waitcnt vmcnt(52)
	v_lshlrev_b32_e32 v160, 16, v16
	v_pk_fma_f32 v[24:25], v[24:25], v[24:25], v[90:91]
	v_lshlrev_b32_e32 v90, 16, v20
	v_and_b32_e32 v91, 0xffff0000, v20
	v_and_b32_e32 v161, 0xffff0000, v16
	v_lshlrev_b32_e32 v20, 16, v21
	v_and_b32_e32 v21, 0xffff0000, v21
	v_lshlrev_b32_e32 v16, 16, v17
	v_and_b32_e32 v17, 0xffff0000, v17
	v_pk_add_f32 v[160:161], v[90:91], v[160:161]
	v_pk_add_f32 v[164:165], v[20:21], v[16:17]
	s_waitcnt vmcnt(50)
	v_lshlrev_b32_e32 v90, 16, v12
	v_and_b32_e32 v91, 0xffff0000, v12
	s_waitcnt vmcnt(49)
	v_lshlrev_b32_e32 v162, 16, v4
	v_and_b32_e32 v163, 0xffff0000, v4
	v_lshlrev_b32_e32 v12, 16, v13
	v_and_b32_e32 v13, 0xffff0000, v13
	v_lshlrev_b32_e32 v4, 16, v5
	v_and_b32_e32 v5, 0xffff0000, v5
	v_mul_f32_e32 v16, v161, v161
	v_mul_f32_e32 v20, v165, v165
	v_pk_add_f32 v[90:91], v[90:91], v[162:163]
	v_pk_add_f32 v[162:163], v[12:13], v[4:5]
	v_pk_add_f32 v[24:25], v[24:25], v[24:25] op_sel:[0,1] op_sel_hi:[1,0]
	v_pk_fma_f32 v[16:17], v[160:161], v[160:161], v[16:17] op_sel_hi:[1,1,0]
	v_pk_fma_f32 v[20:21], v[164:165], v[164:165], v[20:21] op_sel_hi:[1,1,0]
	v_pk_mul_f32 v[4:5], v[90:91], v[90:91]
	v_pk_mul_f32 v[12:13], v[162:163], v[162:163]
	v_mov_b32_e32 v35, v4
	v_mov_b32_e32 v25, v5
	v_mov_b32_e32 v17, v12
	v_mov_b32_e32 v21, v13
	v_pk_add_f32 v[4:5], v[34:35], v[24:25]
	v_pk_add_f32 v[12:13], v[16:17], v[20:21]
	s_waitcnt vmcnt(47)
	v_lshlrev_b32_e32 v172, 16, v146
	v_pk_add_f32 v[4:5], v[4:5], v[12:13]
	v_and_b32_e32 v173, 0xffff0000, v146
	v_add_f32_e32 v4, v4, v5
	s_waitcnt vmcnt(46)
; template <bool HG>
; __device__ __forceinline__ void readout_phase2(const Args& a, Frame& F, const float* gain, int nrows) {
;     ...
;               asm volatile("s_waitcnt lgkmcnt(0)" ::: "memory"); __builtin_amdgcn_s_barrier(); asm volatile("" ::: "memory"); }
	v_lshlrev_b32_e32 v176, 16, v144
	v_and_b32_e32 v177, 0xffff0000, v144
	v_add_f32_dpp v4, v4, v4 quad_perm:[1,0,3,2] row_mask:0xf bank_mask:0xf bound_ctrl:1
	v_lshlrev_b32_e32 v146, 16, v147
	v_and_b32_e32 v147, 0xffff0000, v147
	v_add_f32_dpp v4, v4, v4 quad_perm:[2,3,0,1] row_mask:0xf bank_mask:0xf bound_ctrl:1
	v_lshlrev_b32_e32 v144, 16, v145
	v_and_b32_e32 v145, 0xffff0000, v145
	v_add_f32_dpp v4, v4, v4 row_half_mirror row_mask:0xf bank_mask:0xf bound_ctrl:1
	v_pk_add_f32 v[172:173], v[172:173], v[176:177]
	v_pk_add_f32 v[146:147], v[146:147], v[144:145]
	v_add_f32_dpp v4, v4, v4 row_mirror row_mask:0xf bank_mask:0xf bound_ctrl:1
	s_waitcnt vmcnt(44)
	v_lshlrev_b32_e32 v144, 16, v142
	v_readlane_b32 s8, v4, 16
	v_readlane_b32 s9, v4, 48
	v_readlane_b32 s6, v4, 0
	v_readlane_b32 s7, v4, 32
	v_mov_b32_e32 v4, s8
	v_mov_b32_e32 v5, s9
	v_pk_add_f32 v[4:5], s[6:7], v[4:5]
	s_mov_b64 s[6:7], 0x8c00000
	v_add_f32_e32 v4, v4, v5
	v_fmamk_f32 v4, v4, 0x3a000000, v252
	v_mul_f32_e32 v5, 0x4f800000, v4
	v_cmp_gt_f32_e32 vcc, s55, v4
	v_lshl_add_u64 v[34:35], v[2:3], 0, s[6:7]
	v_and_b32_e32 v145, 0xffff0000, v142
	v_cndmask_b32_e32 v4, v4, v5, vcc
	v_sqrt_f32_e32 v5, v4
	s_waitcnt vmcnt(43)
	v_lshlrev_b32_e32 v176, 16, v138
	v_and_b32_e32 v177, 0xffff0000, v138
	v_pk_add_f32 v[144:145], v[144:145], v[176:177]
	v_add_u32_e32 v2, -1, v5
	v_fma_f32 v3, -v2, v5, v4
	v_cmp_ge_f32_e64 s[8:9], 0, v3
	v_add_u32_e32 v3, 1, v5
	v_lshlrev_b32_e32 v142, 16, v143
	v_cndmask_b32_e64 v2, v5, v2, s[8:9]
	v_fma_f32 v5, -v3, v5, v4
	v_cmp_lt_f32_e64 s[8:9], 0, v5
	v_and_b32_e32 v143, 0xffff0000, v143
	v_lshlrev_b32_e32 v138, 16, v139
	v_cndmask_b32_e64 v2, v2, v3, s[8:9]
	v_mul_f32_e32 v3, 0x37800000, v2
	v_cndmask_b32_e32 v2, v2, v3, vcc
	v_cmp_class_f32_e32 vcc, v4, v253
	v_and_b32_e32 v139, 0xffff0000, v139
	v_pk_add_f32 v[138:139], v[142:143], v[138:139]
	v_cndmask_b32_e32 v2, v2, v4, vcc
	v_div_scale_f32 v3, s[6:7], v2, v2, 1.0
	v_rcp_f32_e32 v4, v3
	v_mov_b32_e32 v176, v173
	v_mov_b32_e32 v177, v145
	v_mov_b32_e32 v142, v172
	v_fma_f32 v5, -v3, v4, 1.0
	v_fmac_f32_e32 v4, v5, v4
	v_div_scale_f32 v5, vcc, 1.0, v2, 1.0
	v_mul_f32_e32 v12, v5, v4
	v_fma_f32 v13, -v3, v12, v5
	v_mov_b32_e32 v143, v144
	v_pk_mul_f32 v[176:177], v[176:177], v[176:177]
	v_mov_b32_e32 v178, v147
	v_mov_b32_e32 v179, v139
	v_fmac_f32_e32 v12, v13, v4
	v_pk_fma_f32 v[142:143], v[142:143], v[142:143], v[176:177]
	v_mov_b32_e32 v176, v146
	v_mov_b32_e32 v177, v138
	v_pk_mul_f32 v[178:179], v[178:179], v[178:179]
	v_fma_f32 v3, -v3, v12, v5
	v_pk_fma_f32 v[176:177], v[176:177], v[176:177], v[178:179]
	s_lshl_b64 s[16:17], s[10:11], 11
	v_div_fmas_f32 v3, v3, v4, v12
	v_pk_add_f32 v[142:143], v[142:143], v[176:177]
	s_waitcnt lgkmcnt(0)
	s_barrier
	v_div_fixup_f32 v168, v3, v2, 1.0
	v_lshl_add_u64 v[2:3], s[16:17], 1, v[34:35]
	v_lshl_add_u32 v166, v166, 4, 0
	v_pk_add_f32 v[176:177], v[142:143], v[142:143] op_sel:[0,1] op_sel_hi:[1,0]
	s_waitcnt vmcnt(41)
	v_lshlrev_b32_e32 v142, 16, v128
	v_and_b32_e32 v143, 0xffff0000, v128
	s_waitcnt vmcnt(40)
	v_lshlrev_b32_e32 v178, 16, v126
	v_and_b32_e32 v179, 0xffff0000, v126
	v_lshlrev_b32_e32 v128, 16, v129
	v_and_b32_e32 v129, 0xffff0000, v129
	v_lshlrev_b32_e32 v126, 16, v127
	v_and_b32_e32 v127, 0xffff0000, v127
	v_lshl_add_u64 v[170:171], v[2:3], 0, v[0:1]
	ds_read_b128 v[2:5], v166
	v_pk_add_f32 v[142:143], v[142:143], v[178:179]
	v_pk_add_f32 v[178:179], v[128:129], v[126:127]
	v_mov_b32_e32 v128, v143
	v_mov_b32_e32 v129, v179
	v_mov_b32_e32 v126, v142
	v_mov_b32_e32 v127, v178
	v_pk_mul_f32 v[128:129], v[128:129], v[128:129]
	v_lshlrev_b32_e32 v12, 16, v8
	v_and_b32_e32 v13, 0xffff0000, v8
	v_lshlrev_b32_e32 v16, 16, v9
	v_and_b32_e32 v17, 0xffff0000, v9
	v_pk_mul_f32 v[24:25], v[6:7], v[168:169] op_sel_hi:[1,0]
	ds_read_b128 v[6:9], v166 offset:1024
	v_pk_fma_f32 v[126:127], v[126:127], v[126:127], v[128:129]
	s_waitcnt vmcnt(38)
	v_lshlrev_b32_e32 v128, 16, v120
	v_and_b32_e32 v129, 0xffff0000, v120
	s_waitcnt vmcnt(37)
	v_lshlrev_b32_e32 v180, 16, v118
	v_and_b32_e32 v181, 0xffff0000, v118
	v_lshlrev_b32_e32 v120, 16, v121
	v_and_b32_e32 v121, 0xffff0000, v121
	v_lshlrev_b32_e32 v118, 16, v119
	v_and_b32_e32 v119, 0xffff0000, v119
	v_pk_mul_f32 v[20:21], v[154:155], v[168:169] op_sel_hi:[1,0]
	v_pk_add_f32 v[128:129], v[128:129], v[180:181]
	v_pk_add_f32 v[118:119], v[120:121], v[118:119]
	s_waitcnt vmcnt(35)
	v_lshlrev_b32_e32 v184, 16, v108
	v_and_b32_e32 v185, 0xffff0000, v108
	s_waitcnt vmcnt(34)
	v_lshlrev_b32_e32 v186, 16, v106
	v_and_b32_e32 v187, 0xffff0000, v106
	v_lshlrev_b32_e32 v108, 16, v109
	v_and_b32_e32 v109, 0xffff0000, v109
	v_lshlrev_b32_e32 v106, 16, v107
	v_and_b32_e32 v107, 0xffff0000, v107
	s_waitcnt lgkmcnt(1)
	v_pk_mul_f32 v[24:25], v[2:3], v[24:25]
	v_pk_mul_f32 v[20:21], v[4:5], v[20:21]
	v_mul_f32_e32 v120, v129, v129
	v_mul_f32_e32 v180, v119, v119
	v_pk_add_f32 v[186:187], v[184:185], v[186:187]
	v_pk_add_f32 v[106:107], v[108:109], v[106:107]
	v_pk_mul_f32 v[16:17], v[20:21], v[16:17]
	v_pk_mul_f32 v[12:13], v[24:25], v[12:13]
	v_pk_add_f32 v[126:127], v[126:127], v[126:127] op_sel:[0,1] op_sel_hi:[1,0]
	v_pk_fma_f32 v[120:121], v[128:129], v[128:129], v[120:121] op_sel_hi:[1,1,0]
	v_pk_fma_f32 v[180:181], v[118:119], v[118:119], v[180:181] op_sel_hi:[1,1,0]
	v_pk_mul_f32 v[108:109], v[186:187], v[186:187]
	v_pk_mul_f32 v[184:185], v[106:107], v[106:107]
	v_cvt_pk_bf16_f32 v12, v12, v13
	v_cvt_pk_bf16_f32 v13, v16, v17
	v_pk_mul_f32 v[16:17], v[150:151], v[168:169] op_sel_hi:[1,0]
	v_pk_mul_f32 v[20:21], v[100:101], v[168:169] op_sel_hi:[1,0]
	v_mov_b32_e32 v177, v108
	v_mov_b32_e32 v127, v109
	v_mov_b32_e32 v121, v184
	v_mov_b32_e32 v181, v185
	global_store_dwordx2 v[170:171], v[12:13], off
	v_lshlrev_b32_e32 v12, 16, v10
	v_and_b32_e32 v13, 0xffff0000, v10
	v_lshlrev_b32_e32 v10, 16, v11
	v_and_b32_e32 v11, 0xffff0000, v11
	s_waitcnt lgkmcnt(0)
	v_pk_mul_f32 v[20:21], v[6:7], v[20:21]
	v_pk_mul_f32 v[16:17], v[8:9], v[16:17]
	v_pk_add_f32 v[108:109], v[176:177], v[126:127]
	v_pk_add_f32 v[120:121], v[120:121], v[180:181]
	v_pk_mul_f32 v[10:11], v[16:17], v[10:11]
	v_pk_mul_f32 v[12:13], v[20:21], v[12:13]
	v_pk_add_f32 v[108:109], v[108:109], v[120:121]
	s_waitcnt vmcnt(33)
	v_lshlrev_b32_e32 v120, 16, v98
	v_and_b32_e32 v121, 0xffff0000, v98
	s_waitcnt vmcnt(32)
	v_lshlrev_b32_e32 v126, 16, v96
	v_and_b32_e32 v127, 0xffff0000, v96
	v_lshlrev_b32_e32 v98, 16, v99
	v_and_b32_e32 v99, 0xffff0000, v99
	v_lshlrev_b32_e32 v96, 16, v97
	v_and_b32_e32 v97, 0xffff0000, v97
	v_cvt_pk_bf16_f32 v12, v12, v13
	v_cvt_pk_bf16_f32 v13, v10, v11
	v_pk_add_f32 v[120:121], v[120:121], v[126:127]
	v_pk_add_f32 v[96:97], v[98:99], v[96:97]
	global_store_dwordx2 v[170:171], v[12:13], off offset:512
	ds_read_b128 v[10:13], v166 offset:2048
	v_mov_b32_e32 v126, v121
	v_mov_b32_e32 v127, v97
	v_mov_b32_e32 v98, v120
	v_mov_b32_e32 v99, v96
	v_pk_mul_f32 v[126:127], v[126:127], v[126:127]
	s_waitcnt vmcnt(30)
	v_lshlrev_b32_e32 v176, 16, v82
	v_pk_fma_f32 v[98:99], v[98:99], v[98:99], v[126:127]
	v_lshlrev_b32_e32 v126, 16, v84
	v_and_b32_e32 v127, 0xffff0000, v84
	v_and_b32_e32 v177, 0xffff0000, v82
	v_lshlrev_b32_e32 v84, 16, v85
	v_and_b32_e32 v85, 0xffff0000, v85
	v_lshlrev_b32_e32 v82, 16, v83
	v_and_b32_e32 v83, 0xffff0000, v83
	v_lshlrev_b32_e32 v20, 16, v14
	v_and_b32_e32 v21, 0xffff0000, v14
	v_lshlrev_b32_e32 v24, 16, v15
	v_and_b32_e32 v25, 0xffff0000, v15
	ds_read_b128 v[14:17], v166 offset:3072
	v_pk_add_f32 v[176:177], v[126:127], v[176:177]
	v_pk_add_f32 v[82:83], v[84:85], v[82:83]
	s_waitcnt vmcnt(28)
	v_lshlrev_b32_e32 v180, 16, v78
	v_and_b32_e32 v181, 0xffff0000, v78
	s_waitcnt vmcnt(27)
	v_lshlrev_b32_e32 v184, 16, v74
	v_and_b32_e32 v185, 0xffff0000, v74
	v_lshlrev_b32_e32 v78, 16, v79
	v_and_b32_e32 v79, 0xffff0000, v79
	v_lshlrev_b32_e32 v74, 16, v75
	v_and_b32_e32 v75, 0xffff0000, v75
	v_pk_mul_f32 v[100:101], v[156:157], v[168:169] op_sel_hi:[1,0]
	v_pk_mul_f32 v[150:151], v[152:153], v[168:169] op_sel_hi:[1,0]
	v_mul_f32_e32 v84, v177, v177
	v_mul_f32_e32 v126, v83, v83
	v_pk_add_f32 v[180:181], v[180:181], v[184:185]
	v_pk_add_f32 v[78:79], v[78:79], v[74:75]
	s_waitcnt lgkmcnt(1)
	v_pk_mul_f32 v[150:151], v[10:11], v[150:151]
	v_pk_mul_f32 v[100:101], v[12:13], v[100:101]
	v_pk_add_f32 v[108:109], v[108:109], v[108:109] op_sel:[0,1] op_sel_hi:[1,0]
	v_pk_add_f32 v[98:99], v[98:99], v[98:99] op_sel:[0,1] op_sel_hi:[1,0]
	v_pk_fma_f32 v[84:85], v[176:177], v[176:177], v[84:85] op_sel_hi:[1,1,0]
	v_pk_fma_f32 v[126:127], v[82:83], v[82:83], v[126:127] op_sel_hi:[1,1,0]
	v_pk_mul_f32 v[74:75], v[180:181], v[180:181]
	v_pk_mul_f32 v[184:185], v[78:79], v[78:79]
	v_pk_mul_f32 v[24:25], v[100:101], v[24:25]
	v_pk_mul_f32 v[20:21], v[150:151], v[20:21]
	v_mov_b32_e32 v109, v74
	v_mov_b32_e32 v99, v75
	v_mov_b32_e32 v85, v184
	v_mov_b32_e32 v127, v185
	v_cvt_pk_bf16_f32 v20, v20, v21
	v_cvt_pk_bf16_f32 v21, v24, v25
	v_pk_mul_f32 v[24:25], v[148:149], v[168:169] op_sel_hi:[1,0]
	v_pk_mul_f32 v[100:101], v[140:141], v[168:169] op_sel_hi:[1,0]
	v_pk_add_f32 v[74:75], v[108:109], v[98:99]
	v_pk_add_f32 v[84:85], v[84:85], v[126:127]
	global_store_dwordx2 v[170:171], v[20:21], off offset:1024
	v_lshlrev_b32_e32 v20, 16, v18
	v_and_b32_e32 v21, 0xffff0000, v18
	v_lshlrev_b32_e32 v18, 16, v19
	v_and_b32_e32 v19, 0xffff0000, v19
	s_waitcnt lgkmcnt(0)
	v_pk_mul_f32 v[100:101], v[14:15], v[100:101]
	v_pk_mul_f32 v[24:25], v[16:17], v[24:25]
	v_pk_add_f32 v[74:75], v[74:75], v[84:85]
	v_pk_mul_f32 v[18:19], v[24:25], v[18:19]
	v_pk_mul_f32 v[20:21], v[100:101], v[20:21]
	v_add_f32_e32 v74, v74, v75
	v_cvt_pk_bf16_f32 v20, v20, v21
	v_cvt_pk_bf16_f32 v21, v18, v19
	v_add_f32_dpp v74, v74, v74 quad_perm:[1,0,3,2] row_mask:0xf bank_mask:0xf bound_ctrl:1
	global_store_dwordx2 v[170:171], v[20:21], off offset:1536
	ds_read_b128 v[18:21], v166 offset:4096
	v_add_f32_dpp v74, v74, v74 quad_perm:[2,3,0,1] row_mask:0xf bank_mask:0xf bound_ctrl:1
	v_lshlrev_b32_e32 v100, 16, v22
	v_and_b32_e32 v101, 0xffff0000, v22
	v_add_f32_dpp v74, v74, v74 row_half_mirror row_mask:0xf bank_mask:0xf bound_ctrl:1
	v_lshlrev_b32_e32 v140, 16, v23
	v_and_b32_e32 v141, 0xffff0000, v23
	v_add_f32_dpp v74, v74, v74 row_mirror row_mask:0xf bank_mask:0xf bound_ctrl:1
	ds_read_b128 v[22:25], v166 offset:5120
	v_readlane_b32 s8, v74, 16
	v_readlane_b32 s9, v74, 48
	v_pk_mul_f32 v[148:149], v[158:159], v[168:169] op_sel_hi:[1,0]
	v_pk_mul_f32 v[80:81], v[80:81], v[168:169] op_sel_hi:[1,0]
	v_readlane_b32 s6, v74, 0
	v_readlane_b32 s7, v74, 32
	v_mov_b32_e32 v74, s8
	v_mov_b32_e32 v75, s9
	s_waitcnt lgkmcnt(1)
	v_pk_mul_f32 v[80:81], v[18:19], v[80:81]
	v_pk_mul_f32 v[148:149], v[20:21], v[148:149]
	v_pk_add_f32 v[74:75], s[6:7], v[74:75]
	v_pk_mul_f32 v[140:141], v[148:149], v[140:141]
	v_pk_mul_f32 v[80:81], v[80:81], v[100:101]
	v_add_f32_e32 v74, v74, v75
	v_cvt_pk_bf16_f32 v80, v80, v81
	v_cvt_pk_bf16_f32 v81, v140, v141
	v_pk_mul_f32 v[28:29], v[28:29], v[168:169] op_sel_hi:[1,0]
	v_pk_mul_f32 v[32:33], v[32:33], v[168:169] op_sel_hi:[1,0]
	v_fmamk_f32 v74, v74, 0x3a000000, v252
	global_store_dwordx2 v[170:171], v[80:81], off offset:2048
	v_lshlrev_b32_e32 v80, 16, v26
	v_and_b32_e32 v81, 0xffff0000, v26
	v_lshlrev_b32_e32 v26, 16, v27
	v_and_b32_e32 v27, 0xffff0000, v27
	s_waitcnt lgkmcnt(0)
; template <bool HG>
; __device__ __forceinline__ void readout_phase2(const Args& a, Frame& F, const float* gain, int nrows) {
;     ...
;     RO_FINISH(f0, b0, g0, nw);            RO_LOAD(f0, b0, g0, nw + 3 * 2048);
	v_pk_mul_f32 v[32:33], v[32:33], v[22:23]
	v_pk_mul_f32 v[28:29], v[28:29], v[24:25]
	v_mul_f32_e32 v75, 0x4f800000, v74
	v_cmp_gt_f32_e32 vcc, s55, v74
	v_pk_mul_f32 v[26:27], v[28:29], v[26:27]
	v_pk_mul_f32 v[28:29], v[32:33], v[80:81]
	v_cndmask_b32_e32 v74, v74, v75, vcc
	v_cvt_pk_bf16_f32 v28, v28, v29
	v_cvt_pk_bf16_f32 v29, v26, v27
	v_sqrt_f32_e32 v75, v74
	global_store_dwordx2 v[170:171], v[28:29], off offset:2560
	ds_read_b128 v[26:29], v166 offset:6144
	v_lshlrev_b32_e32 v80, 16, v30
	v_and_b32_e32 v81, 0xffff0000, v30
	v_lshlrev_b32_e32 v100, 16, v31
	v_and_b32_e32 v101, 0xffff0000, v31
	ds_read_b128 v[30:33], v166 offset:7168
	v_add_u32_e32 v84, -1, v75
	v_pk_mul_f32 v[140:141], v[164:165], v[168:169] op_sel_hi:[1,0]
	v_pk_mul_f32 v[148:149], v[160:161], v[168:169] op_sel_hi:[1,0]
	v_fma_f32 v85, -v84, v75, v74
	s_waitcnt lgkmcnt(1)
	v_pk_mul_f32 v[148:149], v[148:149], v[26:27]
	v_pk_mul_f32 v[140:141], v[140:141], v[28:29]
	v_cmp_ge_f32_e64 s[8:9], 0, v85
	v_add_u32_e32 v85, 1, v75
	v_pk_mul_f32 v[100:101], v[140:141], v[100:101]
	v_pk_mul_f32 v[80:81], v[148:149], v[80:81]
	v_cndmask_b32_e64 v84, v75, v84, s[8:9]
	v_fma_f32 v75, -v85, v75, v74
	s_lshl_b64 s[14:15], s[12:13], 11
	v_cvt_pk_bf16_f32 v80, v80, v81
	v_cvt_pk_bf16_f32 v81, v100, v101
	v_pk_mul_f32 v[100:101], v[162:163], v[168:169] op_sel_hi:[1,0]
	v_pk_mul_f32 v[90:91], v[90:91], v[168:169] op_sel_hi:[1,0]
	s_lshl_b64 s[12:13], s[10:11], 12
	v_cmp_lt_f32_e64 s[8:9], 0, v75
	global_store_dwordx2 v[170:171], v[80:81], off offset:3072
	v_lshlrev_b32_e32 v80, 16, v76
	v_and_b32_e32 v81, 0xffff0000, v76
	v_lshlrev_b32_e32 v76, 16, v77
	v_and_b32_e32 v77, 0xffff0000, v77
	s_waitcnt lgkmcnt(0)
	v_pk_mul_f32 v[90:91], v[90:91], v[30:31]
	v_pk_mul_f32 v[100:101], v[100:101], v[32:33]
	s_add_u32 s16, s12, 0x1800000
	v_cndmask_b32_e64 v75, v84, v85, s[8:9]
	v_pk_mul_f32 v[76:77], v[100:101], v[76:77]
	v_pk_mul_f32 v[80:81], v[90:91], v[80:81]
	s_addc_u32 s17, s13, 0
	v_mul_f32_e32 v84, 0x37800000, v75
	v_cvt_pk_bf16_f32 v80, v80, v81
	v_cvt_pk_bf16_f32 v81, v76, v77
	v_lshl_add_u64 v[76:77], v[36:37], 0, s[16:17]
	v_cndmask_b32_e32 v75, v75, v84, vcc
	v_cmp_class_f32_e32 vcc, v74, v253
	v_lshl_add_u64 v[140:141], v[76:77], 0, v[0:1]
	v_lshl_add_u64 v[76:77], v[38:39], 0, s[16:17]
	v_cndmask_b32_e32 v84, v75, v74, vcc
	global_store_dwordx2 v[170:171], v[80:81], off offset:3584
	v_lshl_add_u64 v[170:171], v[76:77], 0, v[0:1]
	v_lshl_add_u64 v[76:77], v[40:41], 0, s[16:17]
	v_div_scale_f32 v85, s[6:7], v84, v84, 1.0
	v_lshl_add_u64 v[166:167], v[76:77], 0, v[0:1]
	global_load_dwordx2 v[168:169], v[140:141], off nt
	global_load_dwordx2 v[162:163], v[140:141], off offset:512 nt
	global_load_dwordx2 v[158:159], v[140:141], off offset:1024 nt
	global_load_dwordx2 v[154:155], v[140:141], off offset:1536 nt
	global_load_dwordx2 v[174:175], v[170:171], off nt
	global_load_dwordx2 v[164:165], v[170:171], off offset:512 nt
	global_load_dwordx2 v[160:161], v[170:171], off offset:1024 nt
	global_load_dwordx2 v[156:157], v[170:171], off offset:1536 nt
	global_load_dwordx2 v[100:101], v[166:167], off nt
	global_load_dwordx2 v[90:91], v[166:167], off offset:512 nt
	global_load_dwordx2 v[80:81], v[166:167], off offset:1024 nt
	global_load_dwordx2 v[76:77], v[166:167], off offset:1536 nt
	global_load_dwordx2 v[152:153], v[140:141], off offset:2048 nt
	global_load_dwordx2 v[150:151], v[140:141], off offset:2560 nt
	global_load_dwordx2 v[148:149], v[140:141], off offset:3072 nt
	s_nop 0
	global_load_dwordx2 v[140:141], v[140:141], off offset:3584 nt
	s_nop 0
	global_load_dwordx2 v[196:197], v[170:171], off offset:2048 nt
	global_load_dwordx2 v[192:193], v[170:171], off offset:2560 nt
	global_load_dwordx2 v[188:189], v[170:171], off offset:3072 nt
	global_load_dwordx2 v[184:185], v[170:171], off offset:3584 nt
	v_rcp_f32_e32 v170, v85
	global_load_dwordx2 v[126:127], v[166:167], off offset:2048 nt
	global_load_dwordx2 v[108:109], v[166:167], off offset:2560 nt
	global_load_dwordx2 v[98:99], v[166:167], off offset:3072 nt
	global_load_dwordx2 v[74:75], v[166:167], off offset:3584 nt
	v_fma_f32 v166, -v85, v170, 1.0
	v_fmac_f32_e32 v170, v166, v170
	v_div_scale_f32 v166, vcc, 1.0, v84, 1.0
	v_mul_f32_e32 v167, v166, v170
	v_fma_f32 v171, -v85, v167, v166
	v_fmac_f32_e32 v167, v171, v170
	v_fma_f32 v85, -v85, v167, v166
	v_div_fmas_f32 v85, v85, v170, v167
	v_div_fixup_f32 v84, v85, v84, 1.0
	v_pk_mul_f32 v[146:147], v[146:147], v[84:85] op_sel_hi:[1,0]
	v_pk_mul_f32 v[172:173], v[172:173], v[84:85] op_sel_hi:[1,0]
	v_lshlrev_b32_e32 v170, 16, v72
	v_and_b32_e32 v171, 0xffff0000, v72
	v_lshlrev_b32_e32 v72, 16, v73
	v_and_b32_e32 v73, 0xffff0000, v73
	v_pk_mul_f32 v[172:173], v[2:3], v[172:173]
	v_pk_mul_f32 v[146:147], v[4:5], v[146:147]
	v_pk_mul_f32 v[138:139], v[138:139], v[84:85] op_sel_hi:[1,0]
	v_pk_mul_f32 v[72:73], v[146:147], v[72:73]
	v_pk_mul_f32 v[146:147], v[172:173], v[170:171]
	v_pk_mul_f32 v[144:145], v[144:145], v[84:85] op_sel_hi:[1,0]
	v_cvt_pk_bf16_f32 v146, v146, v147
	v_cvt_pk_bf16_f32 v147, v72, v73
	v_lshlrev_b32_e32 v72, 16, v70
	v_and_b32_e32 v73, 0xffff0000, v70
	v_lshlrev_b32_e32 v70, 16, v71
	v_and_b32_e32 v71, 0xffff0000, v71
	v_pk_mul_f32 v[144:145], v[6:7], v[144:145]
	v_pk_mul_f32 v[138:139], v[8:9], v[138:139]
	v_lshl_add_u64 v[166:167], s[18:19], 1, v[34:35]
	v_pk_mul_f32 v[70:71], v[138:139], v[70:71]
	v_pk_mul_f32 v[72:73], v[144:145], v[72:73]
	v_lshl_add_u64 v[166:167], v[166:167], 0, v[0:1]
	v_cvt_pk_bf16_f32 v72, v72, v73
	v_cvt_pk_bf16_f32 v73, v70, v71
	global_store_dwordx2 v[166:167], v[72:73], off offset:512
	v_pk_mul_f32 v[72:73], v[178:179], v[84:85] op_sel_hi:[1,0]
; template <bool HG>
; __device__ __forceinline__ void readout_phase2(const Args& a, Frame& F, const float* gain, int nrows) {
;     ...
;     RO_FINISH(f1, b1, g1, nw + 2048);     RO_LOAD(f1, b1, g1, nw + 4 * 2048);
	v_pk_mul_f32 v[138:139], v[142:143], v[84:85] op_sel_hi:[1,0]
	v_lshlrev_b32_e32 v70, 16, v66
	v_and_b32_e32 v71, 0xffff0000, v66
	v_lshlrev_b32_e32 v66, 16, v67
	v_and_b32_e32 v67, 0xffff0000, v67
	v_pk_mul_f32 v[138:139], v[10:11], v[138:139]
	v_pk_mul_f32 v[72:73], v[12:13], v[72:73]
	v_pk_mul_f32 v[70:71], v[138:139], v[70:71]
	v_pk_mul_f32 v[66:67], v[72:73], v[66:67]
	v_cvt_pk_bf16_f32 v70, v70, v71
	v_cvt_pk_bf16_f32 v71, v66, v67
	global_store_dwordx2 v[166:167], v[70:71], off offset:1024
	v_pk_mul_f32 v[70:71], v[118:119], v[84:85] op_sel_hi:[1,0]
	v_pk_mul_f32 v[72:73], v[128:129], v[84:85] op_sel_hi:[1,0]
	v_lshlrev_b32_e32 v66, 16, v60
	v_and_b32_e32 v67, 0xffff0000, v60
	v_lshlrev_b32_e32 v60, 16, v61
	v_and_b32_e32 v61, 0xffff0000, v61
	v_pk_mul_f32 v[72:73], v[14:15], v[72:73]
	v_pk_mul_f32 v[70:71], v[16:17], v[70:71]
	v_pk_mul_f32 v[66:67], v[72:73], v[66:67]
	v_pk_mul_f32 v[60:61], v[70:71], v[60:61]
	v_cvt_pk_bf16_f32 v66, v66, v67
	v_cvt_pk_bf16_f32 v67, v60, v61
	global_store_dwordx2 v[166:167], v[66:67], off offset:1536
	v_pk_mul_f32 v[66:67], v[106:107], v[84:85] op_sel_hi:[1,0]
	v_pk_mul_f32 v[70:71], v[186:187], v[84:85] op_sel_hi:[1,0]
	v_lshlrev_b32_e32 v60, 16, v54
	v_and_b32_e32 v61, 0xffff0000, v54
	v_lshlrev_b32_e32 v54, 16, v55
	v_and_b32_e32 v55, 0xffff0000, v55
	v_pk_mul_f32 v[70:71], v[18:19], v[70:71]
	v_pk_mul_f32 v[66:67], v[20:21], v[66:67]
	v_pk_mul_f32 v[60:61], v[70:71], v[60:61]
	v_pk_mul_f32 v[54:55], v[66:67], v[54:55]
	v_cvt_pk_bf16_f32 v60, v60, v61
	v_cvt_pk_bf16_f32 v61, v54, v55
	global_store_dwordx2 v[166:167], v[60:61], off offset:2048
	v_pk_mul_f32 v[60:61], v[96:97], v[84:85] op_sel_hi:[1,0]
	v_pk_mul_f32 v[66:67], v[120:121], v[84:85] op_sel_hi:[1,0]
	v_lshlrev_b32_e32 v54, 16, v46
	v_and_b32_e32 v55, 0xffff0000, v46
	v_lshlrev_b32_e32 v46, 16, v47
	v_and_b32_e32 v47, 0xffff0000, v47
	v_pk_mul_f32 v[66:67], v[22:23], v[66:67]
	v_pk_mul_f32 v[60:61], v[24:25], v[60:61]
	v_pk_mul_f32 v[54:55], v[66:67], v[54:55]
	v_pk_mul_f32 v[46:47], v[60:61], v[46:47]
	v_cvt_pk_bf16_f32 v54, v54, v55
	v_cvt_pk_bf16_f32 v55, v46, v47
	global_store_dwordx2 v[166:167], v[54:55], off offset:2560
	v_pk_mul_f32 v[54:55], v[82:83], v[84:85] op_sel_hi:[1,0]
	v_pk_mul_f32 v[60:61], v[176:177], v[84:85] op_sel_hi:[1,0]
	v_lshlrev_b32_e32 v46, 16, v44
	v_and_b32_e32 v47, 0xffff0000, v44
	v_lshlrev_b32_e32 v44, 16, v45
	v_and_b32_e32 v45, 0xffff0000, v45
	v_pk_mul_f32 v[60:61], v[26:27], v[60:61]
	v_pk_mul_f32 v[54:55], v[28:29], v[54:55]
	v_pk_mul_f32 v[46:47], v[60:61], v[46:47]
	v_pk_mul_f32 v[44:45], v[54:55], v[44:45]
	v_cvt_pk_bf16_f32 v46, v46, v47
	v_cvt_pk_bf16_f32 v47, v44, v45
	global_store_dwordx2 v[166:167], v[46:47], off offset:3072
	v_pk_mul_f32 v[46:47], v[78:79], v[84:85] op_sel_hi:[1,0]
	v_pk_mul_f32 v[54:55], v[180:181], v[84:85] op_sel_hi:[1,0]
	s_waitcnt vmcnt(62)
	v_lshlrev_b32_e32 v44, 16, v42
	v_and_b32_e32 v45, 0xffff0000, v42
	v_lshlrev_b32_e32 v42, 16, v43
	v_and_b32_e32 v43, 0xffff0000, v43
	v_pk_mul_f32 v[54:55], v[30:31], v[54:55]
	v_pk_mul_f32 v[46:47], v[32:33], v[46:47]
	s_add_u32 s18, s12, 0x2000000
	v_pk_mul_f32 v[42:43], v[46:47], v[42:43]
	v_pk_mul_f32 v[44:45], v[54:55], v[44:45]
	s_addc_u32 s19, s13, 0
	v_cvt_pk_bf16_f32 v44, v44, v45
	v_cvt_pk_bf16_f32 v45, v42, v43
	v_lshl_add_u64 v[42:43], v[36:37], 0, s[18:19]
	v_lshl_add_u64 v[70:71], v[42:43], 0, v[0:1]
	v_lshl_add_u64 v[42:43], v[38:39], 0, s[18:19]
	global_store_dwordx2 v[166:167], v[146:147], off
	global_store_dwordx2 v[166:167], v[44:45], off offset:3584
	v_lshl_add_u64 v[44:45], v[42:43], 0, v[0:1]
	v_lshl_add_u64 v[42:43], v[40:41], 0, s[18:19]
	v_lshl_add_u64 v[42:43], v[42:43], 0, v[0:1]
	global_load_dwordx2 v[170:171], v[70:71], off nt
	global_load_dwordx2 v[144:145], v[70:71], off offset:512 nt
	global_load_dwordx2 v[138:139], v[70:71], off offset:1024 nt
	global_load_dwordx2 v[118:119], v[70:71], off offset:1536 nt
	global_load_dwordx2 v[176:177], v[44:45], off nt
	global_load_dwordx2 v[146:147], v[44:45], off offset:512 nt
	global_load_dwordx2 v[142:143], v[44:45], off offset:1024 nt
	global_load_dwordx2 v[120:121], v[44:45], off offset:1536 nt
	global_load_dwordx2 v[66:67], v[42:43], off nt
	global_load_dwordx2 v[60:61], v[42:43], off offset:512 nt
	global_load_dwordx2 v[54:55], v[42:43], off offset:1024 nt
	global_load_dwordx2 v[46:47], v[42:43], off offset:1536 nt
	global_load_dwordx2 v[106:107], v[70:71], off offset:2048 nt
	global_load_dwordx2 v[96:97], v[70:71], off offset:2560 nt
	global_load_dwordx2 v[82:83], v[70:71], off offset:3072 nt
	global_load_dwordx2 v[72:73], v[70:71], off offset:3584 nt
	s_waitcnt vmcnt(62)
	v_lshlrev_b32_e32 v70, 16, v136
	v_and_b32_e32 v71, 0xffff0000, v136
	v_lshlrev_b32_e32 v78, 16, v134
	v_and_b32_e32 v79, 0xffff0000, v134
	v_pk_add_f32 v[78:79], v[70:71], v[78:79]
	v_lshlrev_b32_e32 v70, 16, v137
	v_and_b32_e32 v71, 0xffff0000, v137
	v_lshlrev_b32_e32 v84, 16, v135
	v_and_b32_e32 v85, 0xffff0000, v135
	v_pk_add_f32 v[128:129], v[70:71], v[84:85]
	v_lshlrev_b32_e32 v70, 16, v132
	v_and_b32_e32 v71, 0xffff0000, v132
	v_lshlrev_b32_e32 v84, 16, v130
	v_and_b32_e32 v85, 0xffff0000, v130
	v_pk_add_f32 v[70:71], v[70:71], v[84:85]
	v_lshlrev_b32_e32 v84, 16, v133
	v_and_b32_e32 v85, 0xffff0000, v133
	v_lshlrev_b32_e32 v130, 16, v131
	v_and_b32_e32 v131, 0xffff0000, v131
	v_pk_add_f32 v[84:85], v[84:85], v[130:131]
	v_mov_b32_e32 v132, v79
	v_mov_b32_e32 v133, v71
	v_mov_b32_e32 v130, v78
	v_mov_b32_e32 v131, v70
	v_pk_mul_f32 v[132:133], v[132:133], v[132:133]
	v_mov_b32_e32 v134, v129
	v_mov_b32_e32 v135, v85
	v_pk_fma_f32 v[130:131], v[130:131], v[130:131], v[132:133]
	v_mov_b32_e32 v132, v128
	v_mov_b32_e32 v133, v84
	v_pk_mul_f32 v[134:135], v[134:135], v[134:135]
	v_lshlrev_b32_e32 v136, 16, v116
	v_pk_fma_f32 v[132:133], v[132:133], v[132:133], v[134:135]
	v_lshlrev_b32_e32 v134, 16, v122
	v_pk_add_f32 v[130:131], v[130:131], v[132:133]
	v_and_b32_e32 v135, 0xffff0000, v122
	v_pk_add_f32 v[132:133], v[130:131], v[130:131] op_sel:[0,1] op_sel_hi:[1,0]
	v_lshlrev_b32_e32 v130, 16, v124
	v_and_b32_e32 v131, 0xffff0000, v124
	v_lshlrev_b32_e32 v124, 16, v125
	v_and_b32_e32 v125, 0xffff0000, v125
	v_lshlrev_b32_e32 v122, 16, v123
	v_and_b32_e32 v123, 0xffff0000, v123
	v_pk_add_f32 v[130:131], v[130:131], v[134:135]
	v_pk_add_f32 v[134:135], v[124:125], v[122:123]
	v_mov_b32_e32 v124, v131
	v_mov_b32_e32 v125, v135
	v_mov_b32_e32 v122, v130
	v_mov_b32_e32 v123, v134
	v_pk_mul_f32 v[124:125], v[124:125], v[124:125]
	v_and_b32_e32 v137, 0xffff0000, v116
	v_pk_fma_f32 v[122:123], v[122:123], v[122:123], v[124:125]
	v_lshlrev_b32_e32 v124, 16, v114
	v_and_b32_e32 v125, 0xffff0000, v114
	v_lshlrev_b32_e32 v114, 16, v115
	v_and_b32_e32 v115, 0xffff0000, v115
	v_lshlrev_b32_e32 v116, 16, v117
	v_and_b32_e32 v117, 0xffff0000, v117
	v_pk_add_f32 v[124:125], v[124:125], v[136:137]
	v_pk_add_f32 v[114:115], v[114:115], v[116:117]
	v_lshlrev_b32_e32 v166, 16, v112
	v_and_b32_e32 v167, 0xffff0000, v112
	v_lshlrev_b32_e32 v172, 16, v110
	v_and_b32_e32 v173, 0xffff0000, v110
	v_lshlrev_b32_e32 v112, 16, v113
	v_and_b32_e32 v113, 0xffff0000, v113
	v_lshlrev_b32_e32 v110, 16, v111
	v_and_b32_e32 v111, 0xffff0000, v111
	v_mul_f32_e32 v116, v125, v125
	v_mul_f32_e32 v136, v115, v115
	v_pk_add_f32 v[166:167], v[166:167], v[172:173]
	v_pk_add_f32 v[112:113], v[112:113], v[110:111]
	v_pk_add_f32 v[122:123], v[122:123], v[122:123] op_sel:[0,1] op_sel_hi:[1,0]
	v_pk_fma_f32 v[116:117], v[124:125], v[124:125], v[116:117] op_sel_hi:[1,1,0]
	v_pk_fma_f32 v[136:137], v[114:115], v[114:115], v[136:137] op_sel_hi:[1,1,0]
	v_pk_mul_f32 v[110:111], v[166:167], v[166:167]
	v_pk_mul_f32 v[172:173], v[112:113], v[112:113]
	v_mov_b32_e32 v133, v110
	v_mov_b32_e32 v123, v111
	v_mov_b32_e32 v117, v172
	v_mov_b32_e32 v137, v173
	v_pk_add_f32 v[110:111], v[132:133], v[122:123]
	v_pk_add_f32 v[116:117], v[116:117], v[136:137]
	v_lshlrev_b32_e32 v122, 16, v102
	v_pk_add_f32 v[110:111], v[110:111], v[116:117]
	v_lshlrev_b32_e32 v116, 16, v104
	v_and_b32_e32 v117, 0xffff0000, v104
	v_and_b32_e32 v123, 0xffff0000, v102
	v_lshlrev_b32_e32 v104, 16, v105
	v_and_b32_e32 v105, 0xffff0000, v105
	v_lshlrev_b32_e32 v102, 16, v103
	v_and_b32_e32 v103, 0xffff0000, v103
	v_pk_add_f32 v[116:117], v[116:117], v[122:123]
	v_pk_add_f32 v[102:103], v[104:105], v[102:103]
	v_mov_b32_e32 v122, v117
	v_mov_b32_e32 v123, v103
	v_mov_b32_e32 v104, v116
	v_mov_b32_e32 v105, v102
	v_pk_mul_f32 v[122:123], v[122:123], v[122:123]
	s_waitcnt vmcnt(60)
	v_lshlrev_b32_e32 v132, 16, v92
	v_pk_fma_f32 v[104:105], v[104:105], v[104:105], v[122:123]
	v_lshlrev_b32_e32 v122, 16, v94
	v_and_b32_e32 v123, 0xffff0000, v94
	v_and_b32_e32 v133, 0xffff0000, v92
	v_lshlrev_b32_e32 v94, 16, v95
	v_and_b32_e32 v95, 0xffff0000, v95
	v_lshlrev_b32_e32 v92, 16, v93
	v_and_b32_e32 v93, 0xffff0000, v93
	v_pk_add_f32 v[132:133], v[122:123], v[132:133]
	v_pk_add_f32 v[92:93], v[94:95], v[92:93]
	s_waitcnt vmcnt(58)
	v_lshlrev_b32_e32 v136, 16, v86
	v_and_b32_e32 v137, 0xffff0000, v86
	s_waitcnt vmcnt(57)
; template <bool HG>
; __device__ __forceinline__ void readout_phase2(const Args& a, Frame& F, const float* gain, int nrows) {
;     ...
;     RO_FINISH(f1, b1, g1, nw + 2048);     RO_LOAD(f1, b1, g1, nw + 4 * 2048);
	v_lshlrev_b32_e32 v172, 16, v88
	v_and_b32_e32 v173, 0xffff0000, v88
	v_lshlrev_b32_e32 v86, 16, v87
	v_and_b32_e32 v87, 0xffff0000, v87
	v_lshlrev_b32_e32 v88, 16, v89
	v_and_b32_e32 v89, 0xffff0000, v89
	v_mul_f32_e32 v94, v133, v133
	v_mul_f32_e32 v122, v93, v93
	v_pk_add_f32 v[136:137], v[136:137], v[172:173]
	v_pk_add_f32 v[86:87], v[86:87], v[88:89]
	v_pk_add_f32 v[110:111], v[110:111], v[110:111] op_sel:[0,1] op_sel_hi:[1,0]
	v_pk_add_f32 v[104:105], v[104:105], v[104:105] op_sel:[0,1] op_sel_hi:[1,0]
	v_pk_fma_f32 v[94:95], v[132:133], v[132:133], v[94:95] op_sel_hi:[1,1,0]
	v_pk_fma_f32 v[122:123], v[92:93], v[92:93], v[122:123] op_sel_hi:[1,1,0]
	v_pk_mul_f32 v[88:89], v[136:137], v[136:137]
	v_pk_mul_f32 v[172:173], v[86:87], v[86:87]
	v_mov_b32_e32 v111, v88
	v_mov_b32_e32 v105, v89
	v_mov_b32_e32 v95, v172
	v_mov_b32_e32 v123, v173
	v_pk_add_f32 v[88:89], v[110:111], v[104:105]
	v_pk_add_f32 v[94:95], v[94:95], v[122:123]
	global_load_dwordx2 v[198:199], v[44:45], off offset:2048 nt
	global_load_dwordx2 v[194:195], v[44:45], off offset:2560 nt
	global_load_dwordx2 v[190:191], v[44:45], off offset:3072 nt
	global_load_dwordx2 v[186:187], v[44:45], off offset:3584 nt
	v_pk_add_f32 v[88:89], v[88:89], v[94:95]
	s_nop 0
	v_add_f32_e32 v88, v88, v89
	s_nop 1
	v_add_f32_dpp v88, v88, v88 quad_perm:[1,0,3,2] row_mask:0xf bank_mask:0xf bound_ctrl:1
	s_nop 1
	v_add_f32_dpp v88, v88, v88 quad_perm:[2,3,0,1] row_mask:0xf bank_mask:0xf bound_ctrl:1
	s_nop 1
	v_add_f32_dpp v88, v88, v88 row_half_mirror row_mask:0xf bank_mask:0xf bound_ctrl:1
	s_nop 1
	v_add_f32_dpp v88, v88, v88 row_mirror row_mask:0xf bank_mask:0xf bound_ctrl:1
	s_nop 0
	v_readlane_b32 s8, v88, 16
	v_readlane_b32 s9, v88, 48
	v_readlane_b32 s6, v88, 0
	v_readlane_b32 s7, v88, 32
	v_mov_b32_e32 v88, s8
	v_mov_b32_e32 v89, s9
	v_pk_add_f32 v[88:89], s[6:7], v[88:89]
	s_nop 0
	v_add_f32_e32 v88, v88, v89
	v_fmamk_f32 v88, v88, 0x3a000000, v252
	v_mul_f32_e32 v89, 0x4f800000, v88
	v_cmp_gt_f32_e32 vcc, s55, v88
	s_nop 1
	v_cndmask_b32_e32 v88, v88, v89, vcc
	v_sqrt_f32_e32 v89, v88
	s_nop 0
	v_add_u32_e32 v44, -1, v89
	v_fma_f32 v45, -v44, v89, v88
	v_cmp_ge_f32_e64 s[8:9], 0, v45
	v_add_u32_e32 v45, 1, v89
	s_nop 0
	v_cndmask_b32_e64 v44, v89, v44, s[8:9]
	v_fma_f32 v89, -v45, v89, v88
	v_cmp_lt_f32_e64 s[8:9], 0, v89
	s_nop 1
	v_cndmask_b32_e64 v44, v44, v45, s[8:9]
	v_mul_f32_e32 v45, 0x37800000, v44
	v_cndmask_b32_e32 v44, v44, v45, vcc
	v_cmp_class_f32_e32 vcc, v88, v253
	s_nop 1
	v_cndmask_b32_e32 v44, v44, v88, vcc
	v_div_scale_f32 v45, s[6:7], v44, v44, 1.0
	v_rcp_f32_e32 v104, v45
	global_load_dwordx2 v[122:123], v[42:43], off offset:2048 nt
	global_load_dwordx2 v[110:111], v[42:43], off offset:2560 nt
	global_load_dwordx2 v[94:95], v[42:43], off offset:3072 nt
	global_load_dwordx2 v[88:89], v[42:43], off offset:3584 nt
	v_fma_f32 v42, -v45, v104, 1.0
	v_fmac_f32_e32 v104, v42, v104
	v_div_scale_f32 v42, vcc, 1.0, v44, 1.0
	v_mul_f32_e32 v43, v42, v104
	v_fma_f32 v105, -v45, v43, v42
	v_fmac_f32_e32 v43, v105, v104
	v_fma_f32 v42, -v45, v43, v42
	v_div_fmas_f32 v42, v42, v104, v43
	v_div_fixup_f32 v42, v42, v44, 1.0
	v_pk_mul_f32 v[128:129], v[128:129], v[42:43] op_sel_hi:[1,0]
	v_pk_mul_f32 v[78:79], v[78:79], v[42:43] op_sel_hi:[1,0]
	v_lshlrev_b32_e32 v104, 16, v68
	v_and_b32_e32 v105, 0xffff0000, v68
	v_lshlrev_b32_e32 v68, 16, v69
	v_and_b32_e32 v69, 0xffff0000, v69
	v_pk_mul_f32 v[78:79], v[2:3], v[78:79]
	v_pk_mul_f32 v[128:129], v[4:5], v[128:129]
	v_lshl_add_u64 v[44:45], s[14:15], 1, v[34:35]
	v_pk_mul_f32 v[68:69], v[128:129], v[68:69]
	v_pk_mul_f32 v[78:79], v[78:79], v[104:105]
	v_lshl_add_u64 v[44:45], v[44:45], 0, v[0:1]
	v_cvt_pk_bf16_f32 v78, v78, v79
	v_cvt_pk_bf16_f32 v79, v68, v69
	global_store_dwordx2 v[44:45], v[78:79], off
	v_pk_mul_f32 v[78:79], v[84:85], v[42:43] op_sel_hi:[1,0]
	v_pk_mul_f32 v[70:71], v[70:71], v[42:43] op_sel_hi:[1,0]
	v_lshlrev_b32_e32 v68, 16, v64
	v_and_b32_e32 v69, 0xffff0000, v64
	v_lshlrev_b32_e32 v64, 16, v65
	v_and_b32_e32 v65, 0xffff0000, v65
	v_pk_mul_f32 v[70:71], v[6:7], v[70:71]
	v_pk_mul_f32 v[78:79], v[8:9], v[78:79]
	v_pk_mul_f32 v[68:69], v[70:71], v[68:69]
	v_pk_mul_f32 v[64:65], v[78:79], v[64:65]
	v_cvt_pk_bf16_f32 v68, v68, v69
	v_cvt_pk_bf16_f32 v69, v64, v65
	global_store_dwordx2 v[44:45], v[68:69], off offset:512
	v_pk_mul_f32 v[68:69], v[134:135], v[42:43] op_sel_hi:[1,0]
	v_pk_mul_f32 v[70:71], v[130:131], v[42:43] op_sel_hi:[1,0]
	v_lshlrev_b32_e32 v64, 16, v58
	v_and_b32_e32 v65, 0xffff0000, v58
	v_lshlrev_b32_e32 v58, 16, v59
	v_and_b32_e32 v59, 0xffff0000, v59
	v_pk_mul_f32 v[70:71], v[10:11], v[70:71]
	v_pk_mul_f32 v[68:69], v[12:13], v[68:69]
	v_pk_mul_f32 v[64:65], v[70:71], v[64:65]
	v_pk_mul_f32 v[58:59], v[68:69], v[58:59]
	v_cvt_pk_bf16_f32 v64, v64, v65
	v_cvt_pk_bf16_f32 v65, v58, v59
	global_store_dwordx2 v[44:45], v[64:65], off offset:1024
	v_pk_mul_f32 v[64:65], v[114:115], v[42:43] op_sel_hi:[1,0]
	v_pk_mul_f32 v[68:69], v[124:125], v[42:43] op_sel_hi:[1,0]
	v_lshlrev_b32_e32 v58, 16, v62
	v_and_b32_e32 v59, 0xffff0000, v62
	v_lshlrev_b32_e32 v62, 16, v63
	v_and_b32_e32 v63, 0xffff0000, v63
	v_pk_mul_f32 v[68:69], v[14:15], v[68:69]
	v_pk_mul_f32 v[64:65], v[16:17], v[64:65]
	v_pk_mul_f32 v[58:59], v[68:69], v[58:59]
	v_pk_mul_f32 v[62:63], v[64:65], v[62:63]
	v_cvt_pk_bf16_f32 v58, v58, v59
	v_cvt_pk_bf16_f32 v59, v62, v63
	v_pk_mul_f32 v[62:63], v[112:113], v[42:43] op_sel_hi:[1,0]
	v_pk_mul_f32 v[64:65], v[166:167], v[42:43] op_sel_hi:[1,0]
	global_store_dwordx2 v[44:45], v[58:59], off offset:1536
	v_lshlrev_b32_e32 v58, 16, v56
	v_and_b32_e32 v59, 0xffff0000, v56
; template <bool HG>
; __device__ __forceinline__ void readout_phase2(const Args& a, Frame& F, const float* gain, int nrows) {
;     ...
;     RO_FINISH(f2, b2, g2, nw + 2 * 2048); RO_LOAD(f2, b2, g2, nw + 5 * 2048);
	v_lshlrev_b32_e32 v56, 16, v57
	v_and_b32_e32 v57, 0xffff0000, v57
	v_pk_mul_f32 v[64:65], v[18:19], v[64:65]
	v_pk_mul_f32 v[62:63], v[20:21], v[62:63]
	v_pk_mul_f32 v[58:59], v[64:65], v[58:59]
	v_pk_mul_f32 v[56:57], v[62:63], v[56:57]
	v_cvt_pk_bf16_f32 v58, v58, v59
	v_cvt_pk_bf16_f32 v59, v56, v57
	global_store_dwordx2 v[44:45], v[58:59], off offset:2048
	v_pk_mul_f32 v[58:59], v[102:103], v[42:43] op_sel_hi:[1,0]
	v_pk_mul_f32 v[62:63], v[116:117], v[42:43] op_sel_hi:[1,0]
	v_lshlrev_b32_e32 v56, 16, v52
	v_and_b32_e32 v57, 0xffff0000, v52
	v_lshlrev_b32_e32 v52, 16, v53
	v_and_b32_e32 v53, 0xffff0000, v53
	v_pk_mul_f32 v[62:63], v[22:23], v[62:63]
	v_pk_mul_f32 v[58:59], v[24:25], v[58:59]
	v_pk_mul_f32 v[56:57], v[62:63], v[56:57]
	v_pk_mul_f32 v[52:53], v[58:59], v[52:53]
	v_cvt_pk_bf16_f32 v56, v56, v57
	v_cvt_pk_bf16_f32 v57, v52, v53
	global_store_dwordx2 v[44:45], v[56:57], off offset:2560
	v_pk_mul_f32 v[56:57], v[92:93], v[42:43] op_sel_hi:[1,0]
	v_pk_mul_f32 v[58:59], v[132:133], v[42:43] op_sel_hi:[1,0]
	v_lshlrev_b32_e32 v52, 16, v48
	v_and_b32_e32 v53, 0xffff0000, v48
	v_lshlrev_b32_e32 v48, 16, v49
	v_and_b32_e32 v49, 0xffff0000, v49
	v_pk_mul_f32 v[58:59], v[26:27], v[58:59]
	v_pk_mul_f32 v[56:57], v[28:29], v[56:57]
	v_pk_mul_f32 v[52:53], v[58:59], v[52:53]
	v_pk_mul_f32 v[48:49], v[56:57], v[48:49]
	v_cvt_pk_bf16_f32 v52, v52, v53
	v_cvt_pk_bf16_f32 v53, v48, v49
	global_store_dwordx2 v[44:45], v[52:53], off offset:3072
	v_pk_mul_f32 v[52:53], v[86:87], v[42:43] op_sel_hi:[1,0]
	v_pk_mul_f32 v[42:43], v[136:137], v[42:43] op_sel_hi:[1,0]
	s_waitcnt vmcnt(62)
	v_lshlrev_b32_e32 v48, 16, v50
	v_and_b32_e32 v49, 0xffff0000, v50
	v_lshlrev_b32_e32 v50, 16, v51
	v_and_b32_e32 v51, 0xffff0000, v51
	v_pk_mul_f32 v[42:43], v[30:31], v[42:43]
	v_pk_mul_f32 v[52:53], v[32:33], v[52:53]
	v_pk_mul_f32 v[42:43], v[42:43], v[48:49]
	v_pk_mul_f32 v[50:51], v[52:53], v[50:51]
	s_add_u32 s14, s12, 0x2800000
	v_cvt_pk_bf16_f32 v42, v42, v43
	v_cvt_pk_bf16_f32 v43, v50, v51
	s_addc_u32 s15, s13, 0
	global_store_dwordx2 v[44:45], v[42:43], off offset:3584
	v_lshl_add_u64 v[42:43], v[36:37], 0, s[14:15]
	v_lshl_add_u64 v[52:53], v[42:43], 0, v[0:1]
	v_lshl_add_u64 v[42:43], v[38:39], 0, s[14:15]
	v_lshl_add_u64 v[48:49], v[42:43], 0, v[0:1]
	v_lshl_add_u64 v[42:43], v[40:41], 0, s[14:15]
	v_lshl_add_u64 v[42:43], v[42:43], 0, v[0:1]
	global_load_dwordx2 v[166:167], v[52:53], off nt
	global_load_dwordx2 v[134:135], v[52:53], off offset:512 nt
	global_load_dwordx2 v[128:129], v[52:53], off offset:1024 nt
	global_load_dwordx2 v[112:113], v[52:53], off offset:1536 nt
	global_load_dwordx2 v[172:173], v[48:49], off nt
	global_load_dwordx2 v[136:137], v[48:49], off offset:512 nt
	global_load_dwordx2 v[130:131], v[48:49], off offset:1024 nt
	global_load_dwordx2 v[114:115], v[48:49], off offset:1536 nt
	global_load_dwordx2 v[62:63], v[42:43], off nt
	global_load_dwordx2 v[56:57], v[42:43], off offset:512 nt
	global_load_dwordx2 v[50:51], v[42:43], off offset:1024 nt
	global_load_dwordx2 v[44:45], v[42:43], off offset:1536 nt
	global_load_dwordx2 v[102:103], v[52:53], off offset:2048 nt
	global_load_dwordx2 v[84:85], v[52:53], off offset:2560 nt
	global_load_dwordx2 v[78:79], v[52:53], off offset:3072 nt
	global_load_dwordx2 v[70:71], v[52:53], off offset:3584 nt
	v_lshlrev_b32_e32 v52, 16, v168
	v_and_b32_e32 v53, 0xffff0000, v168
	s_waitcnt vmcnt(62)
	v_lshlrev_b32_e32 v58, 16, v174
	v_and_b32_e32 v59, 0xffff0000, v174
	v_pk_add_f32 v[58:59], v[52:53], v[58:59]
	v_lshlrev_b32_e32 v52, 16, v169
	v_and_b32_e32 v53, 0xffff0000, v169
	v_lshlrev_b32_e32 v64, 16, v175
	v_and_b32_e32 v65, 0xffff0000, v175
	v_pk_add_f32 v[68:69], v[52:53], v[64:65]
	v_lshlrev_b32_e32 v52, 16, v162
	v_and_b32_e32 v53, 0xffff0000, v162
	v_lshlrev_b32_e32 v64, 16, v164
	v_and_b32_e32 v65, 0xffff0000, v164
	v_pk_add_f32 v[52:53], v[52:53], v[64:65]
	v_lshlrev_b32_e32 v64, 16, v163
	v_and_b32_e32 v65, 0xffff0000, v163
	v_lshlrev_b32_e32 v86, 16, v165
	v_and_b32_e32 v87, 0xffff0000, v165
	v_pk_add_f32 v[64:65], v[64:65], v[86:87]
	v_mov_b32_e32 v92, v59
	v_mov_b32_e32 v93, v53
	v_mov_b32_e32 v86, v58
	v_mov_b32_e32 v87, v52
	v_pk_mul_f32 v[92:93], v[92:93], v[92:93]
	v_mov_b32_e32 v104, v69
	v_mov_b32_e32 v105, v65
	v_pk_fma_f32 v[86:87], v[86:87], v[86:87], v[92:93]
	v_mov_b32_e32 v92, v68
	v_mov_b32_e32 v93, v64
	v_pk_mul_f32 v[104:105], v[104:105], v[104:105]
	v_lshlrev_b32_e32 v116, 16, v156
	v_pk_fma_f32 v[92:93], v[92:93], v[92:93], v[104:105]
	v_lshlrev_b32_e32 v104, 16, v160
	v_pk_add_f32 v[86:87], v[86:87], v[92:93]
	v_lshlrev_b32_e32 v92, 16, v158
	v_and_b32_e32 v93, 0xffff0000, v158
	v_and_b32_e32 v105, 0xffff0000, v160
	v_pk_add_f32 v[124:125], v[92:93], v[104:105]
	v_lshlrev_b32_e32 v92, 16, v159
	v_and_b32_e32 v93, 0xffff0000, v159
	v_lshlrev_b32_e32 v104, 16, v161
	v_and_b32_e32 v105, 0xffff0000, v161
	v_pk_add_f32 v[158:159], v[92:93], v[104:105]
	v_mov_b32_e32 v104, v125
	v_mov_b32_e32 v105, v159
	v_mov_b32_e32 v92, v124
	v_mov_b32_e32 v93, v158
	v_pk_mul_f32 v[104:105], v[104:105], v[104:105]
	v_and_b32_e32 v117, 0xffff0000, v156
	v_pk_fma_f32 v[92:93], v[92:93], v[92:93], v[104:105]
	v_lshlrev_b32_e32 v104, 16, v154
	v_and_b32_e32 v105, 0xffff0000, v154
	v_pk_add_f32 v[132:133], v[104:105], v[116:117]
	v_lshlrev_b32_e32 v104, 16, v155
	v_and_b32_e32 v105, 0xffff0000, v155
	v_lshlrev_b32_e32 v116, 16, v157
	v_and_b32_e32 v117, 0xffff0000, v157
	v_lshlrev_b32_e32 v156, 16, v152
	v_and_b32_e32 v157, 0xffff0000, v152
	v_lshlrev_b32_e32 v160, 16, v196
	v_and_b32_e32 v161, 0xffff0000, v196
	v_pk_add_f32 v[154:155], v[104:105], v[116:117]
; template <bool HG>
; __device__ __forceinline__ void readout_phase2(const Args& a, Frame& F, const float* gain, int nrows) {
;     ...
;     RO_FINISH(f2, b2, g2, nw + 2 * 2048); RO_LOAD(f2, b2, g2, nw + 5 * 2048);
	v_pk_add_f32 v[162:163], v[156:157], v[160:161]
	v_lshlrev_b32_e32 v152, 16, v153
	v_and_b32_e32 v153, 0xffff0000, v153
	v_lshlrev_b32_e32 v156, 16, v197
	v_and_b32_e32 v157, 0xffff0000, v197
	v_mul_f32_e32 v104, v133, v133
	v_mul_f32_e32 v116, v155, v155
	v_pk_add_f32 v[168:169], v[152:153], v[156:157]
	v_pk_add_f32 v[86:87], v[86:87], v[86:87] op_sel:[0,1] op_sel_hi:[1,0]
	v_pk_add_f32 v[92:93], v[92:93], v[92:93] op_sel:[0,1] op_sel_hi:[1,0]
	v_pk_fma_f32 v[104:105], v[132:133], v[132:133], v[104:105] op_sel_hi:[1,1,0]
	v_pk_fma_f32 v[116:117], v[154:155], v[154:155], v[116:117] op_sel_hi:[1,1,0]
	v_pk_mul_f32 v[152:153], v[162:163], v[162:163]
	v_pk_mul_f32 v[156:157], v[168:169], v[168:169]
	v_mov_b32_e32 v87, v152
	v_mov_b32_e32 v93, v153
	v_mov_b32_e32 v105, v156
	v_mov_b32_e32 v117, v157
	v_pk_add_f32 v[86:87], v[86:87], v[92:93]
	v_pk_add_f32 v[92:93], v[104:105], v[116:117]
	v_lshlrev_b32_e32 v104, 16, v192
	v_pk_add_f32 v[86:87], v[86:87], v[92:93]
	v_lshlrev_b32_e32 v92, 16, v150
	v_and_b32_e32 v93, 0xffff0000, v150
	v_and_b32_e32 v105, 0xffff0000, v192
	v_pk_add_f32 v[174:175], v[92:93], v[104:105]
	v_lshlrev_b32_e32 v92, 16, v151
	v_and_b32_e32 v93, 0xffff0000, v151
	v_lshlrev_b32_e32 v104, 16, v193
	v_and_b32_e32 v105, 0xffff0000, v193
	v_pk_add_f32 v[150:151], v[92:93], v[104:105]
	v_mov_b32_e32 v104, v175
	v_mov_b32_e32 v105, v151
	v_mov_b32_e32 v92, v174
	v_mov_b32_e32 v93, v150
	v_pk_mul_f32 v[104:105], v[104:105], v[104:105]
	s_waitcnt vmcnt(61)
	v_lshlrev_b32_e32 v116, 16, v188
	v_pk_fma_f32 v[92:93], v[92:93], v[92:93], v[104:105]
	v_lshlrev_b32_e32 v104, 16, v148
	v_and_b32_e32 v105, 0xffff0000, v148
	v_and_b32_e32 v117, 0xffff0000, v188
	v_pk_add_f32 v[178:179], v[104:105], v[116:117]
	v_lshlrev_b32_e32 v104, 16, v149
	v_and_b32_e32 v105, 0xffff0000, v149
	v_lshlrev_b32_e32 v116, 16, v189
	v_and_b32_e32 v117, 0xffff0000, v189
	v_lshlrev_b32_e32 v152, 16, v140
	v_and_b32_e32 v153, 0xffff0000, v140
	s_waitcnt vmcnt(60)
	v_lshlrev_b32_e32 v156, 16, v184
	v_and_b32_e32 v157, 0xffff0000, v184
	v_pk_add_f32 v[148:149], v[104:105], v[116:117]
	v_pk_add_f32 v[180:181], v[152:153], v[156:157]
	v_lshlrev_b32_e32 v140, 16, v141
	v_and_b32_e32 v141, 0xffff0000, v141
	v_lshlrev_b32_e32 v152, 16, v185
	v_and_b32_e32 v153, 0xffff0000, v185
	v_mul_f32_e32 v104, v179, v179
	v_mul_f32_e32 v116, v149, v149
	v_pk_add_f32 v[140:141], v[140:141], v[152:153]
	v_pk_add_f32 v[86:87], v[86:87], v[86:87] op_sel:[0,1] op_sel_hi:[1,0]
	v_pk_add_f32 v[92:93], v[92:93], v[92:93] op_sel:[0,1] op_sel_hi:[1,0]
	v_pk_fma_f32 v[104:105], v[178:179], v[178:179], v[104:105] op_sel_hi:[1,1,0]
	v_pk_fma_f32 v[116:117], v[148:149], v[148:149], v[116:117] op_sel_hi:[1,1,0]
	v_pk_mul_f32 v[152:153], v[180:181], v[180:181]
	v_pk_mul_f32 v[156:157], v[140:141], v[140:141]
	v_mov_b32_e32 v87, v152
	v_mov_b32_e32 v93, v153
	v_mov_b32_e32 v105, v156
	v_mov_b32_e32 v117, v157
	v_pk_add_f32 v[86:87], v[86:87], v[92:93]
	v_pk_add_f32 v[92:93], v[104:105], v[116:117]
	global_load_dwordx2 v[164:165], v[48:49], off offset:2048 nt
	global_load_dwordx2 v[160:161], v[48:49], off offset:2560 nt
	global_load_dwordx2 v[156:157], v[48:49], off offset:3072 nt
	global_load_dwordx2 v[152:153], v[48:49], off offset:3584 nt
	v_pk_add_f32 v[86:87], v[86:87], v[92:93]
	s_add_u32 s12, s12, 0x3000000
	v_add_f32_e32 v86, v86, v87
	s_addc_u32 s13, s13, 0
	s_nop 0
	v_add_f32_dpp v86, v86, v86 quad_perm:[1,0,3,2] row_mask:0xf bank_mask:0xf bound_ctrl:1
	s_nop 1
	v_add_f32_dpp v86, v86, v86 quad_perm:[2,3,0,1] row_mask:0xf bank_mask:0xf bound_ctrl:1
	s_nop 1
	v_add_f32_dpp v86, v86, v86 row_half_mirror row_mask:0xf bank_mask:0xf bound_ctrl:1
	s_nop 1
	v_add_f32_dpp v86, v86, v86 row_mirror row_mask:0xf bank_mask:0xf bound_ctrl:1
	s_nop 0
	v_readlane_b32 s8, v86, 16
	v_readlane_b32 s9, v86, 48
	v_readlane_b32 s6, v86, 0
	v_readlane_b32 s7, v86, 32
	v_mov_b32_e32 v86, s8
	v_mov_b32_e32 v87, s9
	v_pk_add_f32 v[86:87], s[6:7], v[86:87]
	s_nop 0
	v_add_f32_e32 v86, v86, v87
	v_fmamk_f32 v86, v86, 0x3a000000, v252
	v_mul_f32_e32 v87, 0x4f800000, v86
	v_cmp_gt_f32_e32 vcc, s55, v86
	s_nop 1
	v_cndmask_b32_e32 v86, v86, v87, vcc
	v_sqrt_f32_e32 v87, v86
	s_nop 0
	v_add_u32_e32 v48, -1, v87
	v_fma_f32 v49, -v48, v87, v86
	v_cmp_ge_f32_e64 s[8:9], 0, v49
	v_add_u32_e32 v49, 1, v87
	s_nop 0
	v_cndmask_b32_e64 v48, v87, v48, s[8:9]
	v_fma_f32 v87, -v49, v87, v86
	v_cmp_lt_f32_e64 s[8:9], 0, v87
	s_nop 1
	v_cndmask_b32_e64 v48, v48, v49, s[8:9]
	v_mul_f32_e32 v49, 0x37800000, v48
	v_cndmask_b32_e32 v48, v48, v49, vcc
	v_cmp_class_f32_e32 vcc, v86, v253
	s_nop 1
	v_cndmask_b32_e32 v48, v48, v86, vcc
	v_div_scale_f32 v49, s[6:7], v48, v48, 1.0
	v_rcp_f32_e32 v184, v49
	global_load_dwordx2 v[116:117], v[42:43], off offset:2048 nt
	global_load_dwordx2 v[104:105], v[42:43], off offset:2560 nt
	global_load_dwordx2 v[92:93], v[42:43], off offset:3072 nt
	global_load_dwordx2 v[86:87], v[42:43], off offset:3584 nt
	v_fma_f32 v42, -v49, v184, 1.0
	v_fmac_f32_e32 v184, v42, v184
	v_div_scale_f32 v42, vcc, 1.0, v48, 1.0
	v_mul_f32_e32 v43, v42, v184
	v_fma_f32 v185, -v49, v43, v42
	v_fmac_f32_e32 v43, v185, v184
	v_fma_f32 v42, -v49, v43, v42
	v_div_fmas_f32 v42, v42, v184, v43
	v_div_fixup_f32 v42, v42, v48, 1.0
	v_pk_mul_f32 v[68:69], v[68:69], v[42:43] op_sel_hi:[1,0]
	v_pk_mul_f32 v[58:59], v[58:59], v[42:43] op_sel_hi:[1,0]
	v_lshlrev_b32_e32 v184, 16, v100
	v_and_b32_e32 v185, 0xffff0000, v100
	v_lshlrev_b32_e32 v100, 16, v101
	v_and_b32_e32 v101, 0xffff0000, v101
	v_pk_mul_f32 v[58:59], v[2:3], v[58:59]
	v_pk_mul_f32 v[68:69], v[4:5], v[68:69]
	v_lshl_add_u64 v[48:49], v[34:35], 0, s[16:17]
	v_pk_mul_f32 v[68:69], v[68:69], v[100:101]
	v_pk_mul_f32 v[58:59], v[58:59], v[184:185]
	v_lshl_add_u64 v[48:49], v[48:49], 0, v[0:1]
	v_cvt_pk_bf16_f32 v58, v58, v59
	v_cvt_pk_bf16_f32 v59, v68, v69
	v_pk_mul_f32 v[64:65], v[64:65], v[42:43] op_sel_hi:[1,0]
	v_pk_mul_f32 v[52:53], v[52:53], v[42:43] op_sel_hi:[1,0]
	global_store_dwordx2 v[48:49], v[58:59], off
	v_lshlrev_b32_e32 v58, 16, v90
	v_and_b32_e32 v59, 0xffff0000, v90
	v_lshlrev_b32_e32 v68, 16, v91
	v_and_b32_e32 v69, 0xffff0000, v91
	v_pk_mul_f32 v[52:53], v[6:7], v[52:53]
	v_pk_mul_f32 v[64:65], v[8:9], v[64:65]
	v_pk_mul_f32 v[52:53], v[52:53], v[58:59]
	v_pk_mul_f32 v[64:65], v[64:65], v[68:69]
	v_cvt_pk_bf16_f32 v52, v52, v53
	v_cvt_pk_bf16_f32 v53, v64, v65
	v_pk_mul_f32 v[64:65], v[158:159], v[42:43] op_sel_hi:[1,0]
	v_pk_mul_f32 v[68:69], v[124:125], v[42:43] op_sel_hi:[1,0]
	global_store_dwordx2 v[48:49], v[52:53], off offset:512
	v_lshlrev_b32_e32 v52, 16, v80
	v_and_b32_e32 v53, 0xffff0000, v80
	v_lshlrev_b32_e32 v58, 16, v81
	v_and_b32_e32 v59, 0xffff0000, v81
	v_pk_mul_f32 v[68:69], v[10:11], v[68:69]
	v_pk_mul_f32 v[64:65], v[12:13], v[64:65]
	v_pk_mul_f32 v[52:53], v[68:69], v[52:53]
	v_pk_mul_f32 v[58:59], v[64:65], v[58:59]
	v_cvt_pk_bf16_f32 v52, v52, v53
	v_cvt_pk_bf16_f32 v53, v58, v59
	v_pk_mul_f32 v[64:65], v[154:155], v[42:43] op_sel_hi:[1,0]
	v_pk_mul_f32 v[68:69], v[132:133], v[42:43] op_sel_hi:[1,0]
	global_store_dwordx2 v[48:49], v[52:53], off offset:1024
	v_lshlrev_b32_e32 v52, 16, v76
	v_and_b32_e32 v53, 0xffff0000, v76
	v_lshlrev_b32_e32 v58, 16, v77
	v_and_b32_e32 v59, 0xffff0000, v77
	v_pk_mul_f32 v[68:69], v[14:15], v[68:69]
	v_pk_mul_f32 v[64:65], v[16:17], v[64:65]
	v_pk_mul_f32 v[52:53], v[68:69], v[52:53]
	v_pk_mul_f32 v[58:59], v[64:65], v[58:59]
	v_pk_mul_f32 v[64:65], v[168:169], v[42:43] op_sel_hi:[1,0]
	v_cvt_pk_bf16_f32 v52, v52, v53
	v_cvt_pk_bf16_f32 v53, v58, v59
	s_waitcnt vmcnt(62)
	v_lshlrev_b32_e32 v58, 16, v127
	v_and_b32_e32 v59, 0xffff0000, v127
	v_pk_mul_f32 v[68:69], v[162:163], v[42:43] op_sel_hi:[1,0]
	v_pk_mul_f32 v[64:65], v[20:21], v[64:65]
	global_store_dwordx2 v[48:49], v[52:53], off offset:1536
	v_lshlrev_b32_e32 v52, 16, v126
	v_and_b32_e32 v53, 0xffff0000, v126
	v_pk_mul_f32 v[68:69], v[18:19], v[68:69]
	v_pk_mul_f32 v[58:59], v[64:65], v[58:59]
	v_pk_mul_f32 v[64:65], v[150:151], v[42:43] op_sel_hi:[1,0]
	s_waitcnt vmcnt(59)
	v_lshlrev_b32_e32 v150, 16, v170
	v_and_b32_e32 v151, 0xffff0000, v170
	s_waitcnt vmcnt(55)
	v_lshlrev_b32_e32 v154, 16, v176
	v_and_b32_e32 v155, 0xffff0000, v176
	v_pk_mul_f32 v[52:53], v[68:69], v[52:53]
	v_pk_mul_f32 v[68:69], v[174:175], v[42:43] op_sel_hi:[1,0]
	v_pk_add_f32 v[174:175], v[150:151], v[154:155]
	v_lshlrev_b32_e32 v150, 16, v171
	v_and_b32_e32 v151, 0xffff0000, v171
	v_lshlrev_b32_e32 v154, 16, v177
	v_and_b32_e32 v155, 0xffff0000, v177
	v_pk_add_f32 v[170:171], v[150:151], v[154:155]
	v_lshlrev_b32_e32 v150, 16, v144
	v_and_b32_e32 v151, 0xffff0000, v144
	s_waitcnt vmcnt(54)
	v_lshlrev_b32_e32 v154, 16, v146
	v_and_b32_e32 v155, 0xffff0000, v146
	v_pk_add_f32 v[168:169], v[150:151], v[154:155]
	v_lshlrev_b32_e32 v144, 16, v145
	v_and_b32_e32 v145, 0xffff0000, v145
	v_lshlrev_b32_e32 v146, 16, v147
	v_and_b32_e32 v147, 0xffff0000, v147
	v_pk_add_f32 v[144:145], v[144:145], v[146:147]
	v_mov_b32_e32 v150, v175
	v_mov_b32_e32 v151, v169
	v_mov_b32_e32 v146, v174
	v_mov_b32_e32 v147, v168
	v_pk_mul_f32 v[150:151], v[150:151], v[150:151]
	v_mov_b32_e32 v154, v171
	v_mov_b32_e32 v155, v145
	v_pk_fma_f32 v[146:147], v[146:147], v[146:147], v[150:151]
	v_mov_b32_e32 v150, v170
	v_mov_b32_e32 v151, v144
	v_pk_mul_f32 v[154:155], v[154:155], v[154:155]
	v_cvt_pk_bf16_f32 v52, v52, v53
	v_pk_fma_f32 v[150:151], v[150:151], v[150:151], v[154:155]
	s_waitcnt vmcnt(53)
	v_lshlrev_b32_e32 v154, 16, v142
	v_pk_add_f32 v[146:147], v[146:147], v[150:151]
	v_and_b32_e32 v155, 0xffff0000, v142
	v_pk_add_f32 v[150:151], v[146:147], v[146:147] op_sel:[0,1] op_sel_hi:[1,0]
	v_lshlrev_b32_e32 v146, 16, v138
	v_and_b32_e32 v147, 0xffff0000, v138
	v_lshlrev_b32_e32 v138, 16, v139
	v_and_b32_e32 v139, 0xffff0000, v139
	v_lshlrev_b32_e32 v142, 16, v143
	v_and_b32_e32 v143, 0xffff0000, v143
	v_pk_add_f32 v[146:147], v[146:147], v[154:155]
	v_pk_add_f32 v[142:143], v[138:139], v[142:143]
	v_mov_b32_e32 v154, v147
	v_mov_b32_e32 v155, v143
	v_mov_b32_e32 v138, v146
	v_mov_b32_e32 v139, v142
	v_pk_mul_f32 v[154:155], v[154:155], v[154:155]
	v_cvt_pk_bf16_f32 v53, v58, v59
	v_pk_fma_f32 v[138:139], v[138:139], v[138:139], v[154:155]
	s_waitcnt vmcnt(52)
	v_lshlrev_b32_e32 v158, 16, v120
	v_pk_add_f32 v[154:155], v[138:139], v[138:139] op_sel:[0,1] op_sel_hi:[1,0]
	v_lshlrev_b32_e32 v138, 16, v118
	v_and_b32_e32 v139, 0xffff0000, v118
	v_and_b32_e32 v159, 0xffff0000, v120
	v_lshlrev_b32_e32 v118, 16, v119
	v_and_b32_e32 v119, 0xffff0000, v119
	v_lshlrev_b32_e32 v120, 16, v121
	v_and_b32_e32 v121, 0xffff0000, v121
	s_waitcnt vmcnt(47)
	v_lshlrev_b32_e32 v162, 16, v106
	v_and_b32_e32 v163, 0xffff0000, v106
	s_waitcnt vmcnt(43)
	v_lshlrev_b32_e32 v176, 16, v198
	v_and_b32_e32 v177, 0xffff0000, v198
	global_store_dwordx2 v[48:49], v[52:53], off offset:2048
	v_lshlrev_b32_e32 v52, 16, v108
	v_and_b32_e32 v53, 0xffff0000, v108
	v_pk_mul_f32 v[68:69], v[22:23], v[68:69]
	v_pk_add_f32 v[138:139], v[138:139], v[158:159]
	v_pk_add_f32 v[118:119], v[118:119], v[120:121]
	v_pk_add_f32 v[176:177], v[162:163], v[176:177]
	v_lshlrev_b32_e32 v106, 16, v107
	v_and_b32_e32 v107, 0xffff0000, v107
	v_lshlrev_b32_e32 v162, 16, v199
	v_and_b32_e32 v163, 0xffff0000, v199
	v_pk_mul_f32 v[52:53], v[68:69], v[52:53]
	v_pk_mul_f32 v[68:69], v[178:179], v[42:43] op_sel_hi:[1,0]
	v_mul_f32_e32 v120, v139, v139
	v_mul_f32_e32 v158, v119, v119
	v_pk_add_f32 v[178:179], v[106:107], v[162:163]
	v_pk_fma_f32 v[120:121], v[138:139], v[138:139], v[120:121] op_sel_hi:[1,1,0]
	v_pk_fma_f32 v[158:159], v[118:119], v[118:119], v[158:159] op_sel_hi:[1,1,0]
	v_pk_mul_f32 v[106:107], v[176:177], v[176:177]
	v_pk_mul_f32 v[162:163], v[178:179], v[178:179]
	v_mov_b32_e32 v151, v106
	v_mov_b32_e32 v155, v107
	v_mov_b32_e32 v121, v162
	v_mov_b32_e32 v159, v163
	v_lshlrev_b32_e32 v58, 16, v109
	v_and_b32_e32 v59, 0xffff0000, v109
	v_pk_mul_f32 v[64:65], v[24:25], v[64:65]
	v_pk_add_f32 v[106:107], v[150:151], v[154:155]
	v_pk_add_f32 v[120:121], v[120:121], v[158:159]
	v_pk_mul_f32 v[58:59], v[64:65], v[58:59]
	v_pk_mul_f32 v[64:65], v[148:149], v[42:43] op_sel_hi:[1,0]
	v_pk_add_f32 v[106:107], v[106:107], v[120:121]
	v_lshlrev_b32_e32 v120, 16, v96
	v_and_b32_e32 v121, 0xffff0000, v96
	s_waitcnt vmcnt(43)
	v_lshlrev_b32_e32 v150, 16, v194
	v_and_b32_e32 v151, 0xffff0000, v194
	v_cvt_pk_bf16_f32 v52, v52, v53
	v_cvt_pk_bf16_f32 v53, v58, v59
	v_lshlrev_b32_e32 v58, 16, v99
	v_and_b32_e32 v59, 0xffff0000, v99
	v_pk_mul_f32 v[64:65], v[28:29], v[64:65]
	v_pk_add_f32 v[120:121], v[120:121], v[150:151]
	v_lshlrev_b32_e32 v96, 16, v97
	v_and_b32_e32 v97, 0xffff0000, v97
	v_lshlrev_b32_e32 v150, 16, v195
	v_and_b32_e32 v151, 0xffff0000, v195
	v_pk_mul_f32 v[58:59], v[64:65], v[58:59]
	v_pk_mul_f32 v[64:65], v[140:141], v[42:43] op_sel_hi:[1,0]
	v_pk_mul_f32 v[42:43], v[180:181], v[42:43] op_sel_hi:[1,0]
	v_pk_add_f32 v[180:181], v[96:97], v[150:151]
	v_mov_b32_e32 v150, v121
	v_mov_b32_e32 v151, v181
	v_mov_b32_e32 v96, v120
	v_mov_b32_e32 v97, v180
	v_pk_mul_f32 v[150:151], v[150:151], v[150:151]
	s_waitcnt vmcnt(42)
	v_lshlrev_b32_e32 v154, 16, v190
	v_pk_fma_f32 v[96:97], v[96:97], v[96:97], v[150:151]
	v_lshlrev_b32_e32 v150, 16, v82
	v_and_b32_e32 v151, 0xffff0000, v82
	v_and_b32_e32 v155, 0xffff0000, v190
	v_pk_add_f32 v[184:185], v[150:151], v[154:155]
	v_lshlrev_b32_e32 v82, 16, v83
	v_and_b32_e32 v83, 0xffff0000, v83
	v_lshlrev_b32_e32 v150, 16, v191
	v_and_b32_e32 v151, 0xffff0000, v191
	v_lshlrev_b32_e32 v154, 16, v72
	v_and_b32_e32 v155, 0xffff0000, v72
	s_waitcnt vmcnt(41)
	v_lshlrev_b32_e32 v158, 16, v186
	v_and_b32_e32 v159, 0xffff0000, v186
	v_pk_add_f32 v[188:189], v[82:83], v[150:151]
	v_pk_add_f32 v[190:191], v[154:155], v[158:159]
	v_lshlrev_b32_e32 v72, 16, v73
	v_and_b32_e32 v73, 0xffff0000, v73
	v_lshlrev_b32_e32 v154, 16, v187
	v_and_b32_e32 v155, 0xffff0000, v187
	v_mul_f32_e32 v82, v185, v185
	v_mul_f32_e32 v150, v189, v189
	v_pk_add_f32 v[186:187], v[72:73], v[154:155]
	v_pk_add_f32 v[106:107], v[106:107], v[106:107] op_sel:[0,1] op_sel_hi:[1,0]
	v_pk_add_f32 v[96:97], v[96:97], v[96:97] op_sel:[0,1] op_sel_hi:[1,0]
	v_pk_fma_f32 v[82:83], v[184:185], v[184:185], v[82:83] op_sel_hi:[1,1,0]
	v_pk_fma_f32 v[150:151], v[188:189], v[188:189], v[150:151] op_sel_hi:[1,1,0]
	v_pk_mul_f32 v[72:73], v[190:191], v[190:191]
	v_pk_mul_f32 v[154:155], v[186:187], v[186:187]
	v_mov_b32_e32 v107, v72
	v_mov_b32_e32 v97, v73
	v_mov_b32_e32 v83, v154
	v_mov_b32_e32 v151, v155
	v_pk_add_f32 v[72:73], v[106:107], v[96:97]
	v_pk_add_f32 v[82:83], v[82:83], v[150:151]
	global_store_dwordx2 v[48:49], v[52:53], off offset:2560
	v_pk_add_f32 v[72:73], v[72:73], v[82:83]
	v_lshlrev_b32_e32 v52, 16, v98
	v_add_f32_e32 v72, v72, v73
	v_and_b32_e32 v53, 0xffff0000, v98
	v_pk_mul_f32 v[68:69], v[26:27], v[68:69]
	v_add_f32_dpp v72, v72, v72 quad_perm:[1,0,3,2] row_mask:0xf bank_mask:0xf bound_ctrl:1
	v_pk_mul_f32 v[52:53], v[68:69], v[52:53]
	v_pk_mul_f32 v[42:43], v[30:31], v[42:43]
	v_add_f32_dpp v72, v72, v72 quad_perm:[2,3,0,1] row_mask:0xf bank_mask:0xf bound_ctrl:1
	v_cvt_pk_bf16_f32 v52, v52, v53
	v_cvt_pk_bf16_f32 v53, v58, v59
	v_add_f32_dpp v72, v72, v72 row_half_mirror row_mask:0xf bank_mask:0xf bound_ctrl:1
	global_store_dwordx2 v[48:49], v[52:53], off offset:3072
	v_lshlrev_b32_e32 v52, 16, v74
	v_add_f32_dpp v72, v72, v72 row_mirror row_mask:0xf bank_mask:0xf bound_ctrl:1
	v_and_b32_e32 v53, 0xffff0000, v74
	v_readlane_b32 s8, v72, 16
	v_readlane_b32 s9, v72, 48
	v_readlane_b32 s6, v72, 0
	v_readlane_b32 s7, v72, 32
	v_mov_b32_e32 v72, s8
	v_mov_b32_e32 v73, s9
	v_pk_add_f32 v[72:73], s[6:7], v[72:73]
	v_lshlrev_b32_e32 v58, 16, v75
	v_add_f32_e32 v72, v72, v73
	v_fmamk_f32 v72, v72, 0x3a000000, v252
	v_and_b32_e32 v59, 0xffff0000, v75
	v_pk_mul_f32 v[64:65], v[32:33], v[64:65]
	v_mul_f32_e32 v73, 0x4f800000, v72
	v_cmp_gt_f32_e32 vcc, s55, v72
	v_pk_mul_f32 v[58:59], v[64:65], v[58:59]
	v_pk_mul_f32 v[42:43], v[42:43], v[52:53]
	v_cndmask_b32_e32 v72, v72, v73, vcc
	v_cvt_pk_bf16_f32 v42, v42, v43
	v_cvt_pk_bf16_f32 v43, v58, v59
	v_sqrt_f32_e32 v73, v72
	global_store_dwordx2 v[48:49], v[42:43], off offset:3584
	v_lshl_add_u64 v[42:43], v[36:37], 0, s[12:13]
	v_lshl_add_u64 v[68:69], v[42:43], 0, v[0:1]
	v_lshl_add_u64 v[42:43], v[38:39], 0, s[12:13]
	v_lshl_add_u64 v[80:81], v[42:43], 0, v[0:1]
; template <bool HG>
; __device__ __forceinline__ void readout_phase2(const Args& a, Frame& F, const float* gain, int nrows) {
;     ...
;     RO_FINISH(f0, b0, g0, nw + 3 * 2048); RO_LOAD(f0, b0, g0, nw + 6 * 2048);
	v_lshl_add_u64 v[42:43], v[40:41], 0, s[12:13]
	v_lshl_add_u64 v[64:65], v[42:43], 0, v[0:1]
	global_load_dwordx2 v[140:141], v[68:69], off nt
	global_load_dwordx2 v[126:127], v[68:69], off offset:512 nt
	global_load_dwordx2 v[108:109], v[68:69], off offset:1024 nt
	global_load_dwordx2 v[98:99], v[68:69], off offset:1536 nt
	global_load_dwordx2 v[148:149], v[80:81], off nt
	global_load_dwordx2 v[132:133], v[80:81], off offset:512 nt
	global_load_dwordx2 v[124:125], v[80:81], off offset:1024 nt
	global_load_dwordx2 v[100:101], v[80:81], off offset:1536 nt
	global_load_dwordx2 v[58:59], v[64:65], off nt
	global_load_dwordx2 v[52:53], v[64:65], off offset:512 nt
	global_load_dwordx2 v[48:49], v[64:65], off offset:1024 nt
	global_load_dwordx2 v[42:43], v[64:65], off offset:1536 nt
	global_load_dwordx2 v[90:91], v[68:69], off offset:2048 nt
	global_load_dwordx2 v[76:77], v[68:69], off offset:2560 nt
	global_load_dwordx2 v[74:75], v[68:69], off offset:3072 nt
	s_nop 0
	global_load_dwordx2 v[68:69], v[68:69], off offset:3584 nt
	s_nop 0
	global_load_dwordx2 v[162:163], v[80:81], off offset:2048 nt
	global_load_dwordx2 v[158:159], v[80:81], off offset:2560 nt
	global_load_dwordx2 v[154:155], v[80:81], off offset:3072 nt
	global_load_dwordx2 v[150:151], v[80:81], off offset:3584 nt
	v_add_u32_e32 v80, -1, v73
	v_fma_f32 v81, -v80, v73, v72
	v_cmp_ge_f32_e64 s[8:9], 0, v81
	v_add_u32_e32 v81, 1, v73
	s_nop 0
	v_cndmask_b32_e64 v80, v73, v80, s[8:9]
	v_fma_f32 v73, -v81, v73, v72
	v_cmp_lt_f32_e64 s[8:9], 0, v73
	s_nop 1
	v_cndmask_b32_e64 v73, v80, v81, s[8:9]
	v_mul_f32_e32 v80, 0x37800000, v73
	v_cndmask_b32_e32 v73, v73, v80, vcc
	v_cmp_class_f32_e32 vcc, v72, v253
	s_nop 1
	v_cndmask_b32_e32 v80, v73, v72, vcc
	v_div_scale_f32 v81, s[6:7], v80, v80, 1.0
	v_rcp_f32_e32 v192, v81
	global_load_dwordx2 v[106:107], v[64:65], off offset:2048 nt
	global_load_dwordx2 v[96:97], v[64:65], off offset:2560 nt
	global_load_dwordx2 v[82:83], v[64:65], off offset:3072 nt
	global_load_dwordx2 v[72:73], v[64:65], off offset:3584 nt
	v_fma_f32 v64, -v81, v192, 1.0
	v_fmac_f32_e32 v192, v64, v192
	v_div_scale_f32 v64, vcc, 1.0, v80, 1.0
	v_mul_f32_e32 v65, v64, v192
	v_fma_f32 v193, -v81, v65, v64
	v_fmac_f32_e32 v65, v193, v192
	v_fma_f32 v64, -v81, v65, v64
	v_div_fmas_f32 v64, v64, v192, v65
	v_div_fixup_f32 v64, v64, v80, 1.0
	v_pk_mul_f32 v[170:171], v[170:171], v[64:65] op_sel_hi:[1,0]
	v_pk_mul_f32 v[174:175], v[174:175], v[64:65] op_sel_hi:[1,0]
	v_lshlrev_b32_e32 v192, 16, v66
	v_and_b32_e32 v193, 0xffff0000, v66
	v_lshlrev_b32_e32 v66, 16, v67
	v_and_b32_e32 v67, 0xffff0000, v67
	v_pk_mul_f32 v[174:175], v[2:3], v[174:175]
	v_pk_mul_f32 v[170:171], v[4:5], v[170:171]
	v_pk_mul_f32 v[144:145], v[144:145], v[64:65] op_sel_hi:[1,0]
	v_pk_mul_f32 v[66:67], v[170:171], v[66:67]
	v_pk_mul_f32 v[170:171], v[174:175], v[192:193]
	v_pk_mul_f32 v[168:169], v[168:169], v[64:65] op_sel_hi:[1,0]
	v_cvt_pk_bf16_f32 v170, v170, v171
	v_cvt_pk_bf16_f32 v171, v66, v67
	v_lshlrev_b32_e32 v66, 16, v60
	v_and_b32_e32 v67, 0xffff0000, v60
	v_lshlrev_b32_e32 v60, 16, v61
	v_and_b32_e32 v61, 0xffff0000, v61
	v_pk_mul_f32 v[168:169], v[6:7], v[168:169]
	v_pk_mul_f32 v[144:145], v[8:9], v[144:145]
	v_lshl_add_u64 v[80:81], v[34:35], 0, s[18:19]
	v_pk_mul_f32 v[60:61], v[144:145], v[60:61]
	v_pk_mul_f32 v[66:67], v[168:169], v[66:67]
	v_lshl_add_u64 v[80:81], v[80:81], 0, v[0:1]
	v_cvt_pk_bf16_f32 v66, v66, v67
	v_cvt_pk_bf16_f32 v67, v60, v61
	global_store_dwordx2 v[80:81], v[66:67], off offset:512
	v_pk_mul_f32 v[66:67], v[142:143], v[64:65] op_sel_hi:[1,0]
	v_pk_mul_f32 v[142:143], v[146:147], v[64:65] op_sel_hi:[1,0]
	v_lshlrev_b32_e32 v60, 16, v54
	v_and_b32_e32 v61, 0xffff0000, v54
	v_lshlrev_b32_e32 v54, 16, v55
	v_and_b32_e32 v55, 0xffff0000, v55
	v_pk_mul_f32 v[142:143], v[10:11], v[142:143]
	v_pk_mul_f32 v[66:67], v[12:13], v[66:67]
	v_pk_mul_f32 v[60:61], v[142:143], v[60:61]
	v_pk_mul_f32 v[54:55], v[66:67], v[54:55]
	v_pk_mul_f32 v[66:67], v[138:139], v[64:65] op_sel_hi:[1,0]
	v_cvt_pk_bf16_f32 v60, v60, v61
	v_cvt_pk_bf16_f32 v61, v54, v55
	v_lshlrev_b32_e32 v54, 16, v46
	v_and_b32_e32 v55, 0xffff0000, v46
	v_pk_mul_f32 v[66:67], v[14:15], v[66:67]
	s_waitcnt vmcnt(56)
	v_lshlrev_b32_e32 v174, 16, v166
	v_pk_mul_f32 v[54:55], v[66:67], v[54:55]
	v_pk_mul_f32 v[66:67], v[176:177], v[64:65] op_sel_hi:[1,0]
	v_and_b32_e32 v175, 0xffff0000, v166
	s_waitcnt vmcnt(52)
	v_lshlrev_b32_e32 v176, 16, v172
	v_and_b32_e32 v177, 0xffff0000, v172
	v_lshlrev_b32_e32 v166, 16, v167
	v_and_b32_e32 v167, 0xffff0000, v167
	v_lshlrev_b32_e32 v172, 16, v173
	v_and_b32_e32 v173, 0xffff0000, v173
	v_pk_add_f32 v[174:175], v[174:175], v[176:177]
	v_pk_add_f32 v[172:173], v[166:167], v[172:173]
	v_lshlrev_b32_e32 v166, 16, v134
	v_and_b32_e32 v167, 0xffff0000, v134
	s_waitcnt vmcnt(51)
	v_lshlrev_b32_e32 v176, 16, v136
	v_and_b32_e32 v177, 0xffff0000, v136
	global_store_dwordx2 v[80:81], v[60:61], off offset:1024
	v_pk_mul_f32 v[60:61], v[118:119], v[64:65] op_sel_hi:[1,0]
	v_pk_add_f32 v[166:167], v[166:167], v[176:177]
	v_lshlrev_b32_e32 v134, 16, v135
	v_and_b32_e32 v135, 0xffff0000, v135
	v_lshlrev_b32_e32 v136, 16, v137
	v_and_b32_e32 v137, 0xffff0000, v137
	v_lshlrev_b32_e32 v46, 16, v47
	v_and_b32_e32 v47, 0xffff0000, v47
	v_pk_mul_f32 v[60:61], v[16:17], v[60:61]
	v_pk_add_f32 v[134:135], v[134:135], v[136:137]
	v_mov_b32_e32 v176, v175
	v_mov_b32_e32 v177, v167
	v_pk_mul_f32 v[46:47], v[60:61], v[46:47]
	v_pk_mul_f32 v[60:61], v[178:179], v[64:65] op_sel_hi:[1,0]
	v_mov_b32_e32 v136, v174
	v_mov_b32_e32 v137, v166
	v_pk_mul_f32 v[176:177], v[176:177], v[176:177]
	v_mov_b32_e32 v178, v173
	v_mov_b32_e32 v179, v135
	v_pk_fma_f32 v[136:137], v[136:137], v[136:137], v[176:177]
	v_mov_b32_e32 v176, v172
	v_mov_b32_e32 v177, v134
	v_pk_mul_f32 v[178:179], v[178:179], v[178:179]
	v_cvt_pk_bf16_f32 v54, v54, v55
	v_cvt_pk_bf16_f32 v55, v46, v47
	v_pk_fma_f32 v[176:177], v[176:177], v[176:177], v[178:179]
	global_store_dwordx2 v[80:81], v[54:55], off offset:1536
	v_lshlrev_b32_e32 v46, 16, v122
	v_and_b32_e32 v47, 0xffff0000, v122
	v_lshlrev_b32_e32 v54, 16, v123
	v_and_b32_e32 v55, 0xffff0000, v123
	v_pk_mul_f32 v[66:67], v[18:19], v[66:67]
	v_pk_mul_f32 v[60:61], v[20:21], v[60:61]
	v_pk_add_f32 v[136:137], v[136:137], v[176:177]
	v_lshlrev_b32_e32 v176, 16, v128
	v_and_b32_e32 v177, 0xffff0000, v128
	s_waitcnt vmcnt(52)
	v_lshlrev_b32_e32 v178, 16, v130
	v_and_b32_e32 v179, 0xffff0000, v130
	v_lshlrev_b32_e32 v128, 16, v129
	v_and_b32_e32 v129, 0xffff0000, v129
	v_lshlrev_b32_e32 v130, 16, v131
	v_and_b32_e32 v131, 0xffff0000, v131
	v_pk_mul_f32 v[54:55], v[60:61], v[54:55]
	v_pk_mul_f32 v[46:47], v[66:67], v[46:47]
	v_pk_add_f32 v[176:177], v[176:177], v[178:179]
	v_pk_add_f32 v[130:131], v[128:129], v[130:131]
	v_cvt_pk_bf16_f32 v46, v46, v47
	v_cvt_pk_bf16_f32 v47, v54, v55
	v_pk_mul_f32 v[60:61], v[180:181], v[64:65] op_sel_hi:[1,0]
	v_pk_mul_f32 v[66:67], v[120:121], v[64:65] op_sel_hi:[1,0]
	v_mov_b32_e32 v178, v177
	v_mov_b32_e32 v179, v131
	global_store_dwordx2 v[80:81], v[46:47], off offset:2048
	v_lshlrev_b32_e32 v46, 16, v110
	v_and_b32_e32 v47, 0xffff0000, v110
	v_lshlrev_b32_e32 v54, 16, v111
	v_and_b32_e32 v55, 0xffff0000, v111
	v_pk_mul_f32 v[66:67], v[22:23], v[66:67]
	v_pk_mul_f32 v[60:61], v[24:25], v[60:61]
	v_mov_b32_e32 v128, v176
	v_mov_b32_e32 v129, v130
	v_pk_mul_f32 v[178:179], v[178:179], v[178:179]
	v_pk_mul_f32 v[54:55], v[60:61], v[54:55]
	v_pk_mul_f32 v[46:47], v[66:67], v[46:47]
	v_pk_mul_f32 v[60:61], v[188:189], v[64:65] op_sel_hi:[1,0]
	v_pk_fma_f32 v[128:129], v[128:129], v[128:129], v[178:179]
	v_cvt_pk_bf16_f32 v46, v46, v47
	v_cvt_pk_bf16_f32 v47, v54, v55
	v_lshlrev_b32_e32 v54, 16, v95
	v_and_b32_e32 v55, 0xffff0000, v95
	v_pk_mul_f32 v[60:61], v[28:29], v[60:61]
	v_pk_add_f32 v[178:179], v[128:129], v[128:129] op_sel:[0,1] op_sel_hi:[1,0]
	v_lshlrev_b32_e32 v128, 16, v112
	v_and_b32_e32 v129, 0xffff0000, v112
	s_waitcnt vmcnt(52)
	v_lshlrev_b32_e32 v180, 16, v114
	v_and_b32_e32 v181, 0xffff0000, v114
	v_lshlrev_b32_e32 v112, 16, v113
	v_and_b32_e32 v113, 0xffff0000, v113
	v_lshlrev_b32_e32 v114, 16, v115
	v_and_b32_e32 v115, 0xffff0000, v115
	v_pk_mul_f32 v[66:67], v[184:185], v[64:65] op_sel_hi:[1,0]
	v_pk_mul_f32 v[54:55], v[60:61], v[54:55]
	v_pk_mul_f32 v[60:61], v[186:187], v[64:65] op_sel_hi:[1,0]
	v_pk_add_f32 v[128:129], v[128:129], v[180:181]
	v_pk_add_f32 v[112:113], v[112:113], v[114:115]
	s_waitcnt vmcnt(47)
	v_lshlrev_b32_e32 v184, 16, v102
	v_and_b32_e32 v185, 0xffff0000, v102
	s_waitcnt vmcnt(43)
	v_lshlrev_b32_e32 v186, 16, v164
	v_and_b32_e32 v187, 0xffff0000, v164
	v_lshlrev_b32_e32 v102, 16, v103
	v_and_b32_e32 v103, 0xffff0000, v103
	v_lshlrev_b32_e32 v164, 16, v165
	v_and_b32_e32 v165, 0xffff0000, v165
	v_mul_f32_e32 v114, v129, v129
	v_mul_f32_e32 v180, v113, v113
	v_pk_add_f32 v[184:185], v[184:185], v[186:187]
	v_pk_add_f32 v[164:165], v[102:103], v[164:165]
	v_pk_add_f32 v[136:137], v[136:137], v[136:137] op_sel:[0,1] op_sel_hi:[1,0]
	v_pk_fma_f32 v[114:115], v[128:129], v[128:129], v[114:115] op_sel_hi:[1,1,0]
	v_pk_fma_f32 v[180:181], v[112:113], v[112:113], v[180:181] op_sel_hi:[1,1,0]
	v_pk_mul_f32 v[102:103], v[184:185], v[184:185]
	v_pk_mul_f32 v[186:187], v[164:165], v[164:165]
	v_mov_b32_e32 v137, v102
	v_mov_b32_e32 v179, v103
	v_mov_b32_e32 v115, v186
	v_mov_b32_e32 v181, v187
	v_pk_add_f32 v[102:103], v[136:137], v[178:179]
	v_pk_add_f32 v[114:115], v[114:115], v[180:181]
	s_waitcnt vmcnt(42)
	v_lshlrev_b32_e32 v136, 16, v160
	v_pk_add_f32 v[102:103], v[102:103], v[114:115]
	v_lshlrev_b32_e32 v114, 16, v84
	v_and_b32_e32 v115, 0xffff0000, v84
	v_and_b32_e32 v137, 0xffff0000, v160
	v_pk_add_f32 v[114:115], v[114:115], v[136:137]
	v_lshlrev_b32_e32 v84, 16, v85
	v_and_b32_e32 v85, 0xffff0000, v85
	v_lshlrev_b32_e32 v136, 16, v161
	v_and_b32_e32 v137, 0xffff0000, v161
	v_pk_add_f32 v[178:179], v[84:85], v[136:137]
	v_mov_b32_e32 v136, v115
	v_mov_b32_e32 v137, v179
	v_mov_b32_e32 v84, v114
	v_mov_b32_e32 v85, v178
	v_pk_mul_f32 v[136:137], v[136:137], v[136:137]
	s_waitcnt vmcnt(41)
	v_lshlrev_b32_e32 v160, 16, v156
	v_pk_fma_f32 v[84:85], v[84:85], v[84:85], v[136:137]
	v_lshlrev_b32_e32 v136, 16, v78
	v_and_b32_e32 v137, 0xffff0000, v78
	v_and_b32_e32 v161, 0xffff0000, v156
	v_pk_add_f32 v[180:181], v[136:137], v[160:161]
	v_lshlrev_b32_e32 v78, 16, v79
	v_and_b32_e32 v79, 0xffff0000, v79
	v_lshlrev_b32_e32 v136, 16, v157
	v_and_b32_e32 v137, 0xffff0000, v157
	v_pk_add_f32 v[186:187], v[78:79], v[136:137]
	v_lshlrev_b32_e32 v156, 16, v70
	v_and_b32_e32 v157, 0xffff0000, v70
	s_waitcnt vmcnt(40)
; template <bool HG>
; __device__ __forceinline__ void readout_phase2(const Args& a, Frame& F, const float* gain, int nrows) {
;     ...
;     RO_FINISH(f1, b1, g1, nw + 4 * 2048); RO_LOAD(f1, b1, g1, nw + 7 * 2048);
	v_lshlrev_b32_e32 v160, 16, v152
	v_and_b32_e32 v161, 0xffff0000, v152
	v_lshlrev_b32_e32 v70, 16, v71
	v_and_b32_e32 v71, 0xffff0000, v71
	v_lshlrev_b32_e32 v152, 16, v153
	v_and_b32_e32 v153, 0xffff0000, v153
	v_pk_mul_f32 v[64:65], v[190:191], v[64:65] op_sel_hi:[1,0]
	v_mul_f32_e32 v78, v181, v181
	v_mul_f32_e32 v136, v187, v187
	v_pk_add_f32 v[188:189], v[156:157], v[160:161]
	v_pk_add_f32 v[190:191], v[70:71], v[152:153]
	v_pk_add_f32 v[102:103], v[102:103], v[102:103] op_sel:[0,1] op_sel_hi:[1,0]
	v_pk_add_f32 v[84:85], v[84:85], v[84:85] op_sel:[0,1] op_sel_hi:[1,0]
	v_pk_fma_f32 v[78:79], v[180:181], v[180:181], v[78:79] op_sel_hi:[1,1,0]
	v_pk_fma_f32 v[136:137], v[186:187], v[186:187], v[136:137] op_sel_hi:[1,1,0]
	v_pk_mul_f32 v[70:71], v[188:189], v[188:189]
	v_pk_mul_f32 v[152:153], v[190:191], v[190:191]
	v_mov_b32_e32 v103, v70
	v_mov_b32_e32 v85, v71
	v_mov_b32_e32 v79, v152
	v_mov_b32_e32 v137, v153
	v_pk_add_f32 v[70:71], v[102:103], v[84:85]
	v_pk_add_f32 v[78:79], v[78:79], v[136:137]
	global_store_dwordx2 v[80:81], v[46:47], off offset:2560
	v_pk_add_f32 v[70:71], v[70:71], v[78:79]
	v_lshlrev_b32_e32 v46, 16, v94
	v_add_f32_e32 v70, v70, v71
	v_and_b32_e32 v47, 0xffff0000, v94
	v_pk_mul_f32 v[66:67], v[26:27], v[66:67]
	v_add_f32_dpp v70, v70, v70 quad_perm:[1,0,3,2] row_mask:0xf bank_mask:0xf bound_ctrl:1
	v_pk_mul_f32 v[46:47], v[66:67], v[46:47]
	v_pk_mul_f32 v[64:65], v[30:31], v[64:65]
	v_add_f32_dpp v70, v70, v70 quad_perm:[2,3,0,1] row_mask:0xf bank_mask:0xf bound_ctrl:1
	v_cvt_pk_bf16_f32 v46, v46, v47
	v_cvt_pk_bf16_f32 v47, v54, v55
	v_add_f32_dpp v70, v70, v70 row_half_mirror row_mask:0xf bank_mask:0xf bound_ctrl:1
	global_store_dwordx2 v[80:81], v[46:47], off offset:3072
	v_lshlrev_b32_e32 v46, 16, v88
	v_add_f32_dpp v70, v70, v70 row_mirror row_mask:0xf bank_mask:0xf bound_ctrl:1
	v_and_b32_e32 v47, 0xffff0000, v88
	v_readlane_b32 s8, v70, 16
	v_readlane_b32 s9, v70, 48
	v_readlane_b32 s6, v70, 0
	v_readlane_b32 s7, v70, 32
	v_mov_b32_e32 v70, s8
	v_mov_b32_e32 v71, s9
	v_pk_add_f32 v[70:71], s[6:7], v[70:71]
	v_lshlrev_b32_e32 v54, 16, v89
	v_add_f32_e32 v70, v70, v71
	v_fmamk_f32 v70, v70, 0x3a000000, v252
	v_mul_f32_e32 v71, 0x4f800000, v70
	v_cmp_gt_f32_e32 vcc, s55, v70
	v_and_b32_e32 v55, 0xffff0000, v89
	v_pk_mul_f32 v[60:61], v[32:33], v[60:61]
	v_cndmask_b32_e32 v70, v70, v71, vcc
	v_sqrt_f32_e32 v71, v70
	s_add_i32 s18, s10, 0x3800
	v_pk_mul_f32 v[54:55], v[60:61], v[54:55]
	v_pk_mul_f32 v[46:47], v[64:65], v[46:47]
	v_add_u32_e32 v78, -1, v71
	v_fma_f32 v79, -v78, v71, v70
	v_cmp_ge_f32_e64 s[8:9], 0, v79
	v_add_u32_e32 v79, 1, v71
	s_ashr_i32 s19, s18, 31
	v_cndmask_b32_e64 v78, v71, v78, s[8:9]
	v_fma_f32 v71, -v79, v71, v70
	v_cvt_pk_bf16_f32 v46, v46, v47
	v_cvt_pk_bf16_f32 v47, v54, v55
	s_lshl_b64 s[16:17], s[18:19], 12
	v_cmp_lt_f32_e64 s[8:9], 0, v71
	global_store_dwordx2 v[80:81], v[46:47], off offset:3584
	v_lshl_add_u64 v[46:47], v[36:37], 0, s[16:17]
	v_cndmask_b32_e64 v71, v78, v79, s[8:9]
	v_lshl_add_u64 v[66:67], v[46:47], 0, v[0:1]
	v_lshl_add_u64 v[46:47], v[38:39], 0, s[16:17]
	v_mul_f32_e32 v78, 0x37800000, v71
	global_store_dwordx2 v[80:81], v[170:171], off
	v_lshl_add_u64 v[170:171], v[46:47], 0, v[0:1]
	v_lshl_add_u64 v[46:47], v[40:41], 0, s[16:17]
	v_cndmask_b32_e32 v71, v71, v78, vcc
	v_cmp_class_f32_e32 vcc, v70, v253
	v_lshl_add_u64 v[168:169], v[46:47], 0, v[0:1]
	global_load_dwordx2 v[144:145], v[66:67], off nt
	global_load_dwordx2 v[138:139], v[66:67], off offset:512 nt
	global_load_dwordx2 v[120:121], v[66:67], off offset:1024 nt
	global_load_dwordx2 v[110:111], v[66:67], off offset:1536 nt
	global_load_dwordx2 v[146:147], v[170:171], off nt
	global_load_dwordx2 v[142:143], v[170:171], off offset:512 nt
	global_load_dwordx2 v[122:123], v[170:171], off offset:1024 nt
	global_load_dwordx2 v[118:119], v[170:171], off offset:1536 nt
	global_load_dwordx2 v[64:65], v[168:169], off nt
	global_load_dwordx2 v[60:61], v[168:169], off offset:512 nt
	global_load_dwordx2 v[54:55], v[168:169], off offset:1024 nt
	global_load_dwordx2 v[46:47], v[168:169], off offset:1536 nt
	global_load_dwordx2 v[94:95], v[66:67], off offset:2048 nt
	global_load_dwordx2 v[88:89], v[66:67], off offset:2560 nt
	global_load_dwordx2 v[80:81], v[66:67], off offset:3072 nt
	s_nop 0
	global_load_dwordx2 v[66:67], v[66:67], off offset:3584 nt
	s_nop 0
	global_load_dwordx2 v[160:161], v[170:171], off offset:2048 nt
	global_load_dwordx2 v[156:157], v[170:171], off offset:2560 nt
	global_load_dwordx2 v[152:153], v[170:171], off offset:3072 nt
	global_load_dwordx2 v[136:137], v[170:171], off offset:3584 nt
	v_cndmask_b32_e32 v170, v71, v70, vcc
	v_div_scale_f32 v171, s[6:7], v170, v170, 1.0
	v_rcp_f32_e32 v192, v171
	global_load_dwordx2 v[102:103], v[168:169], off offset:2048 nt
	global_load_dwordx2 v[84:85], v[168:169], off offset:2560 nt
	global_load_dwordx2 v[78:79], v[168:169], off offset:3072 nt
	global_load_dwordx2 v[70:71], v[168:169], off offset:3584 nt
	s_addk_i32 s10, 0x4000
	s_cmp_lt_i32 s10, s47
	v_fma_f32 v168, -v171, v192, 1.0
	v_fmac_f32_e32 v192, v168, v192
	v_div_scale_f32 v168, vcc, 1.0, v170, 1.0
	v_mul_f32_e32 v169, v168, v192
	v_fma_f32 v193, -v171, v169, v168
	v_fmac_f32_e32 v169, v193, v192
	v_fma_f32 v168, -v171, v169, v168
	v_div_fmas_f32 v168, v168, v192, v169
	v_div_fixup_f32 v168, v168, v170, 1.0
	v_pk_mul_f32 v[172:173], v[172:173], v[168:169] op_sel_hi:[1,0]
	v_pk_mul_f32 v[174:175], v[174:175], v[168:169] op_sel_hi:[1,0]
	v_lshlrev_b32_e32 v192, 16, v62
	v_and_b32_e32 v193, 0xffff0000, v62
	v_lshlrev_b32_e32 v62, 16, v63
	v_and_b32_e32 v63, 0xffff0000, v63
	v_pk_mul_f32 v[174:175], v[2:3], v[174:175]
	v_pk_mul_f32 v[172:173], v[4:5], v[172:173]
	v_pk_mul_f32 v[134:135], v[134:135], v[168:169] op_sel_hi:[1,0]
	v_pk_mul_f32 v[62:63], v[172:173], v[62:63]
	v_pk_mul_f32 v[172:173], v[174:175], v[192:193]
	v_pk_mul_f32 v[166:167], v[166:167], v[168:169] op_sel_hi:[1,0]
	v_cvt_pk_bf16_f32 v172, v172, v173
	v_cvt_pk_bf16_f32 v173, v62, v63
	v_lshlrev_b32_e32 v62, 16, v56
	v_and_b32_e32 v63, 0xffff0000, v56
	v_lshlrev_b32_e32 v56, 16, v57
	v_and_b32_e32 v57, 0xffff0000, v57
	v_pk_mul_f32 v[166:167], v[6:7], v[166:167]
	v_pk_mul_f32 v[134:135], v[8:9], v[134:135]
	v_lshl_add_u64 v[170:171], v[34:35], 0, s[14:15]
	v_pk_mul_f32 v[56:57], v[134:135], v[56:57]
	v_pk_mul_f32 v[62:63], v[166:167], v[62:63]
	v_lshl_add_u64 v[170:171], v[170:171], 0, v[0:1]
	v_cvt_pk_bf16_f32 v62, v62, v63
	v_cvt_pk_bf16_f32 v63, v56, v57
	global_store_dwordx2 v[170:171], v[62:63], off offset:512
	v_pk_mul_f32 v[62:63], v[130:131], v[168:169] op_sel_hi:[1,0]
	v_pk_mul_f32 v[130:131], v[176:177], v[168:169] op_sel_hi:[1,0]
	v_lshlrev_b32_e32 v56, 16, v50
	v_and_b32_e32 v57, 0xffff0000, v50
	v_lshlrev_b32_e32 v50, 16, v51
	v_and_b32_e32 v51, 0xffff0000, v51
	v_pk_mul_f32 v[130:131], v[10:11], v[130:131]
	v_pk_mul_f32 v[62:63], v[12:13], v[62:63]
	v_pk_mul_f32 v[56:57], v[130:131], v[56:57]
	v_pk_mul_f32 v[50:51], v[62:63], v[50:51]
	v_cvt_pk_bf16_f32 v56, v56, v57
	v_cvt_pk_bf16_f32 v57, v50, v51
	global_store_dwordx2 v[170:171], v[56:57], off offset:1024
	v_pk_mul_f32 v[56:57], v[112:113], v[168:169] op_sel_hi:[1,0]
	v_pk_mul_f32 v[62:63], v[128:129], v[168:169] op_sel_hi:[1,0]
	v_lshlrev_b32_e32 v50, 16, v44
	v_and_b32_e32 v51, 0xffff0000, v44
	v_lshlrev_b32_e32 v44, 16, v45
	v_and_b32_e32 v45, 0xffff0000, v45
	v_pk_mul_f32 v[62:63], v[14:15], v[62:63]
	v_pk_mul_f32 v[56:57], v[16:17], v[56:57]
	v_pk_mul_f32 v[50:51], v[62:63], v[50:51]
	v_pk_mul_f32 v[44:45], v[56:57], v[44:45]
	v_cvt_pk_bf16_f32 v50, v50, v51
	v_cvt_pk_bf16_f32 v51, v44, v45
	v_pk_mul_f32 v[56:57], v[164:165], v[168:169] op_sel_hi:[1,0]
	v_pk_mul_f32 v[62:63], v[184:185], v[168:169] op_sel_hi:[1,0]
	global_store_dwordx2 v[170:171], v[50:51], off offset:1536
	s_waitcnt vmcnt(62)
	v_lshlrev_b32_e32 v44, 16, v116
	v_and_b32_e32 v45, 0xffff0000, v116
	v_lshlrev_b32_e32 v50, 16, v117
	v_and_b32_e32 v51, 0xffff0000, v117
	v_pk_mul_f32 v[62:63], v[18:19], v[62:63]
	v_pk_mul_f32 v[56:57], v[20:21], v[56:57]
	v_pk_mul_f32 v[44:45], v[62:63], v[44:45]
	v_pk_mul_f32 v[50:51], v[56:57], v[50:51]
	v_cvt_pk_bf16_f32 v44, v44, v45
	v_cvt_pk_bf16_f32 v45, v50, v51
	v_pk_mul_f32 v[56:57], v[178:179], v[168:169] op_sel_hi:[1,0]
	v_pk_mul_f32 v[62:63], v[114:115], v[168:169] op_sel_hi:[1,0]
	global_store_dwordx2 v[170:171], v[44:45], off offset:2048
	v_lshlrev_b32_e32 v44, 16, v104
	v_and_b32_e32 v45, 0xffff0000, v104
	v_lshlrev_b32_e32 v50, 16, v105
	v_and_b32_e32 v51, 0xffff0000, v105
	v_pk_mul_f32 v[62:63], v[22:23], v[62:63]
	v_pk_mul_f32 v[56:57], v[24:25], v[56:57]
	v_pk_mul_f32 v[44:45], v[62:63], v[44:45]
	v_pk_mul_f32 v[50:51], v[56:57], v[50:51]
	v_cvt_pk_bf16_f32 v44, v44, v45
	v_cvt_pk_bf16_f32 v45, v50, v51
	v_pk_mul_f32 v[56:57], v[186:187], v[168:169] op_sel_hi:[1,0]
	v_pk_mul_f32 v[62:63], v[180:181], v[168:169] op_sel_hi:[1,0]
	global_store_dwordx2 v[170:171], v[44:45], off offset:2560
	v_lshlrev_b32_e32 v44, 16, v92
	v_and_b32_e32 v45, 0xffff0000, v92
	v_lshlrev_b32_e32 v50, 16, v93
	v_and_b32_e32 v51, 0xffff0000, v93
	v_pk_mul_f32 v[62:63], v[26:27], v[62:63]
	v_pk_mul_f32 v[56:57], v[28:29], v[56:57]
	v_pk_mul_f32 v[44:45], v[62:63], v[44:45]
	v_pk_mul_f32 v[50:51], v[56:57], v[50:51]
	v_cvt_pk_bf16_f32 v44, v44, v45
	v_cvt_pk_bf16_f32 v45, v50, v51
	v_pk_mul_f32 v[56:57], v[190:191], v[168:169] op_sel_hi:[1,0]
	v_pk_mul_f32 v[62:63], v[188:189], v[168:169] op_sel_hi:[1,0]
	global_store_dwordx2 v[170:171], v[44:45], off offset:3072
	v_lshlrev_b32_e32 v44, 16, v86
	v_and_b32_e32 v45, 0xffff0000, v86
	v_lshlrev_b32_e32 v50, 16, v87
	v_and_b32_e32 v51, 0xffff0000, v87
	v_pk_mul_f32 v[62:63], v[30:31], v[62:63]
	v_pk_mul_f32 v[56:57], v[32:33], v[56:57]
	v_pk_mul_f32 v[44:45], v[62:63], v[44:45]
	v_pk_mul_f32 v[50:51], v[56:57], v[50:51]
	v_cvt_pk_bf16_f32 v44, v44, v45
	v_cvt_pk_bf16_f32 v45, v50, v51
	global_store_dwordx2 v[170:171], v[172:173], off
	global_store_dwordx2 v[170:171], v[44:45], off offset:3584
	s_waitcnt vmcnt(62)
	v_lshlrev_b32_e32 v168, 16, v140
	v_and_b32_e32 v169, 0xffff0000, v140
	s_waitcnt vmcnt(59)
	v_lshlrev_b32_e32 v170, 16, v148
	v_and_b32_e32 v171, 0xffff0000, v148
	v_lshlrev_b32_e32 v140, 16, v141
	v_and_b32_e32 v141, 0xffff0000, v141
	v_lshlrev_b32_e32 v148, 16, v149
	v_and_b32_e32 v149, 0xffff0000, v149
	v_pk_add_f32 v[168:169], v[168:169], v[170:171]
	v_pk_add_f32 v[148:149], v[140:141], v[148:149]
	v_lshlrev_b32_e32 v140, 16, v126
	v_and_b32_e32 v141, 0xffff0000, v126
	s_waitcnt vmcnt(58)
	v_lshlrev_b32_e32 v170, 16, v132
	v_and_b32_e32 v171, 0xffff0000, v132
	v_pk_add_f32 v[140:141], v[140:141], v[170:171]
	v_lshlrev_b32_e32 v126, 16, v127
	v_and_b32_e32 v127, 0xffff0000, v127
	v_lshlrev_b32_e32 v132, 16, v133
	v_and_b32_e32 v133, 0xffff0000, v133
	v_pk_add_f32 v[132:133], v[126:127], v[132:133]
	v_mov_b32_e32 v170, v169
	v_mov_b32_e32 v171, v141
	v_mov_b32_e32 v126, v168
	v_mov_b32_e32 v127, v140
	v_pk_mul_f32 v[170:171], v[170:171], v[170:171]
	v_mov_b32_e32 v172, v149
	v_mov_b32_e32 v173, v133
	v_pk_fma_f32 v[126:127], v[126:127], v[126:127], v[170:171]
	v_mov_b32_e32 v170, v148
	v_mov_b32_e32 v171, v132
	v_pk_mul_f32 v[172:173], v[172:173], v[172:173]
	s_waitcnt vmcnt(47)
; template <bool HG>
; __device__ __forceinline__ void readout_phase2(const Args& a, Frame& F, const float* gain, int nrows) {
;     ...
;     const bool cx = ML + nw < nrows;
;     RO_LOAD(f2, b2, g2, cx ? ML + nw : nw + 7 * 2048);
	v_lshlrev_b32_e32 v178, 16, v162
	v_pk_fma_f32 v[170:171], v[170:171], v[170:171], v[172:173]
	v_lshlrev_b32_e32 v172, 16, v124
	v_pk_add_f32 v[126:127], v[126:127], v[170:171]
	v_lshlrev_b32_e32 v170, 16, v108
	v_and_b32_e32 v171, 0xffff0000, v108
	v_and_b32_e32 v173, 0xffff0000, v124
	v_lshlrev_b32_e32 v108, 16, v109
	v_and_b32_e32 v109, 0xffff0000, v109
	v_lshlrev_b32_e32 v124, 16, v125
	v_and_b32_e32 v125, 0xffff0000, v125
	v_pk_add_f32 v[170:171], v[170:171], v[172:173]
	v_pk_add_f32 v[174:175], v[108:109], v[124:125]
	v_mov_b32_e32 v124, v171
	v_mov_b32_e32 v125, v175
	v_mov_b32_e32 v108, v170
	v_mov_b32_e32 v109, v174
	v_pk_mul_f32 v[124:125], v[124:125], v[124:125]
	v_lshlrev_b32_e32 v172, 16, v100
	v_pk_fma_f32 v[108:109], v[108:109], v[108:109], v[124:125]
	v_lshlrev_b32_e32 v124, 16, v98
	v_and_b32_e32 v125, 0xffff0000, v98
	v_and_b32_e32 v173, 0xffff0000, v100
	v_pk_add_f32 v[172:173], v[124:125], v[172:173]
	v_lshlrev_b32_e32 v98, 16, v99
	v_and_b32_e32 v99, 0xffff0000, v99
	v_lshlrev_b32_e32 v100, 16, v101
	v_and_b32_e32 v101, 0xffff0000, v101
	v_lshlrev_b32_e32 v124, 16, v90
	v_and_b32_e32 v125, 0xffff0000, v90
	v_and_b32_e32 v179, 0xffff0000, v162
	v_pk_add_f32 v[176:177], v[98:99], v[100:101]
	v_pk_add_f32 v[178:179], v[124:125], v[178:179]
	v_lshlrev_b32_e32 v90, 16, v91
	v_and_b32_e32 v91, 0xffff0000, v91
	v_lshlrev_b32_e32 v124, 16, v163
	v_and_b32_e32 v125, 0xffff0000, v163
	v_mul_f32_e32 v98, v173, v173
	v_mul_f32_e32 v100, v177, v177
	v_pk_add_f32 v[162:163], v[90:91], v[124:125]
	v_pk_add_f32 v[126:127], v[126:127], v[126:127] op_sel:[0,1] op_sel_hi:[1,0]
	v_pk_add_f32 v[108:109], v[108:109], v[108:109] op_sel:[0,1] op_sel_hi:[1,0]
	v_pk_fma_f32 v[98:99], v[172:173], v[172:173], v[98:99] op_sel_hi:[1,1,0]
	v_pk_fma_f32 v[100:101], v[176:177], v[176:177], v[100:101] op_sel_hi:[1,1,0]
	v_pk_mul_f32 v[90:91], v[178:179], v[178:179]
	v_pk_mul_f32 v[124:125], v[162:163], v[162:163]
	v_mov_b32_e32 v127, v90
	v_mov_b32_e32 v109, v91
	v_mov_b32_e32 v99, v124
	v_mov_b32_e32 v101, v125
	v_pk_add_f32 v[90:91], v[126:127], v[108:109]
	v_pk_add_f32 v[98:99], v[98:99], v[100:101]
	s_waitcnt vmcnt(46)
	v_lshlrev_b32_e32 v100, 16, v158
	v_pk_add_f32 v[90:91], v[90:91], v[98:99]
	v_lshlrev_b32_e32 v98, 16, v76
	v_and_b32_e32 v99, 0xffff0000, v76
	v_and_b32_e32 v101, 0xffff0000, v158
	v_pk_add_f32 v[180:181], v[98:99], v[100:101]
	v_lshlrev_b32_e32 v76, 16, v77
	v_and_b32_e32 v77, 0xffff0000, v77
	v_lshlrev_b32_e32 v98, 16, v159
	v_and_b32_e32 v99, 0xffff0000, v159
	v_pk_add_f32 v[158:159], v[76:77], v[98:99]
	v_mov_b32_e32 v98, v181
	v_mov_b32_e32 v99, v159
	v_mov_b32_e32 v76, v180
	v_mov_b32_e32 v77, v158
	v_pk_mul_f32 v[98:99], v[98:99], v[98:99]
	s_waitcnt vmcnt(45)
	v_lshlrev_b32_e32 v100, 16, v154
	v_pk_fma_f32 v[76:77], v[76:77], v[76:77], v[98:99]
	v_lshlrev_b32_e32 v98, 16, v74
	v_and_b32_e32 v99, 0xffff0000, v74
	v_and_b32_e32 v101, 0xffff0000, v154
	v_pk_add_f32 v[184:185], v[98:99], v[100:101]
	v_lshlrev_b32_e32 v74, 16, v75
	v_and_b32_e32 v75, 0xffff0000, v75
	v_lshlrev_b32_e32 v98, 16, v155
	v_and_b32_e32 v99, 0xffff0000, v155
	v_lshlrev_b32_e32 v100, 16, v68
	v_and_b32_e32 v101, 0xffff0000, v68
	s_waitcnt vmcnt(44)
	v_lshlrev_b32_e32 v108, 16, v150
	v_and_b32_e32 v109, 0xffff0000, v150
	v_pk_add_f32 v[154:155], v[74:75], v[98:99]
	v_pk_add_f32 v[186:187], v[100:101], v[108:109]
	v_lshlrev_b32_e32 v68, 16, v69
	v_and_b32_e32 v69, 0xffff0000, v69
	v_lshlrev_b32_e32 v100, 16, v151
	v_and_b32_e32 v101, 0xffff0000, v151
	v_mul_f32_e32 v74, v185, v185
	v_mul_f32_e32 v98, v155, v155
	v_pk_add_f32 v[150:151], v[68:69], v[100:101]
	v_pk_add_f32 v[90:91], v[90:91], v[90:91] op_sel:[0,1] op_sel_hi:[1,0]
	v_pk_add_f32 v[76:77], v[76:77], v[76:77] op_sel:[0,1] op_sel_hi:[1,0]
	v_pk_fma_f32 v[74:75], v[184:185], v[184:185], v[74:75] op_sel_hi:[1,1,0]
	v_pk_fma_f32 v[98:99], v[154:155], v[154:155], v[98:99] op_sel_hi:[1,1,0]
	v_pk_mul_f32 v[68:69], v[186:187], v[186:187]
	v_pk_mul_f32 v[100:101], v[150:151], v[150:151]
	v_mov_b32_e32 v91, v68
	v_mov_b32_e32 v77, v69
	v_mov_b32_e32 v75, v100
	v_mov_b32_e32 v99, v101
	v_pk_add_f32 v[68:69], v[90:91], v[76:77]
	v_pk_add_f32 v[74:75], v[74:75], v[98:99]
	s_cselect_b64 s[14:15], -1, 0
	v_pk_add_f32 v[68:69], v[68:69], v[74:75]
	s_and_b64 s[6:7], s[14:15], exec
	v_add_f32_e32 v68, v68, v69
	s_cselect_b32 s6, s10, s18
	s_ashr_i32 s7, s6, 31
	v_add_f32_dpp v68, v68, v68 quad_perm:[1,0,3,2] row_mask:0xf bank_mask:0xf bound_ctrl:1
	s_lshl_b64 s[6:7], s[6:7], 12
	v_lshl_add_u64 v[36:37], v[36:37], 0, s[6:7]
	v_add_f32_dpp v68, v68, v68 quad_perm:[2,3,0,1] row_mask:0xf bank_mask:0xf bound_ctrl:1
	v_lshl_add_u64 v[50:51], v[36:37], 0, v[0:1]
	v_lshl_add_u64 v[36:37], v[38:39], 0, s[6:7]
	v_add_f32_dpp v68, v68, v68 row_half_mirror row_mask:0xf bank_mask:0xf bound_ctrl:1
	v_lshl_add_u64 v[166:167], v[36:37], 0, v[0:1]
	v_lshl_add_u64 v[36:37], v[40:41], 0, s[6:7]
	v_add_f32_dpp v68, v68, v68 row_mirror row_mask:0xf bank_mask:0xf bound_ctrl:1
	v_lshl_add_u64 v[164:165], v[36:37], 0, v[0:1]
	v_readlane_b32 s8, v68, 16
	v_readlane_b32 s9, v68, 48
	v_readlane_b32 s6, v68, 0
	v_readlane_b32 s7, v68, 32
	v_mov_b32_e32 v68, s8
	v_mov_b32_e32 v69, s9
	v_pk_add_f32 v[68:69], s[6:7], v[68:69]
	global_load_dwordx2 v[130:131], v[50:51], off nt
	global_load_dwordx2 v[116:117], v[50:51], off offset:512 nt
	global_load_dwordx2 v[112:113], v[50:51], off offset:1024 nt
	global_load_dwordx2 v[92:93], v[50:51], off offset:1536 nt
	global_load_dwordx2 v[134:135], v[166:167], off nt
	global_load_dwordx2 v[128:129], v[166:167], off offset:512 nt
	global_load_dwordx2 v[114:115], v[166:167], off offset:1024 nt
; template <bool HG>
; __device__ __forceinline__ void readout_phase2(const Args& a, Frame& F, const float* gain, int nrows) {
;     ...
;     RO_LOAD(f2, b2, g2, cx ? ML + nw : nw + 7 * 2048);
;     RO_FINISH(f0, b0, g0, nw + 6 * 2048);
	global_load_dwordx2 v[104:105], v[166:167], off offset:1536 nt
	global_load_dwordx2 v[44:45], v[164:165], off nt
	global_load_dwordx2 v[40:41], v[164:165], off offset:512 nt
	global_load_dwordx2 v[38:39], v[164:165], off offset:1024 nt
	global_load_dwordx2 v[36:37], v[164:165], off offset:1536 nt
	global_load_dwordx2 v[86:87], v[50:51], off offset:2048 nt
	global_load_dwordx2 v[62:63], v[50:51], off offset:2560 nt
	global_load_dwordx2 v[56:57], v[50:51], off offset:3072 nt
	s_nop 0
	global_load_dwordx2 v[50:51], v[50:51], off offset:3584 nt
	v_add_f32_e32 v68, v68, v69
	v_fmamk_f32 v68, v68, 0x3a000000, v252
	v_mul_f32_e32 v69, 0x4f800000, v68
	v_cmp_gt_f32_e32 vcc, s55, v68
	global_load_dwordx2 v[124:125], v[166:167], off offset:2048 nt
	global_load_dwordx2 v[108:109], v[166:167], off offset:2560 nt
	global_load_dwordx2 v[100:101], v[166:167], off offset:3072 nt
	global_load_dwordx2 v[98:99], v[166:167], off offset:3584 nt
	v_cndmask_b32_e32 v68, v68, v69, vcc
	v_sqrt_f32_e32 v69, v68
	s_nop 0
	v_add_u32_e32 v74, -1, v69
	v_fma_f32 v75, -v74, v69, v68
	v_cmp_ge_f32_e64 s[8:9], 0, v75
	v_add_u32_e32 v75, 1, v69
	s_nop 0
	v_cndmask_b32_e64 v74, v69, v74, s[8:9]
	v_fma_f32 v69, -v75, v69, v68
	v_cmp_lt_f32_e64 s[8:9], 0, v69
	s_nop 1
	v_cndmask_b32_e64 v69, v74, v75, s[8:9]
	v_mul_f32_e32 v74, 0x37800000, v69
	v_cndmask_b32_e32 v69, v69, v74, vcc
	v_cmp_class_f32_e32 vcc, v68, v253
	s_nop 1
	v_cndmask_b32_e32 v126, v69, v68, vcc
	v_div_scale_f32 v127, s[6:7], v126, v126, 1.0
	v_rcp_f32_e32 v166, v127
	global_load_dwordx2 v[90:91], v[164:165], off offset:2048 nt
	global_load_dwordx2 v[76:77], v[164:165], off offset:2560 nt
	global_load_dwordx2 v[74:75], v[164:165], off offset:3072 nt
	global_load_dwordx2 v[68:69], v[164:165], off offset:3584 nt
	v_fma_f32 v164, -v127, v166, 1.0
	v_fmac_f32_e32 v166, v164, v166
	v_div_scale_f32 v164, vcc, 1.0, v126, 1.0
	v_mul_f32_e32 v165, v164, v166
	v_fma_f32 v167, -v127, v165, v164
	v_fmac_f32_e32 v165, v167, v166
	v_fma_f32 v127, -v127, v165, v164
	v_div_fmas_f32 v127, v127, v166, v165
	v_div_fixup_f32 v164, v127, v126, 1.0
	v_pk_mul_f32 v[148:149], v[148:149], v[164:165] op_sel_hi:[1,0]
	v_pk_mul_f32 v[168:169], v[168:169], v[164:165] op_sel_hi:[1,0]
	v_lshlrev_b32_e32 v166, 16, v58
	v_and_b32_e32 v167, 0xffff0000, v58
	v_lshlrev_b32_e32 v58, 16, v59
	v_and_b32_e32 v59, 0xffff0000, v59
	v_pk_mul_f32 v[168:169], v[2:3], v[168:169]
	v_pk_mul_f32 v[148:149], v[4:5], v[148:149]
	v_pk_mul_f32 v[132:133], v[132:133], v[164:165] op_sel_hi:[1,0]
	v_pk_mul_f32 v[58:59], v[148:149], v[58:59]
	v_pk_mul_f32 v[148:149], v[168:169], v[166:167]
	v_pk_mul_f32 v[140:141], v[140:141], v[164:165] op_sel_hi:[1,0]
	v_cvt_pk_bf16_f32 v148, v148, v149
	v_cvt_pk_bf16_f32 v149, v58, v59
	v_lshlrev_b32_e32 v58, 16, v52
	v_and_b32_e32 v59, 0xffff0000, v52
	v_lshlrev_b32_e32 v52, 16, v53
	v_and_b32_e32 v53, 0xffff0000, v53
	v_pk_mul_f32 v[140:141], v[6:7], v[140:141]
	v_pk_mul_f32 v[132:133], v[8:9], v[132:133]
	v_lshl_add_u64 v[126:127], v[34:35], 0, s[12:13]
	v_pk_mul_f32 v[52:53], v[132:133], v[52:53]
	v_pk_mul_f32 v[58:59], v[140:141], v[58:59]
	v_lshl_add_u64 v[126:127], v[126:127], 0, v[0:1]
	v_cvt_pk_bf16_f32 v58, v58, v59
	v_cvt_pk_bf16_f32 v59, v52, v53
	global_store_dwordx2 v[126:127], v[58:59], off offset:512
	v_pk_mul_f32 v[58:59], v[174:175], v[164:165] op_sel_hi:[1,0]
	v_pk_mul_f32 v[132:133], v[170:171], v[164:165] op_sel_hi:[1,0]
	v_lshlrev_b32_e32 v52, 16, v48
	v_and_b32_e32 v53, 0xffff0000, v48
	v_lshlrev_b32_e32 v48, 16, v49
	v_and_b32_e32 v49, 0xffff0000, v49
	v_pk_mul_f32 v[132:133], v[10:11], v[132:133]
	v_pk_mul_f32 v[58:59], v[12:13], v[58:59]
	v_pk_mul_f32 v[52:53], v[132:133], v[52:53]
	v_pk_mul_f32 v[48:49], v[58:59], v[48:49]
	v_cvt_pk_bf16_f32 v52, v52, v53
	v_cvt_pk_bf16_f32 v53, v48, v49
	global_store_dwordx2 v[126:127], v[52:53], off offset:1024
	v_pk_mul_f32 v[52:53], v[176:177], v[164:165] op_sel_hi:[1,0]
	v_pk_mul_f32 v[58:59], v[172:173], v[164:165] op_sel_hi:[1,0]
	v_lshlrev_b32_e32 v48, 16, v42
	v_and_b32_e32 v49, 0xffff0000, v42
	v_lshlrev_b32_e32 v42, 16, v43
	v_and_b32_e32 v43, 0xffff0000, v43
	v_pk_mul_f32 v[58:59], v[14:15], v[58:59]
	v_pk_mul_f32 v[52:53], v[16:17], v[52:53]
	v_pk_mul_f32 v[48:49], v[58:59], v[48:49]
	v_pk_mul_f32 v[42:43], v[52:53], v[42:43]
	v_cvt_pk_bf16_f32 v48, v48, v49
	v_cvt_pk_bf16_f32 v49, v42, v43
	v_pk_mul_f32 v[52:53], v[162:163], v[164:165] op_sel_hi:[1,0]
	v_pk_mul_f32 v[58:59], v[178:179], v[164:165] op_sel_hi:[1,0]
	global_store_dwordx2 v[126:127], v[48:49], off offset:1536
	s_waitcnt vmcnt(62)
	v_lshlrev_b32_e32 v42, 16, v106
	v_and_b32_e32 v43, 0xffff0000, v106
	v_lshlrev_b32_e32 v48, 16, v107
	v_and_b32_e32 v49, 0xffff0000, v107
	v_pk_mul_f32 v[58:59], v[18:19], v[58:59]
	v_pk_mul_f32 v[52:53], v[20:21], v[52:53]
	v_pk_mul_f32 v[42:43], v[58:59], v[42:43]
	v_pk_mul_f32 v[48:49], v[52:53], v[48:49]
	v_cvt_pk_bf16_f32 v42, v42, v43
	v_cvt_pk_bf16_f32 v43, v48, v49
	v_pk_mul_f32 v[52:53], v[158:159], v[164:165] op_sel_hi:[1,0]
	v_pk_mul_f32 v[58:59], v[180:181], v[164:165] op_sel_hi:[1,0]
	global_store_dwordx2 v[126:127], v[42:43], off offset:2048
	v_lshlrev_b32_e32 v42, 16, v96
	v_and_b32_e32 v43, 0xffff0000, v96
	v_lshlrev_b32_e32 v48, 16, v97
	v_and_b32_e32 v49, 0xffff0000, v97
	v_pk_mul_f32 v[58:59], v[22:23], v[58:59]
	v_pk_mul_f32 v[52:53], v[24:25], v[52:53]
	v_pk_mul_f32 v[42:43], v[58:59], v[42:43]
	v_pk_mul_f32 v[48:49], v[52:53], v[48:49]
	v_cvt_pk_bf16_f32 v42, v42, v43
	v_cvt_pk_bf16_f32 v43, v48, v49
	v_pk_mul_f32 v[52:53], v[154:155], v[164:165] op_sel_hi:[1,0]
	v_pk_mul_f32 v[58:59], v[184:185], v[164:165] op_sel_hi:[1,0]
	global_store_dwordx2 v[126:127], v[42:43], off offset:2560
	v_lshlrev_b32_e32 v42, 16, v82
	v_and_b32_e32 v43, 0xffff0000, v82
	v_lshlrev_b32_e32 v48, 16, v83
	v_and_b32_e32 v49, 0xffff0000, v83
	v_pk_mul_f32 v[58:59], v[26:27], v[58:59]
	v_pk_mul_f32 v[52:53], v[28:29], v[52:53]
	v_pk_mul_f32 v[42:43], v[58:59], v[42:43]
	v_pk_mul_f32 v[48:49], v[52:53], v[48:49]
	v_cvt_pk_bf16_f32 v42, v42, v43
	v_cvt_pk_bf16_f32 v43, v48, v49
	global_store_dwordx2 v[126:127], v[42:43], off offset:3072
	v_pk_mul_f32 v[42:43], v[186:187], v[164:165] op_sel_hi:[1,0]
	s_waitcnt vmcnt(57)
	v_lshlrev_b32_e32 v48, 16, v146
	v_pk_mul_f32 v[132:133], v[30:31], v[42:43]
	v_lshlrev_b32_e32 v42, 16, v144
	v_and_b32_e32 v43, 0xffff0000, v144
	v_and_b32_e32 v49, 0xffff0000, v146
	v_pk_add_f32 v[48:49], v[42:43], v[48:49]
	v_lshlrev_b32_e32 v42, 16, v145
	v_and_b32_e32 v43, 0xffff0000, v145
	v_lshlrev_b32_e32 v52, 16, v147
	v_and_b32_e32 v53, 0xffff0000, v147
	v_pk_add_f32 v[58:59], v[42:43], v[52:53]
	v_lshlrev_b32_e32 v42, 16, v138
	v_and_b32_e32 v43, 0xffff0000, v138
	s_waitcnt vmcnt(56)
	v_lshlrev_b32_e32 v52, 16, v142
	v_and_b32_e32 v53, 0xffff0000, v142
	v_pk_add_f32 v[42:43], v[42:43], v[52:53]
	v_lshlrev_b32_e32 v52, 16, v139
	v_and_b32_e32 v53, 0xffff0000, v139
	v_lshlrev_b32_e32 v96, 16, v143
	v_and_b32_e32 v97, 0xffff0000, v143
	v_pk_add_f32 v[52:53], v[52:53], v[96:97]
	v_mov_b32_e32 v138, v49
	v_mov_b32_e32 v139, v43
	v_mov_b32_e32 v96, v48
	v_mov_b32_e32 v97, v42
	v_pk_mul_f32 v[138:139], v[138:139], v[138:139]
	v_mov_b32_e32 v140, v59
	v_mov_b32_e32 v141, v53
	v_pk_fma_f32 v[96:97], v[96:97], v[96:97], v[138:139]
	v_mov_b32_e32 v138, v58
	v_mov_b32_e32 v139, v52
	v_pk_mul_f32 v[140:141], v[140:141], v[140:141]
	s_waitcnt vmcnt(54)
	v_lshlrev_b32_e32 v142, 16, v118
	v_pk_fma_f32 v[138:139], v[138:139], v[138:139], v[140:141]
	v_lshlrev_b32_e32 v140, 16, v122
	v_pk_add_f32 v[96:97], v[96:97], v[138:139]
	v_and_b32_e32 v141, 0xffff0000, v122
	v_pk_add_f32 v[138:139], v[96:97], v[96:97] op_sel:[0,1] op_sel_hi:[1,0]
	v_lshlrev_b32_e32 v96, 16, v120
	v_and_b32_e32 v97, 0xffff0000, v120
	v_lshlrev_b32_e32 v120, 16, v121
	v_and_b32_e32 v121, 0xffff0000, v121
	v_lshlrev_b32_e32 v122, 16, v123
	v_and_b32_e32 v123, 0xffff0000, v123
	v_pk_add_f32 v[96:97], v[96:97], v[140:141]
	v_pk_add_f32 v[120:121], v[120:121], v[122:123]
	v_mov_b32_e32 v140, v97
	v_mov_b32_e32 v141, v121
	v_mov_b32_e32 v122, v96
	v_mov_b32_e32 v123, v120
	v_pk_mul_f32 v[140:141], v[140:141], v[140:141]
	v_and_b32_e32 v143, 0xffff0000, v118
	v_pk_fma_f32 v[122:123], v[122:123], v[122:123], v[140:141]
	v_lshlrev_b32_e32 v140, 16, v110
	v_and_b32_e32 v141, 0xffff0000, v110
	v_lshlrev_b32_e32 v110, 16, v111
	v_and_b32_e32 v111, 0xffff0000, v111
	v_lshlrev_b32_e32 v118, 16, v119
	v_and_b32_e32 v119, 0xffff0000, v119
	s_waitcnt vmcnt(49)
	v_lshlrev_b32_e32 v144, 16, v94
	v_and_b32_e32 v145, 0xffff0000, v94
	s_waitcnt vmcnt(45)
	v_lshlrev_b32_e32 v146, 16, v160
	v_and_b32_e32 v147, 0xffff0000, v160
	v_pk_add_f32 v[140:141], v[140:141], v[142:143]
	v_pk_add_f32 v[110:111], v[110:111], v[118:119]
	v_pk_add_f32 v[144:145], v[144:145], v[146:147]
	v_lshlrev_b32_e32 v94, 16, v95
	v_and_b32_e32 v95, 0xffff0000, v95
	v_lshlrev_b32_e32 v146, 16, v161
	v_and_b32_e32 v147, 0xffff0000, v161
	v_mul_f32_e32 v118, v141, v141
	v_mul_f32_e32 v142, v111, v111
	v_pk_add_f32 v[94:95], v[94:95], v[146:147]
	global_store_dwordx2 v[126:127], v[148:149], off
	v_pk_add_f32 v[122:123], v[122:123], v[122:123] op_sel:[0,1] op_sel_hi:[1,0]
	v_pk_fma_f32 v[118:119], v[140:141], v[140:141], v[118:119] op_sel_hi:[1,1,0]
	v_pk_fma_f32 v[142:143], v[110:111], v[110:111], v[142:143] op_sel_hi:[1,1,0]
	v_pk_mul_f32 v[146:147], v[144:145], v[144:145]
	v_pk_mul_f32 v[148:149], v[94:95], v[94:95]
	v_mov_b32_e32 v139, v146
	v_mov_b32_e32 v123, v147
	v_mov_b32_e32 v119, v148
	v_mov_b32_e32 v143, v149
	v_pk_add_f32 v[122:123], v[138:139], v[122:123]
	v_pk_add_f32 v[118:119], v[118:119], v[142:143]
	s_waitcnt vmcnt(45)
	v_lshlrev_b32_e32 v138, 16, v156
	v_pk_add_f32 v[118:119], v[122:123], v[118:119]
	v_lshlrev_b32_e32 v122, 16, v88
	v_and_b32_e32 v123, 0xffff0000, v88
	v_and_b32_e32 v139, 0xffff0000, v156
	v_pk_add_f32 v[122:123], v[122:123], v[138:139]
	v_lshlrev_b32_e32 v88, 16, v89
	v_and_b32_e32 v89, 0xffff0000, v89
	v_lshlrev_b32_e32 v138, 16, v157
	v_and_b32_e32 v139, 0xffff0000, v157
	v_pk_add_f32 v[88:89], v[88:89], v[138:139]
	v_mov_b32_e32 v142, v123
	v_mov_b32_e32 v143, v89
	v_mov_b32_e32 v138, v122
	v_mov_b32_e32 v139, v88
	v_pk_mul_f32 v[142:143], v[142:143], v[142:143]
	s_waitcnt vmcnt(44)
	v_lshlrev_b32_e32 v146, 16, v152
	v_pk_fma_f32 v[138:139], v[138:139], v[138:139], v[142:143]
	v_lshlrev_b32_e32 v142, 16, v80
	v_and_b32_e32 v143, 0xffff0000, v80
	v_and_b32_e32 v147, 0xffff0000, v152
	v_pk_add_f32 v[142:143], v[142:143], v[146:147]
	v_lshlrev_b32_e32 v80, 16, v81
	v_and_b32_e32 v81, 0xffff0000, v81
	v_lshlrev_b32_e32 v146, 16, v153
	v_and_b32_e32 v147, 0xffff0000, v153
	v_pk_mul_f32 v[106:107], v[150:151], v[164:165] op_sel_hi:[1,0]
	v_pk_add_f32 v[80:81], v[80:81], v[146:147]
	v_lshlrev_b32_e32 v150, 16, v66
	v_and_b32_e32 v151, 0xffff0000, v66
	s_waitcnt vmcnt(43)
	v_lshlrev_b32_e32 v152, 16, v136
	v_and_b32_e32 v153, 0xffff0000, v136
	v_lshlrev_b32_e32 v66, 16, v67
	v_and_b32_e32 v67, 0xffff0000, v67
	v_lshlrev_b32_e32 v136, 16, v137
	v_and_b32_e32 v137, 0xffff0000, v137
	v_mul_f32_e32 v146, v143, v143
	v_mul_f32_e32 v148, v81, v81
	v_pk_add_f32 v[150:151], v[150:151], v[152:153]
	v_pk_add_f32 v[66:67], v[66:67], v[136:137]
	v_pk_add_f32 v[118:119], v[118:119], v[118:119] op_sel:[0,1] op_sel_hi:[1,0]
	v_pk_add_f32 v[138:139], v[138:139], v[138:139] op_sel:[0,1] op_sel_hi:[1,0]
	v_pk_fma_f32 v[146:147], v[142:143], v[142:143], v[146:147] op_sel_hi:[1,1,0]
	v_pk_fma_f32 v[148:149], v[80:81], v[80:81], v[148:149] op_sel_hi:[1,1,0]
	v_pk_mul_f32 v[136:137], v[150:151], v[150:151]
	v_pk_mul_f32 v[152:153], v[66:67], v[66:67]
	v_mov_b32_e32 v119, v136
	v_mov_b32_e32 v139, v137
	v_mov_b32_e32 v147, v152
	v_mov_b32_e32 v149, v153
	v_pk_add_f32 v[118:119], v[118:119], v[138:139]
	v_pk_add_f32 v[136:137], v[146:147], v[148:149]
	v_lshlrev_b32_e32 v82, 16, v72
	v_pk_add_f32 v[118:119], v[118:119], v[136:137]
	v_and_b32_e32 v83, 0xffff0000, v72
	v_add_f32_e32 v118, v118, v119
	v_lshlrev_b32_e32 v72, 16, v73
	v_and_b32_e32 v73, 0xffff0000, v73
	v_add_f32_dpp v118, v118, v118 quad_perm:[1,0,3,2] row_mask:0xf bank_mask:0xf bound_ctrl:1
	v_pk_mul_f32 v[106:107], v[32:33], v[106:107]
	v_pk_mul_f32 v[82:83], v[132:133], v[82:83]
	v_add_f32_dpp v118, v118, v118 quad_perm:[2,3,0,1] row_mask:0xf bank_mask:0xf bound_ctrl:1
	v_pk_mul_f32 v[72:73], v[106:107], v[72:73]
	v_cvt_pk_bf16_f32 v82, v82, v83
	v_add_f32_dpp v118, v118, v118 row_half_mirror row_mask:0xf bank_mask:0xf bound_ctrl:1
	v_cvt_pk_bf16_f32 v83, v72, v73
	global_store_dwordx2 v[126:127], v[82:83], off offset:3584
	v_add_f32_dpp v118, v118, v118 row_mirror row_mask:0xf bank_mask:0xf bound_ctrl:1
	s_nop 0
	v_readlane_b32 s8, v118, 16
	v_readlane_b32 s9, v118, 48
	v_readlane_b32 s6, v118, 0
	v_readlane_b32 s7, v118, 32
	v_mov_b32_e32 v118, s8
	v_mov_b32_e32 v119, s9
	v_pk_add_f32 v[118:119], s[6:7], v[118:119]
	s_nop 0
	v_add_f32_e32 v118, v118, v119
	v_fmamk_f32 v118, v118, 0x3a000000, v252
	v_mul_f32_e32 v119, 0x4f800000, v118
	v_cmp_gt_f32_e32 vcc, s55, v118
	s_nop 1
	v_cndmask_b32_e32 v118, v118, v119, vcc
	v_sqrt_f32_e32 v119, v118
	s_nop 0
	v_add_u32_e32 v106, -1, v119
	v_fma_f32 v107, -v106, v119, v118
	v_cmp_ge_f32_e64 s[8:9], 0, v107
	v_add_u32_e32 v107, 1, v119
	s_nop 0
	v_cndmask_b32_e64 v106, v119, v106, s[8:9]
	v_fma_f32 v119, -v107, v119, v118
	v_cmp_lt_f32_e64 s[8:9], 0, v119
	s_nop 1
	v_cndmask_b32_e64 v106, v106, v107, s[8:9]
	v_mul_f32_e32 v107, 0x37800000, v106
	v_cndmask_b32_e32 v106, v106, v107, vcc
	v_cmp_class_f32_e32 vcc, v118, v253
	s_nop 1
	v_cndmask_b32_e32 v106, v106, v118, vcc
	v_div_scale_f32 v107, s[6:7], v106, v106, 1.0
	v_rcp_f32_e32 v118, v107
	s_nop 0
	v_fma_f32 v72, -v107, v118, 1.0
	v_fmac_f32_e32 v118, v72, v118
	v_div_scale_f32 v72, vcc, 1.0, v106, 1.0
	v_mul_f32_e32 v73, v72, v118
	v_fma_f32 v82, -v107, v73, v72
	v_fmac_f32_e32 v73, v82, v118
	v_fma_f32 v72, -v107, v73, v72
	v_div_fmas_f32 v72, v72, v118, v73
	v_div_fixup_f32 v72, v72, v106, 1.0
	v_pk_mul_f32 v[58:59], v[58:59], v[72:73] op_sel_hi:[1,0]
	v_pk_mul_f32 v[48:49], v[48:49], v[72:73] op_sel_hi:[1,0]
	v_lshlrev_b32_e32 v106, 16, v64
	v_and_b32_e32 v107, 0xffff0000, v64
	v_lshlrev_b32_e32 v64, 16, v65
	v_and_b32_e32 v65, 0xffff0000, v65
	v_pk_mul_f32 v[48:49], v[2:3], v[48:49]
	v_pk_mul_f32 v[58:59], v[4:5], v[58:59]
	v_lshl_add_u64 v[82:83], v[34:35], 0, s[16:17]
	v_pk_mul_f32 v[58:59], v[58:59], v[64:65]
	v_pk_mul_f32 v[48:49], v[48:49], v[106:107]
	v_lshl_add_u64 v[82:83], v[82:83], 0, v[0:1]
	v_cvt_pk_bf16_f32 v48, v48, v49
	v_cvt_pk_bf16_f32 v49, v58, v59
	v_pk_mul_f32 v[52:53], v[52:53], v[72:73] op_sel_hi:[1,0]
	v_pk_mul_f32 v[42:43], v[42:43], v[72:73] op_sel_hi:[1,0]
	global_store_dwordx2 v[82:83], v[48:49], off
	v_lshlrev_b32_e32 v48, 16, v60
	v_and_b32_e32 v49, 0xffff0000, v60
	v_lshlrev_b32_e32 v58, 16, v61
	v_and_b32_e32 v59, 0xffff0000, v61
	v_pk_mul_f32 v[42:43], v[6:7], v[42:43]
	v_pk_mul_f32 v[52:53], v[8:9], v[52:53]
	v_pk_mul_f32 v[42:43], v[42:43], v[48:49]
	v_pk_mul_f32 v[52:53], v[52:53], v[58:59]
	v_cvt_pk_bf16_f32 v42, v42, v43
	v_cvt_pk_bf16_f32 v43, v52, v53
	global_store_dwordx2 v[82:83], v[42:43], off offset:512
	v_lshlrev_b32_e32 v42, 16, v54
	v_and_b32_e32 v43, 0xffff0000, v54
	v_lshlrev_b32_e32 v48, 16, v55
	v_and_b32_e32 v49, 0xffff0000, v55
	v_pk_mul_f32 v[52:53], v[120:121], v[72:73] op_sel_hi:[1,0]
	v_pk_mul_f32 v[54:55], v[96:97], v[72:73] op_sel_hi:[1,0]
	v_pk_mul_f32 v[52:53], v[12:13], v[52:53]
	v_pk_mul_f32 v[54:55], v[10:11], v[54:55]
	v_pk_mul_f32 v[48:49], v[52:53], v[48:49]
	v_pk_mul_f32 v[42:43], v[54:55], v[42:43]
	v_pk_mul_f32 v[52:53], v[140:141], v[72:73] op_sel_hi:[1,0]
	v_cvt_pk_bf16_f32 v42, v42, v43
	v_cvt_pk_bf16_f32 v43, v48, v49
	v_pk_mul_f32 v[48:49], v[110:111], v[72:73] op_sel_hi:[1,0]
	global_store_dwordx2 v[82:83], v[42:43], off offset:1024
	v_lshlrev_b32_e32 v42, 16, v46
	v_and_b32_e32 v43, 0xffff0000, v46
	v_lshlrev_b32_e32 v46, 16, v47
	v_and_b32_e32 v47, 0xffff0000, v47
	v_pk_mul_f32 v[52:53], v[14:15], v[52:53]
	v_pk_mul_f32 v[48:49], v[16:17], v[48:49]
	v_pk_mul_f32 v[42:43], v[52:53], v[42:43]
	v_pk_mul_f32 v[46:47], v[48:49], v[46:47]
	v_cvt_pk_bf16_f32 v42, v42, v43
	v_cvt_pk_bf16_f32 v43, v46, v47
	v_pk_mul_f32 v[48:49], v[94:95], v[72:73] op_sel_hi:[1,0]
	v_pk_mul_f32 v[52:53], v[144:145], v[72:73] op_sel_hi:[1,0]
	global_store_dwordx2 v[82:83], v[42:43], off offset:1536
	s_waitcnt vmcnt(47)
; template <bool HG>
; __device__ __forceinline__ void readout_phase2(const Args& a, Frame& F, const float* gain, int nrows) {
;     ...
;     const bool cx = ML + nw < nrows;
;     RO_LOAD(f2, b2, g2, cx ? ML + nw : nw + 7 * 2048);
;     RO_FINISH(f0, b0, g0, nw + 6 * 2048);
;     RO_FINISH(f1, b1, g1, nw + 7 * 2048);
;     if (cx) RO_FINISH(f2, b2, g2, ML + nw);
	v_lshlrev_b32_e32 v42, 16, v102
	v_and_b32_e32 v43, 0xffff0000, v102
	v_lshlrev_b32_e32 v46, 16, v103
	v_and_b32_e32 v47, 0xffff0000, v103
	v_pk_mul_f32 v[52:53], v[18:19], v[52:53]
	v_pk_mul_f32 v[48:49], v[20:21], v[48:49]
	v_pk_mul_f32 v[42:43], v[52:53], v[42:43]
	v_pk_mul_f32 v[46:47], v[48:49], v[46:47]
	v_cvt_pk_bf16_f32 v42, v42, v43
	v_cvt_pk_bf16_f32 v43, v46, v47
	v_pk_mul_f32 v[48:49], v[88:89], v[72:73] op_sel_hi:[1,0]
	v_pk_mul_f32 v[52:53], v[122:123], v[72:73] op_sel_hi:[1,0]
	global_store_dwordx2 v[82:83], v[42:43], off offset:2048
	s_waitcnt vmcnt(47)
	v_lshlrev_b32_e32 v42, 16, v84
	v_and_b32_e32 v43, 0xffff0000, v84
	v_lshlrev_b32_e32 v46, 16, v85
	v_and_b32_e32 v47, 0xffff0000, v85
	v_pk_mul_f32 v[52:53], v[22:23], v[52:53]
	v_pk_mul_f32 v[48:49], v[24:25], v[48:49]
	v_pk_mul_f32 v[42:43], v[52:53], v[42:43]
	v_pk_mul_f32 v[46:47], v[48:49], v[46:47]
	v_cvt_pk_bf16_f32 v42, v42, v43
	v_cvt_pk_bf16_f32 v43, v46, v47
	v_pk_mul_f32 v[48:49], v[80:81], v[72:73] op_sel_hi:[1,0]
	v_pk_mul_f32 v[52:53], v[142:143], v[72:73] op_sel_hi:[1,0]
	global_store_dwordx2 v[82:83], v[42:43], off offset:2560
	s_waitcnt vmcnt(47)
	v_lshlrev_b32_e32 v42, 16, v78
	v_and_b32_e32 v43, 0xffff0000, v78
	v_lshlrev_b32_e32 v46, 16, v79
	v_and_b32_e32 v47, 0xffff0000, v79
	v_pk_mul_f32 v[52:53], v[26:27], v[52:53]
	v_pk_mul_f32 v[48:49], v[28:29], v[48:49]
	v_pk_mul_f32 v[42:43], v[52:53], v[42:43]
	v_pk_mul_f32 v[46:47], v[48:49], v[46:47]
	v_cvt_pk_bf16_f32 v42, v42, v43
	v_cvt_pk_bf16_f32 v43, v46, v47
	v_pk_mul_f32 v[48:49], v[66:67], v[72:73] op_sel_hi:[1,0]
	v_pk_mul_f32 v[52:53], v[150:151], v[72:73] op_sel_hi:[1,0]
	global_store_dwordx2 v[82:83], v[42:43], off offset:3072
	s_waitcnt vmcnt(47)
	v_lshlrev_b32_e32 v42, 16, v70
	v_and_b32_e32 v43, 0xffff0000, v70
	v_lshlrev_b32_e32 v46, 16, v71
	v_and_b32_e32 v47, 0xffff0000, v71
	v_pk_mul_f32 v[52:53], v[30:31], v[52:53]
	v_pk_mul_f32 v[48:49], v[32:33], v[48:49]
	v_pk_mul_f32 v[42:43], v[52:53], v[42:43]
	v_pk_mul_f32 v[46:47], v[48:49], v[46:47]
	v_cvt_pk_bf16_f32 v42, v42, v43
	v_cvt_pk_bf16_f32 v43, v46, v47
	s_and_b64 vcc, exec, s[14:15]
	global_store_dwordx2 v[82:83], v[42:43], off offset:3584
	s_cbranch_vccz .LBB0_582
	s_waitcnt vmcnt(39)
	v_lshlrev_b32_e32 v42, 16, v130
	v_and_b32_e32 v43, 0xffff0000, v130
	s_waitcnt vmcnt(35)
	v_lshlrev_b32_e32 v46, 16, v134
	v_and_b32_e32 v47, 0xffff0000, v134
	v_pk_add_f32 v[46:47], v[42:43], v[46:47]
	v_lshlrev_b32_e32 v42, 16, v131
	v_and_b32_e32 v43, 0xffff0000, v131
	v_lshlrev_b32_e32 v48, 16, v135
	v_and_b32_e32 v49, 0xffff0000, v135
	v_pk_add_f32 v[52:53], v[42:43], v[48:49]
	v_lshlrev_b32_e32 v42, 16, v116
	v_and_b32_e32 v43, 0xffff0000, v116
	s_waitcnt vmcnt(34)
	v_lshlrev_b32_e32 v48, 16, v128
	v_and_b32_e32 v49, 0xffff0000, v128
	v_pk_add_f32 v[42:43], v[42:43], v[48:49]
	v_lshlrev_b32_e32 v48, 16, v117
	v_and_b32_e32 v49, 0xffff0000, v117
	v_lshlrev_b32_e32 v54, 16, v129
	v_and_b32_e32 v55, 0xffff0000, v129
	v_pk_add_f32 v[48:49], v[48:49], v[54:55]
	v_mov_b32_e32 v58, v47
	v_mov_b32_e32 v59, v43
	v_mov_b32_e32 v54, v46
	v_mov_b32_e32 v55, v42
	v_pk_mul_f32 v[58:59], v[58:59], v[58:59]
	v_mov_b32_e32 v60, v53
	v_mov_b32_e32 v61, v49
	v_pk_fma_f32 v[54:55], v[54:55], v[54:55], v[58:59]
	v_mov_b32_e32 v58, v52
	v_mov_b32_e32 v59, v48
	v_pk_mul_f32 v[60:61], v[60:61], v[60:61]
	s_waitcnt vmcnt(33)
	v_lshlrev_b32_e32 v64, 16, v115
	v_pk_fma_f32 v[58:59], v[58:59], v[58:59], v[60:61]
	v_lshlrev_b32_e32 v60, 16, v114
	v_pk_add_f32 v[54:55], v[54:55], v[58:59]
	v_and_b32_e32 v61, 0xffff0000, v114
	v_pk_add_f32 v[58:59], v[54:55], v[54:55] op_sel:[0,1] op_sel_hi:[1,0]
	v_lshlrev_b32_e32 v54, 16, v112
	v_and_b32_e32 v55, 0xffff0000, v112
	v_pk_add_f32 v[54:55], v[54:55], v[60:61]
	v_lshlrev_b32_e32 v60, 16, v113
	v_and_b32_e32 v61, 0xffff0000, v113
	v_and_b32_e32 v65, 0xffff0000, v115
	v_pk_add_f32 v[60:61], v[60:61], v[64:65]
	v_mov_b32_e32 v66, v55
	v_mov_b32_e32 v67, v61
	v_mov_b32_e32 v64, v54
	v_mov_b32_e32 v65, v60
	v_pk_mul_f32 v[66:67], v[66:67], v[66:67]
	s_waitcnt vmcnt(32)
	v_lshlrev_b32_e32 v70, 16, v104
	v_pk_fma_f32 v[64:65], v[64:65], v[64:65], v[66:67]
	v_lshlrev_b32_e32 v66, 16, v92
	v_and_b32_e32 v67, 0xffff0000, v92
	v_and_b32_e32 v71, 0xffff0000, v104
	v_pk_add_f32 v[66:67], v[66:67], v[70:71]
	v_lshlrev_b32_e32 v70, 16, v93
	v_and_b32_e32 v71, 0xffff0000, v93
	v_lshlrev_b32_e32 v72, 16, v105
	v_and_b32_e32 v73, 0xffff0000, v105
	s_waitcnt vmcnt(27)
	v_lshlrev_b32_e32 v80, 16, v86
	v_and_b32_e32 v81, 0xffff0000, v86
	s_waitcnt vmcnt(23)
	v_lshlrev_b32_e32 v82, 16, v124
	v_and_b32_e32 v83, 0xffff0000, v124
	v_pk_add_f32 v[70:71], v[70:71], v[72:73]
	v_pk_add_f32 v[80:81], v[80:81], v[82:83]
	v_lshlrev_b32_e32 v82, 16, v87
	v_and_b32_e32 v83, 0xffff0000, v87
	v_lshlrev_b32_e32 v84, 16, v125
	v_and_b32_e32 v85, 0xffff0000, v125
	v_mul_f32_e32 v72, v67, v67
	v_mul_f32_e32 v78, v71, v71
	v_pk_add_f32 v[82:83], v[82:83], v[84:85]
	v_pk_add_f32 v[64:65], v[64:65], v[64:65] op_sel:[0,1] op_sel_hi:[1,0]
	v_pk_fma_f32 v[72:73], v[66:67], v[66:67], v[72:73] op_sel_hi:[1,1,0]
	v_pk_fma_f32 v[78:79], v[70:71], v[70:71], v[78:79] op_sel_hi:[1,1,0]
	v_pk_mul_f32 v[84:85], v[80:81], v[80:81]
	v_pk_mul_f32 v[86:87], v[82:83], v[82:83]
	v_mov_b32_e32 v59, v84
	v_mov_b32_e32 v65, v85
	v_mov_b32_e32 v73, v86
	v_mov_b32_e32 v79, v87
	v_pk_add_f32 v[58:59], v[58:59], v[64:65]
	v_pk_add_f32 v[64:65], v[72:73], v[78:79]
	s_waitcnt vmcnt(22)
; template <bool HG>
; __device__ __forceinline__ void readout_phase2(const Args& a, Frame& F, const float* gain, int nrows) {
;     ...
;     const bool cx = ML + nw < nrows;
;     RO_LOAD(f2, b2, g2, cx ? ML + nw : nw + 7 * 2048);
;     RO_FINISH(f0, b0, g0, nw + 6 * 2048);
;     RO_FINISH(f1, b1, g1, nw + 7 * 2048);
;     if (cx) RO_FINISH(f2, b2, g2, ML + nw);
	v_lshlrev_b32_e32 v72, 16, v108
	v_pk_add_f32 v[58:59], v[58:59], v[64:65]
	v_lshlrev_b32_e32 v64, 16, v62
	v_and_b32_e32 v65, 0xffff0000, v62
	v_and_b32_e32 v73, 0xffff0000, v108
	v_pk_add_f32 v[64:65], v[64:65], v[72:73]
	v_lshlrev_b32_e32 v62, 16, v63
	v_and_b32_e32 v63, 0xffff0000, v63
	v_lshlrev_b32_e32 v72, 16, v109
	v_and_b32_e32 v73, 0xffff0000, v109
	v_pk_add_f32 v[62:63], v[62:63], v[72:73]
	v_mov_b32_e32 v78, v65
	v_mov_b32_e32 v79, v63
	v_mov_b32_e32 v72, v64
	v_mov_b32_e32 v73, v62
	v_pk_mul_f32 v[78:79], v[78:79], v[78:79]
	s_waitcnt vmcnt(21)
	v_lshlrev_b32_e32 v84, 16, v100
	v_pk_fma_f32 v[72:73], v[72:73], v[72:73], v[78:79]
	v_lshlrev_b32_e32 v78, 16, v56
	v_and_b32_e32 v79, 0xffff0000, v56
	v_and_b32_e32 v85, 0xffff0000, v100
	v_pk_add_f32 v[78:79], v[78:79], v[84:85]
	v_lshlrev_b32_e32 v56, 16, v57
	v_and_b32_e32 v57, 0xffff0000, v57
	v_lshlrev_b32_e32 v84, 16, v101
	v_and_b32_e32 v85, 0xffff0000, v101
	v_lshlrev_b32_e32 v88, 16, v50
	v_and_b32_e32 v89, 0xffff0000, v50
	s_waitcnt vmcnt(20)
	v_lshlrev_b32_e32 v92, 16, v98
	v_and_b32_e32 v93, 0xffff0000, v98
	v_pk_add_f32 v[56:57], v[56:57], v[84:85]
	v_pk_add_f32 v[88:89], v[88:89], v[92:93]
	v_lshlrev_b32_e32 v50, 16, v51
	v_and_b32_e32 v51, 0xffff0000, v51
	v_lshlrev_b32_e32 v92, 16, v99
	v_and_b32_e32 v93, 0xffff0000, v99
	v_mul_f32_e32 v84, v79, v79
	v_mul_f32_e32 v86, v57, v57
	v_pk_add_f32 v[50:51], v[50:51], v[92:93]
	v_pk_add_f32 v[58:59], v[58:59], v[58:59] op_sel:[0,1] op_sel_hi:[1,0]
	v_pk_add_f32 v[72:73], v[72:73], v[72:73] op_sel:[0,1] op_sel_hi:[1,0]
	v_pk_fma_f32 v[84:85], v[78:79], v[78:79], v[84:85] op_sel_hi:[1,1,0]
	v_pk_fma_f32 v[86:87], v[56:57], v[56:57], v[86:87] op_sel_hi:[1,1,0]
	v_pk_mul_f32 v[92:93], v[88:89], v[88:89]
	v_pk_mul_f32 v[94:95], v[50:51], v[50:51]
	v_mov_b32_e32 v59, v92
	v_mov_b32_e32 v73, v93
	v_mov_b32_e32 v85, v94
	v_mov_b32_e32 v87, v95
	v_pk_add_f32 v[58:59], v[58:59], v[72:73]
	v_pk_add_f32 v[72:73], v[84:85], v[86:87]
	s_ashr_i32 s11, s10, 31
	v_pk_add_f32 v[58:59], v[58:59], v[72:73]
	s_nop 0
	v_add_f32_e32 v58, v58, v59
	s_nop 1
	v_add_f32_dpp v58, v58, v58 quad_perm:[1,0,3,2] row_mask:0xf bank_mask:0xf bound_ctrl:1
	s_nop 1
	v_add_f32_dpp v58, v58, v58 quad_perm:[2,3,0,1] row_mask:0xf bank_mask:0xf bound_ctrl:1
	s_nop 1
	v_add_f32_dpp v58, v58, v58 row_half_mirror row_mask:0xf bank_mask:0xf bound_ctrl:1
	s_nop 1
	v_add_f32_dpp v58, v58, v58 row_mirror row_mask:0xf bank_mask:0xf bound_ctrl:1
	s_nop 0
	v_readlane_b32 s8, v58, 16
	v_readlane_b32 s9, v58, 48
	v_readlane_b32 s6, v58, 0
	v_readlane_b32 s7, v58, 32
	v_mov_b32_e32 v58, s8
	v_mov_b32_e32 v59, s9
	v_pk_add_f32 v[58:59], s[6:7], v[58:59]
	s_nop 0
	v_add_f32_e32 v58, v58, v59
	v_fmamk_f32 v58, v58, 0x3a000000, v252
	v_mul_f32_e32 v59, 0x4f800000, v58
	v_cmp_gt_f32_e32 vcc, s55, v58
	s_nop 1
	v_cndmask_b32_e32 v58, v58, v59, vcc
	v_sqrt_f32_e32 v59, v58
	s_nop 0
	v_add_u32_e32 v72, -1, v59
	v_fma_f32 v73, -v72, v59, v58
	v_cmp_ge_f32_e64 s[8:9], 0, v73
	v_add_u32_e32 v73, 1, v59
	s_nop 0
	v_cndmask_b32_e64 v72, v59, v72, s[8:9]
	v_fma_f32 v59, -v73, v59, v58
	v_cmp_lt_f32_e64 s[8:9], 0, v59
	s_nop 1
	v_cndmask_b32_e64 v59, v72, v73, s[8:9]
	v_mul_f32_e32 v72, 0x37800000, v59
	v_cndmask_b32_e32 v59, v59, v72, vcc
	v_cmp_class_f32_e32 vcc, v58, v253
	s_nop 1
	v_cndmask_b32_e32 v58, v59, v58, vcc
	v_div_scale_f32 v59, s[6:7], v58, v58, 1.0
	v_rcp_f32_e32 v72, v59
	s_lshl_b64 s[6:7], s[10:11], 12
	v_lshl_add_u64 v[34:35], v[34:35], 0, s[6:7]
	v_lshl_add_u64 v[34:35], v[34:35], 0, v[0:1]
	v_fma_f32 v73, -v59, v72, 1.0
	v_fmac_f32_e32 v72, v73, v72
	v_div_scale_f32 v73, vcc, 1.0, v58, 1.0
	v_mul_f32_e32 v84, v73, v72
	v_fma_f32 v85, -v59, v84, v73
	v_fmac_f32_e32 v84, v85, v72
	v_fma_f32 v59, -v59, v84, v73
	v_div_fmas_f32 v59, v59, v72, v84
	v_div_fixup_f32 v58, v59, v58, 1.0
	v_pk_mul_f32 v[52:53], v[52:53], v[58:59] op_sel_hi:[1,0]
	v_pk_mul_f32 v[46:47], v[46:47], v[58:59] op_sel_hi:[1,0]
	v_lshlrev_b32_e32 v72, 16, v44
	v_and_b32_e32 v73, 0xffff0000, v44
	v_lshlrev_b32_e32 v44, 16, v45
	v_and_b32_e32 v45, 0xffff0000, v45
	v_pk_mul_f32 v[2:3], v[2:3], v[46:47]
	v_pk_mul_f32 v[4:5], v[4:5], v[52:53]
	v_pk_mul_f32 v[2:3], v[2:3], v[72:73]
	v_pk_mul_f32 v[4:5], v[4:5], v[44:45]
	v_cvt_pk_bf16_f32 v2, v2, v3
	v_cvt_pk_bf16_f32 v3, v4, v5
	global_store_dwordx2 v[34:35], v[2:3], off
	v_lshlrev_b32_e32 v2, 16, v40
	v_and_b32_e32 v3, 0xffff0000, v40
	v_lshlrev_b32_e32 v4, 16, v41
	v_and_b32_e32 v5, 0xffff0000, v41
	v_pk_mul_f32 v[40:41], v[48:49], v[58:59] op_sel_hi:[1,0]
	v_pk_mul_f32 v[42:43], v[42:43], v[58:59] op_sel_hi:[1,0]
	v_pk_mul_f32 v[8:9], v[8:9], v[40:41]
	v_pk_mul_f32 v[6:7], v[6:7], v[42:43]
	v_pk_mul_f32 v[4:5], v[8:9], v[4:5]
	v_pk_mul_f32 v[2:3], v[6:7], v[2:3]
	v_pk_mul_f32 v[6:7], v[60:61], v[58:59] op_sel_hi:[1,0]
	v_cvt_pk_bf16_f32 v2, v2, v3
	v_cvt_pk_bf16_f32 v3, v4, v5
	v_pk_mul_f32 v[8:9], v[54:55], v[58:59] op_sel_hi:[1,0]
	global_store_dwordx2 v[34:35], v[2:3], off offset:512
	v_lshlrev_b32_e32 v2, 16, v38
	v_and_b32_e32 v3, 0xffff0000, v38
	v_lshlrev_b32_e32 v4, 16, v39
	v_and_b32_e32 v5, 0xffff0000, v39
	v_pk_mul_f32 v[8:9], v[10:11], v[8:9]
	v_pk_mul_f32 v[6:7], v[12:13], v[6:7]
	v_pk_mul_f32 v[2:3], v[8:9], v[2:3]
	v_pk_mul_f32 v[4:5], v[6:7], v[4:5]
	v_cvt_pk_bf16_f32 v2, v2, v3
	v_cvt_pk_bf16_f32 v3, v4, v5
	v_pk_mul_f32 v[6:7], v[70:71], v[58:59] op_sel_hi:[1,0]
	v_pk_mul_f32 v[8:9], v[66:67], v[58:59] op_sel_hi:[1,0]
	global_store_dwordx2 v[34:35], v[2:3], off offset:1024
	v_lshlrev_b32_e32 v2, 16, v36
	v_and_b32_e32 v3, 0xffff0000, v36
	v_lshlrev_b32_e32 v4, 16, v37
	v_and_b32_e32 v5, 0xffff0000, v37
	v_pk_mul_f32 v[8:9], v[14:15], v[8:9]
	v_pk_mul_f32 v[6:7], v[16:17], v[6:7]
	v_pk_mul_f32 v[2:3], v[8:9], v[2:3]
	v_pk_mul_f32 v[4:5], v[6:7], v[4:5]
	v_cvt_pk_bf16_f32 v2, v2, v3
	v_cvt_pk_bf16_f32 v3, v4, v5
	v_pk_mul_f32 v[6:7], v[82:83], v[58:59] op_sel_hi:[1,0]
	v_pk_mul_f32 v[8:9], v[80:81], v[58:59] op_sel_hi:[1,0]
	global_store_dwordx2 v[34:35], v[2:3], off offset:1536
	s_waitcnt vmcnt(23)
	v_lshlrev_b32_e32 v2, 16, v90
	v_and_b32_e32 v3, 0xffff0000, v90
	v_lshlrev_b32_e32 v4, 16, v91
	v_and_b32_e32 v5, 0xffff0000, v91
	v_pk_mul_f32 v[8:9], v[18:19], v[8:9]
	v_pk_mul_f32 v[6:7], v[20:21], v[6:7]
	v_pk_mul_f32 v[2:3], v[8:9], v[2:3]
	v_pk_mul_f32 v[4:5], v[6:7], v[4:5]
	v_cvt_pk_bf16_f32 v2, v2, v3
	v_cvt_pk_bf16_f32 v3, v4, v5
	v_pk_mul_f32 v[6:7], v[62:63], v[58:59] op_sel_hi:[1,0]
	v_pk_mul_f32 v[8:9], v[64:65], v[58:59] op_sel_hi:[1,0]
	global_store_dwordx2 v[34:35], v[2:3], off offset:2048
	s_waitcnt vmcnt(23)
	v_lshlrev_b32_e32 v2, 16, v76
	v_and_b32_e32 v3, 0xffff0000, v76
	v_lshlrev_b32_e32 v4, 16, v77
	v_and_b32_e32 v5, 0xffff0000, v77
	v_pk_mul_f32 v[8:9], v[22:23], v[8:9]
	v_pk_mul_f32 v[6:7], v[24:25], v[6:7]
	v_pk_mul_f32 v[2:3], v[8:9], v[2:3]
	v_pk_mul_f32 v[4:5], v[6:7], v[4:5]
	v_cvt_pk_bf16_f32 v2, v2, v3
	v_cvt_pk_bf16_f32 v3, v4, v5
	v_pk_mul_f32 v[6:7], v[56:57], v[58:59] op_sel_hi:[1,0]
	v_pk_mul_f32 v[8:9], v[78:79], v[58:59] op_sel_hi:[1,0]
	global_store_dwordx2 v[34:35], v[2:3], off offset:2560
	s_waitcnt vmcnt(23)
	v_lshlrev_b32_e32 v2, 16, v74
	v_and_b32_e32 v3, 0xffff0000, v74
	v_lshlrev_b32_e32 v4, 16, v75
	v_and_b32_e32 v5, 0xffff0000, v75
	v_pk_mul_f32 v[8:9], v[26:27], v[8:9]
	v_pk_mul_f32 v[6:7], v[28:29], v[6:7]
	v_pk_mul_f32 v[2:3], v[8:9], v[2:3]
	v_pk_mul_f32 v[4:5], v[6:7], v[4:5]
	v_cvt_pk_bf16_f32 v2, v2, v3
	v_cvt_pk_bf16_f32 v3, v4, v5
	v_pk_mul_f32 v[6:7], v[50:51], v[58:59] op_sel_hi:[1,0]
	v_pk_mul_f32 v[8:9], v[88:89], v[58:59] op_sel_hi:[1,0]
	global_store_dwordx2 v[34:35], v[2:3], off offset:3072
	s_waitcnt vmcnt(23)
	v_lshlrev_b32_e32 v2, 16, v68
	v_and_b32_e32 v3, 0xffff0000, v68
	v_lshlrev_b32_e32 v4, 16, v69
	v_and_b32_e32 v5, 0xffff0000, v69
	v_pk_mul_f32 v[8:9], v[30:31], v[8:9]
	v_pk_mul_f32 v[6:7], v[32:33], v[6:7]
	v_pk_mul_f32 v[2:3], v[8:9], v[2:3]
	v_pk_mul_f32 v[4:5], v[6:7], v[4:5]
	v_cvt_pk_bf16_f32 v2, v2, v3
	v_cvt_pk_bf16_f32 v3, v4, v5
	global_store_dwordx2 v[34:35], v[2:3], off offset:3584
